# GEMM K-loops: priority raise moved before the opening barrier and drop after the closing barrier, mid-block priority flip and redundant LDS wait removed, the two pre-barrier waits merged
# speedup vs baseline: 1.0052x; 1.0038x over previous
; #define PG8_STAGE(bufoff, gbase, voff) do { _Pragma("unroll") for (int _i = 0; _i < 2; ++_i) \
;         __builtin_amdgcn_global_load_lds((const unsigned*)((const char*)(gbase) + (voff)[_i]), (LAS unsigned*)(lds + (bufoff) + ldsw + _i * 8192), 16, 0, 0); } while (0)
; #define PG8_LDA(dst, b, h) do { _Pragma("unroll") for (int m = 0; m < 4; ++m) _Pragma("unroll") for (int k = 0; k < 2; ++k) dst[m][k] = *(const LAS bf16x8*)(lds + PG8_SA(b, h) + aoff + m * 2048 + k * 1024); } while (0)
; #define PG8_LDB(dst, b, h) do { _Pragma("unroll") for (int n = 0; n < 2; ++n) _Pragma("unroll") for (int k = 0; k < 2; ++k) dst[n][k] = *(const LAS bf16x8*)(lds + PG8_SB(b, h) + boff + n * 2048 + k * 1024); } while (0)
; #define PG8_MMA(ai, bj, At, Bt) do { __builtin_amdgcn_s_setprio(1); _Pragma("unroll") for (int m = 0; m < 4; ++m) _Pragma("unroll") for (int n = 0; n < 2; ++n) _Pragma("unroll") for (int k = 0; k < 2; ++k) \
;         acc[ai][bj][m][n] = __builtin_amdgcn_mfma_f32_16x16x32_bf16(Bt[n][k], At[m][k], acc[ai][bj][m][n], 0, 0, 0); __builtin_amdgcn_s_setprio(0); } while (0)
; #define PG8_WAIT_V(n) asm volatile("s_waitcnt vmcnt(" #n ")" ::: "memory")
; #define PG8_WAIT_L(n) asm volatile("s_waitcnt lgkmcnt(" #n ")" ::: "memory")
; #define PG8_BAR __builtin_amdgcn_s_barrier()
; #define PG8_SCHED __builtin_amdgcn_sched_barrier(0)
; template <class Epi, class Sched>
; DI void gemm_phase(LAS unsigned char* lds, const Sched& S, const Epi& E) {
;     ...
;     for (int t = 0; t < nt; t += 2) {
;       const bool last = (t == nt - 2);
;       const char* a1 = cA + (size_t)(t + 1) * kstep;
;       const char* a2 = last ? nA : cA + (size_t)(t + 2) * kstep; const char* b2 = last ? nB : cB + (size_t)(t + 2) * kstep;
;       const char* a3 = a2 + kstep; const char* b3 = b2 + kstep;
;       PG8_LDB(B0, 0, 0); PG8_LDB(B1, 0, 1); PG8_SCHED; PG8_LDA(At, 0, 0); PG8_STAGE(PG8_SA(1, 1), a1 + hstep, voffA);
;       PG8_WAIT_V(8); PG8_WAIT_L(0); PG8_BAR; PG8_MMA(0, 0, At, B0); PG8_MMA(0, 1, At, B1); PG8_BAR; PG8_SCHED;
;       PG8_LDA(At, 0, 1); PG8_STAGE(PG8_SB(0, 0), b2, voffB); PG8_STAGE(PG8_SB(0, 1), b2 + hstep, voffB); PG8_STAGE(PG8_SA(0, 0), a2, voffA);
;       PG8_WAIT_V(8); PG8_WAIT_L(0); PG8_BAR; PG8_MMA(1, 0, At, B0); PG8_MMA(1, 1, At, B1); PG8_BAR; PG8_SCHED;
.LBB0_139:
	s_add_u32 s26, s48, 0xfff80080
	s_addc_u32 s27, s49, -1
	s_add_i32 s62, 0, 0x10000
	s_cmp_eq_u32 s61, 28
	s_cselect_b32 s51, s25, s27
	s_cselect_b32 s50, s31, s26
	v_add_u32_e32 v138, s62, v141
	s_cselect_b32 s27, s41, s39
	s_cselect_b32 s26, s40, s37
	s_add_i32 s64, 0, 0x14000
	ds_read_b128 v[144:147], v138
	ds_read_b128 v[148:151], v138 offset:1024
	ds_read_b128 v[152:155], v138 offset:2048
	ds_read_b128 v[156:159], v138 offset:3072
	v_add_u32_e32 v138, s64, v141
	ds_read_b128 v[160:163], v138
	ds_read_b128 v[164:167], v138 offset:1024
	ds_read_b128 v[168:171], v138 offset:2048
	ds_read_b128 v[172:175], v138 offset:3072
	v_lshl_add_u64 v[138:139], s[48:49], 0, v[134:135]
	s_add_i32 m0, s45, 0xc000
	ds_read_b128 v[176:179], v143
	ds_read_b128 v[180:183], v143 offset:1024
	ds_read_b128 v[184:187], v143 offset:2048
	ds_read_b128 v[188:191], v143 offset:3072
	ds_read_b128 v[192:195], v143 offset:4096
	ds_read_b128 v[196:199], v143 offset:5120
	ds_read_b128 v[200:203], v143 offset:6144
	ds_read_b128 v[204:207], v143 offset:7168
	global_load_lds_dwordx4 v[138:139], off
	v_lshl_add_u64 v[138:139], s[48:49], 0, v[136:137]
	s_add_i32 m0, s45, 0xe000
	s_nop 0
	global_load_lds_dwordx4 v[138:139], off
	s_waitcnt vmcnt(8) lgkmcnt(0)
	s_setprio 1
	s_barrier
	v_mfma_f32_16x16x32_bf16 v[124:127], v[144:147], v[176:179], v[124:127]
	v_mfma_f32_16x16x32_bf16 v[120:123], v[152:155], v[176:179], v[120:123]
	v_mfma_f32_16x16x32_bf16 v[116:119], v[144:147], v[184:187], v[116:119]
	v_mfma_f32_16x16x32_bf16 v[108:111], v[152:155], v[184:187], v[108:111]
	v_mfma_f32_16x16x32_bf16 v[100:103], v[144:147], v[192:195], v[100:103]
	v_mfma_f32_16x16x32_bf16 v[92:95], v[152:155], v[192:195], v[92:95]
	v_mfma_f32_16x16x32_bf16 v[84:87], v[144:147], v[200:203], v[84:87]
	v_mfma_f32_16x16x32_bf16 v[76:79], v[152:155], v[200:203], v[76:79]
	v_mfma_f32_16x16x32_bf16 v[124:127], v[148:151], v[180:183], v[124:127]
	v_mfma_f32_16x16x32_bf16 v[120:123], v[156:159], v[180:183], v[120:123]
	v_mfma_f32_16x16x32_bf16 v[116:119], v[148:151], v[188:191], v[116:119]
	v_mfma_f32_16x16x32_bf16 v[108:111], v[156:159], v[188:191], v[108:111]
	v_mfma_f32_16x16x32_bf16 v[100:103], v[148:151], v[196:199], v[100:103]
	v_mfma_f32_16x16x32_bf16 v[92:95], v[156:159], v[196:199], v[92:95]
	v_mfma_f32_16x16x32_bf16 v[84:87], v[148:151], v[204:207], v[84:87]
	v_mfma_f32_16x16x32_bf16 v[76:79], v[156:159], v[204:207], v[76:79]
	v_mfma_f32_16x16x32_bf16 v[112:115], v[160:163], v[176:179], v[112:115]
	v_mfma_f32_16x16x32_bf16 v[104:107], v[168:171], v[176:179], v[104:107]
	v_mfma_f32_16x16x32_bf16 v[96:99], v[160:163], v[184:187], v[96:99]
	v_mfma_f32_16x16x32_bf16 v[88:91], v[168:171], v[184:187], v[88:91]
	v_mfma_f32_16x16x32_bf16 v[80:83], v[160:163], v[192:195], v[80:83]
	v_mfma_f32_16x16x32_bf16 v[72:75], v[168:171], v[192:195], v[72:75]
	v_mfma_f32_16x16x32_bf16 v[68:71], v[160:163], v[200:203], v[68:71]
	v_mfma_f32_16x16x32_bf16 v[64:67], v[168:171], v[200:203], v[64:67]
	v_mfma_f32_16x16x32_bf16 v[112:115], v[164:167], v[180:183], v[112:115]
	v_mfma_f32_16x16x32_bf16 v[104:107], v[172:175], v[180:183], v[104:107]
	v_mfma_f32_16x16x32_bf16 v[96:99], v[164:167], v[188:191], v[96:99]
	v_mfma_f32_16x16x32_bf16 v[88:91], v[172:175], v[188:191], v[88:91]
	v_mfma_f32_16x16x32_bf16 v[80:83], v[164:167], v[196:199], v[80:83]
	v_mfma_f32_16x16x32_bf16 v[72:75], v[172:175], v[196:199], v[72:75]
	v_mfma_f32_16x16x32_bf16 v[68:71], v[164:167], v[204:207], v[68:71]
	v_mfma_f32_16x16x32_bf16 v[64:67], v[172:175], v[204:207], v[64:67]
	s_barrier
	s_setprio 0
	s_add_i32 s62, s62, s52
	v_lshl_add_u64 v[138:139], s[26:27], 0, v[208:209]
	s_mov_b32 m0, s62
	ds_read_b128 v[176:179], v143 offset:16384
	ds_read_b128 v[180:183], v143 offset:17408
	ds_read_b128 v[184:187], v143 offset:18432
	ds_read_b128 v[188:191], v143 offset:19456
	ds_read_b128 v[192:195], v143 offset:20480
	ds_read_b128 v[196:199], v143 offset:21504
	ds_read_b128 v[200:203], v143 offset:22528
	ds_read_b128 v[204:207], v143 offset:23552
	global_load_lds_dwordx4 v[138:139], off
	s_add_i32 m0, s62, 0x2000
	s_add_u32 s62, s26, 0x80000
	v_lshl_add_u64 v[210:211], s[26:27], 0, v[132:133]
	s_addc_u32 s63, s27, 0
	s_add_i32 s64, s64, s52
	global_load_lds_dwordx4 v[210:211], off
	v_lshl_add_u64 v[212:213], s[62:63], 0, v[208:209]
	s_mov_b32 m0, s64
	v_lshl_add_u64 v[214:215], s[50:51], 0, v[130:131]
	global_load_lds_dwordx4 v[212:213], off
	v_lshl_add_u64 v[212:213], s[62:63], 0, v[132:133]
	s_add_i32 m0, s64, 0x2000
	s_nop 0
	global_load_lds_dwordx4 v[212:213], off
	v_lshl_add_u64 v[212:213], s[50:51], 0, v[128:129]
	s_mov_b32 m0, s45
	s_nop 0
	global_load_lds_dwordx4 v[212:213], off
	s_mov_b32 m0, s47
	s_nop 0
	global_load_lds_dwordx4 v[214:215], off
	s_waitcnt vmcnt(8) lgkmcnt(0)
	s_setprio 1
	s_barrier
; #define PG8_STAGE(bufoff, gbase, voff) do { _Pragma("unroll") for (int _i = 0; _i < 2; ++_i) \
;         __builtin_amdgcn_global_load_lds((const unsigned*)((const char*)(gbase) + (voff)[_i]), (LAS unsigned*)(lds + (bufoff) + ldsw + _i * 8192), 16, 0, 0); } while (0)
; #define PG8_LDA(dst, b, h) do { _Pragma("unroll") for (int m = 0; m < 4; ++m) _Pragma("unroll") for (int k = 0; k < 2; ++k) dst[m][k] = *(const LAS bf16x8*)(lds + PG8_SA(b, h) + aoff + m * 2048 + k * 1024); } while (0)
; #define PG8_LDB(dst, b, h) do { _Pragma("unroll") for (int n = 0; n < 2; ++n) _Pragma("unroll") for (int k = 0; k < 2; ++k) dst[n][k] = *(const LAS bf16x8*)(lds + PG8_SB(b, h) + boff + n * 2048 + k * 1024); } while (0)
; #define PG8_MMA(ai, bj, At, Bt) do { __builtin_amdgcn_s_setprio(1); _Pragma("unroll") for (int m = 0; m < 4; ++m) _Pragma("unroll") for (int n = 0; n < 2; ++n) _Pragma("unroll") for (int k = 0; k < 2; ++k) \
;         acc[ai][bj][m][n] = __builtin_amdgcn_mfma_f32_16x16x32_bf16(Bt[n][k], At[m][k], acc[ai][bj][m][n], 0, 0, 0); __builtin_amdgcn_s_setprio(0); } while (0)
; #define PG8_WAIT_V(n) asm volatile("s_waitcnt vmcnt(" #n ")" ::: "memory")
; #define PG8_WAIT_L(n) asm volatile("s_waitcnt lgkmcnt(" #n ")" ::: "memory")
; #define PG8_BAR __builtin_amdgcn_s_barrier()
; #define PG8_SCHED __builtin_amdgcn_sched_barrier(0)
; template <class Epi, class Sched>
; DI void gemm_phase(LAS unsigned char* lds, const Sched& S, const Epi& E) {
;     ...
;       PG8_WAIT_V(8); PG8_WAIT_L(0); PG8_BAR; PG8_MMA(0, 0, At, B0); PG8_MMA(0, 1, At, B1); PG8_BAR; PG8_SCHED;
;       PG8_LDA(At, 0, 1); PG8_STAGE(PG8_SB(0, 0), b2, voffB); PG8_STAGE(PG8_SB(0, 1), b2 + hstep, voffB); PG8_STAGE(PG8_SA(0, 0), a2, voffA);
;       PG8_WAIT_V(8); PG8_WAIT_L(0); PG8_BAR; PG8_MMA(1, 0, At, B0); PG8_MMA(1, 1, At, B1); PG8_BAR; PG8_SCHED;
;       PG8_LDB(B0, 1, 0); PG8_LDB(B1, 1, 1); PG8_SCHED; PG8_LDA(At, 1, 0); PG8_STAGE(PG8_SA(0, 1), a2 + hstep, voffA);
;       PG8_WAIT_V(8); PG8_WAIT_L(0); PG8_BAR; PG8_MMA(0, 0, At, B0); PG8_MMA(0, 1, At, B1); PG8_BAR; PG8_SCHED;
	v_mfma_f32_16x16x32_bf16 v[60:63], v[144:147], v[176:179], v[60:63]
	v_mfma_f32_16x16x32_bf16 v[56:59], v[152:155], v[176:179], v[56:59]
	v_mfma_f32_16x16x32_bf16 v[52:55], v[144:147], v[184:187], v[52:55]
	v_mfma_f32_16x16x32_bf16 v[44:47], v[152:155], v[184:187], v[44:47]
	v_mfma_f32_16x16x32_bf16 v[36:39], v[144:147], v[192:195], v[36:39]
	v_mfma_f32_16x16x32_bf16 v[28:31], v[152:155], v[192:195], v[28:31]
	v_mfma_f32_16x16x32_bf16 v[20:23], v[144:147], v[200:203], v[20:23]
	v_mfma_f32_16x16x32_bf16 v[12:15], v[152:155], v[200:203], v[12:15]
	v_mfma_f32_16x16x32_bf16 v[60:63], v[148:151], v[180:183], v[60:63]
	v_mfma_f32_16x16x32_bf16 v[56:59], v[156:159], v[180:183], v[56:59]
	v_mfma_f32_16x16x32_bf16 v[52:55], v[148:151], v[188:191], v[52:55]
	v_mfma_f32_16x16x32_bf16 v[44:47], v[156:159], v[188:191], v[44:47]
	v_mfma_f32_16x16x32_bf16 v[36:39], v[148:151], v[196:199], v[36:39]
	v_mfma_f32_16x16x32_bf16 v[28:31], v[156:159], v[196:199], v[28:31]
	v_mfma_f32_16x16x32_bf16 v[20:23], v[148:151], v[204:207], v[20:23]
	v_mfma_f32_16x16x32_bf16 v[12:15], v[156:159], v[204:207], v[12:15]
	v_mfma_f32_16x16x32_bf16 v[48:51], v[160:163], v[176:179], v[48:51]
	v_mfma_f32_16x16x32_bf16 v[40:43], v[168:171], v[176:179], v[40:43]
	v_mfma_f32_16x16x32_bf16 v[32:35], v[160:163], v[184:187], v[32:35]
	v_mfma_f32_16x16x32_bf16 v[24:27], v[168:171], v[184:187], v[24:27]
	v_mfma_f32_16x16x32_bf16 v[16:19], v[160:163], v[192:195], v[16:19]
	v_mfma_f32_16x16x32_bf16 v[8:11], v[168:171], v[192:195], v[8:11]
	v_mfma_f32_16x16x32_bf16 v[4:7], v[160:163], v[200:203], v[4:7]
	v_mfma_f32_16x16x32_bf16 v[0:3], v[168:171], v[200:203], v[0:3]
	v_mfma_f32_16x16x32_bf16 v[48:51], v[164:167], v[180:183], v[48:51]
	v_mfma_f32_16x16x32_bf16 v[40:43], v[172:175], v[180:183], v[40:43]
	v_mfma_f32_16x16x32_bf16 v[32:35], v[164:167], v[188:191], v[32:35]
	v_mfma_f32_16x16x32_bf16 v[24:27], v[172:175], v[188:191], v[24:27]
	v_mfma_f32_16x16x32_bf16 v[16:19], v[164:167], v[196:199], v[16:19]
	v_mfma_f32_16x16x32_bf16 v[8:11], v[172:175], v[196:199], v[8:11]
	v_mfma_f32_16x16x32_bf16 v[4:7], v[164:167], v[204:207], v[4:7]
	v_mfma_f32_16x16x32_bf16 v[0:3], v[172:175], v[204:207], v[0:3]
	s_barrier
	s_setprio 0
	s_add_i32 s62, 0, 0x18000
	s_add_i32 s63, 0, 0x1c000
	v_add_u32_e32 v156, s62, v141
	v_add_u32_e32 v172, s63, v141
	ds_read_b128 v[144:147], v156
	ds_read_b128 v[148:151], v156 offset:1024
	ds_read_b128 v[152:155], v156 offset:2048
	ds_read_b128 v[156:159], v156 offset:3072
	ds_read_b128 v[160:163], v172
	ds_read_b128 v[164:167], v172 offset:1024
	ds_read_b128 v[168:171], v172 offset:2048
	ds_read_b128 v[172:175], v172 offset:3072
	s_add_u32 s50, s50, 0x80000
	s_addc_u32 s51, s51, 0
	s_mov_b32 m0, s55
	v_lshl_add_u64 v[216:217], s[50:51], 0, v[128:129]
	ds_read_b128 v[176:179], v143 offset:32768
	ds_read_b128 v[180:183], v143 offset:33792
	ds_read_b128 v[184:187], v143 offset:34816
	ds_read_b128 v[188:191], v143 offset:35840
	ds_read_b128 v[192:195], v143 offset:36864
	ds_read_b128 v[196:199], v143 offset:37888
	ds_read_b128 v[200:203], v143 offset:38912
	ds_read_b128 v[204:207], v143 offset:39936
	global_load_lds_dwordx4 v[216:217], off
	v_lshl_add_u64 v[216:217], s[50:51], 0, v[130:131]
	s_mov_b32 m0, s56
	s_nop 0
	global_load_lds_dwordx4 v[216:217], off
	s_waitcnt vmcnt(8) lgkmcnt(0)
	s_setprio 1
	s_barrier
	v_mfma_f32_16x16x32_bf16 v[124:127], v[144:147], v[176:179], v[124:127]
	v_mfma_f32_16x16x32_bf16 v[120:123], v[152:155], v[176:179], v[120:123]
	v_mfma_f32_16x16x32_bf16 v[116:119], v[144:147], v[184:187], v[116:119]
	v_mfma_f32_16x16x32_bf16 v[108:111], v[152:155], v[184:187], v[108:111]
	v_mfma_f32_16x16x32_bf16 v[100:103], v[144:147], v[192:195], v[100:103]
	v_mfma_f32_16x16x32_bf16 v[92:95], v[152:155], v[192:195], v[92:95]
	v_mfma_f32_16x16x32_bf16 v[84:87], v[144:147], v[200:203], v[84:87]
	v_mfma_f32_16x16x32_bf16 v[76:79], v[152:155], v[200:203], v[76:79]
	v_mfma_f32_16x16x32_bf16 v[124:127], v[148:151], v[180:183], v[124:127]
	v_mfma_f32_16x16x32_bf16 v[120:123], v[156:159], v[180:183], v[120:123]
	v_mfma_f32_16x16x32_bf16 v[116:119], v[148:151], v[188:191], v[116:119]
	v_mfma_f32_16x16x32_bf16 v[108:111], v[156:159], v[188:191], v[108:111]
	v_mfma_f32_16x16x32_bf16 v[100:103], v[148:151], v[196:199], v[100:103]
	v_mfma_f32_16x16x32_bf16 v[92:95], v[156:159], v[196:199], v[92:95]
	v_mfma_f32_16x16x32_bf16 v[84:87], v[148:151], v[204:207], v[84:87]
	v_mfma_f32_16x16x32_bf16 v[76:79], v[156:159], v[204:207], v[76:79]
	v_mfma_f32_16x16x32_bf16 v[112:115], v[160:163], v[176:179], v[112:115]
	v_mfma_f32_16x16x32_bf16 v[104:107], v[168:171], v[176:179], v[104:107]
	v_mfma_f32_16x16x32_bf16 v[96:99], v[160:163], v[184:187], v[96:99]
	v_mfma_f32_16x16x32_bf16 v[88:91], v[168:171], v[184:187], v[88:91]
	v_mfma_f32_16x16x32_bf16 v[80:83], v[160:163], v[192:195], v[80:83]
	v_mfma_f32_16x16x32_bf16 v[72:75], v[168:171], v[192:195], v[72:75]
	v_mfma_f32_16x16x32_bf16 v[68:71], v[160:163], v[200:203], v[68:71]
	v_mfma_f32_16x16x32_bf16 v[64:67], v[168:171], v[200:203], v[64:67]
	v_mfma_f32_16x16x32_bf16 v[112:115], v[164:167], v[180:183], v[112:115]
	v_mfma_f32_16x16x32_bf16 v[104:107], v[172:175], v[180:183], v[104:107]
	v_mfma_f32_16x16x32_bf16 v[96:99], v[164:167], v[188:191], v[96:99]
	v_mfma_f32_16x16x32_bf16 v[88:91], v[172:175], v[188:191], v[88:91]
	v_mfma_f32_16x16x32_bf16 v[80:83], v[164:167], v[196:199], v[80:83]
	v_mfma_f32_16x16x32_bf16 v[72:75], v[172:175], v[196:199], v[72:75]
	v_mfma_f32_16x16x32_bf16 v[68:71], v[164:167], v[204:207], v[68:71]
	v_mfma_f32_16x16x32_bf16 v[64:67], v[172:175], v[204:207], v[64:67]
	s_barrier
; #define PG8_STAGE(bufoff, gbase, voff) do { _Pragma("unroll") for (int _i = 0; _i < 2; ++_i) \
;         __builtin_amdgcn_global_load_lds((const unsigned*)((const char*)(gbase) + (voff)[_i]), (LAS unsigned*)(lds + (bufoff) + ldsw + _i * 8192), 16, 0, 0); } while (0)
; #define PG8_LDA(dst, b, h) do { _Pragma("unroll") for (int m = 0; m < 4; ++m) _Pragma("unroll") for (int k = 0; k < 2; ++k) dst[m][k] = *(const LAS bf16x8*)(lds + PG8_SA(b, h) + aoff + m * 2048 + k * 1024); } while (0)
; #define PG8_LDB(dst, b, h) do { _Pragma("unroll") for (int n = 0; n < 2; ++n) _Pragma("unroll") for (int k = 0; k < 2; ++k) dst[n][k] = *(const LAS bf16x8*)(lds + PG8_SB(b, h) + boff + n * 2048 + k * 1024); } while (0)
; #define PG8_MMA(ai, bj, At, Bt) do { __builtin_amdgcn_s_setprio(1); _Pragma("unroll") for (int m = 0; m < 4; ++m) _Pragma("unroll") for (int n = 0; n < 2; ++n) _Pragma("unroll") for (int k = 0; k < 2; ++k) \
;         acc[ai][bj][m][n] = __builtin_amdgcn_mfma_f32_16x16x32_bf16(Bt[n][k], At[m][k], acc[ai][bj][m][n], 0, 0, 0); __builtin_amdgcn_s_setprio(0); } while (0)
; #define PG8_WAIT_V(n) asm volatile("s_waitcnt vmcnt(" #n ")" ::: "memory")
; #define PG8_WAIT_L(n) asm volatile("s_waitcnt lgkmcnt(" #n ")" ::: "memory")
; #define PG8_BAR __builtin_amdgcn_s_barrier()
; #define PG8_SCHED __builtin_amdgcn_sched_barrier(0)
; template <class Epi, class Sched>
; DI void gemm_phase(LAS unsigned char* lds, const Sched& S, const Epi& E) {
;     ...
;       PG8_LDB(B0, 1, 0); PG8_LDB(B1, 1, 1); PG8_SCHED; PG8_LDA(At, 1, 0); PG8_STAGE(PG8_SA(0, 1), a2 + hstep, voffA);
;       PG8_WAIT_V(8); PG8_WAIT_L(0); PG8_BAR; PG8_MMA(0, 0, At, B0); PG8_MMA(0, 1, At, B1); PG8_BAR; PG8_SCHED;
;       PG8_LDA(At, 1, 1); PG8_STAGE(PG8_SB(1, 0), b3, voffB); PG8_STAGE(PG8_SB(1, 1), b3 + hstep, voffB); PG8_STAGE(PG8_SA(1, 0), a3, voffA);
;       PG8_WAIT_V(8); PG8_WAIT_L(0); PG8_BAR; PG8_MMA(1, 0, At, B0); PG8_MMA(1, 1, At, B1); PG8_BAR; PG8_SCHED;
;     }
;     if (wr == 0) PG8_BAR;
;     if constexpr (Epi::CARRY) E.carry(acc, cur, wr, wc, fr, fq);
;     else if constexpr (!Epi::AFTER_DRAIN) E(acc, cur, wr, wc, fr, fq);
;     if (!has_next) break;
	s_setprio 0
	s_add_i32 s50, s62, s52
	v_lshl_add_u64 v[138:139], v[138:139], 0, s[6:7]
	s_mov_b32 m0, s50
	ds_read_b128 v[176:179], v143 offset:49152
	ds_read_b128 v[180:183], v143 offset:50176
	ds_read_b128 v[184:187], v143 offset:51200
	ds_read_b128 v[188:191], v143 offset:52224
	ds_read_b128 v[192:195], v143 offset:53248
	ds_read_b128 v[196:199], v143 offset:54272
	ds_read_b128 v[200:203], v143 offset:55296
	ds_read_b128 v[204:207], v143 offset:56320
	global_load_lds_dwordx4 v[138:139], off
	s_add_i32 m0, s50, 0x2000
	s_add_u32 s26, s26, 0x80080
	v_lshl_add_u64 v[138:139], v[210:211], 0, s[6:7]
	s_addc_u32 s27, s27, 0
	s_add_i32 s50, s63, s52
	global_load_lds_dwordx4 v[138:139], off
	v_lshl_add_u64 v[138:139], s[26:27], 0, v[208:209]
	s_mov_b32 m0, s50
	s_nop 0
	global_load_lds_dwordx4 v[138:139], off
	v_lshl_add_u64 v[138:139], s[26:27], 0, v[132:133]
	s_add_i32 m0, s50, 0x2000
	s_nop 0
	global_load_lds_dwordx4 v[138:139], off
	v_lshl_add_u64 v[138:139], v[212:213], 0, s[6:7]
	s_mov_b32 m0, s57
	s_nop 0
	global_load_lds_dwordx4 v[138:139], off
	v_lshl_add_u64 v[138:139], v[214:215], 0, s[6:7]
	s_mov_b32 m0, s58
	s_nop 0
	global_load_lds_dwordx4 v[138:139], off
	s_waitcnt vmcnt(8) lgkmcnt(0)
	s_setprio 1
	s_barrier
	v_mfma_f32_16x16x32_bf16 v[60:63], v[144:147], v[176:179], v[60:63]
	v_mfma_f32_16x16x32_bf16 v[56:59], v[152:155], v[176:179], v[56:59]
	v_mfma_f32_16x16x32_bf16 v[52:55], v[144:147], v[184:187], v[52:55]
	v_mfma_f32_16x16x32_bf16 v[44:47], v[152:155], v[184:187], v[44:47]
	v_mfma_f32_16x16x32_bf16 v[36:39], v[144:147], v[192:195], v[36:39]
	v_mfma_f32_16x16x32_bf16 v[28:31], v[152:155], v[192:195], v[28:31]
	v_mfma_f32_16x16x32_bf16 v[20:23], v[144:147], v[200:203], v[20:23]
	v_mfma_f32_16x16x32_bf16 v[12:15], v[152:155], v[200:203], v[12:15]
	v_mfma_f32_16x16x32_bf16 v[60:63], v[148:151], v[180:183], v[60:63]
	v_mfma_f32_16x16x32_bf16 v[56:59], v[156:159], v[180:183], v[56:59]
	v_mfma_f32_16x16x32_bf16 v[52:55], v[148:151], v[188:191], v[52:55]
	v_mfma_f32_16x16x32_bf16 v[44:47], v[156:159], v[188:191], v[44:47]
	v_mfma_f32_16x16x32_bf16 v[36:39], v[148:151], v[196:199], v[36:39]
	v_mfma_f32_16x16x32_bf16 v[28:31], v[156:159], v[196:199], v[28:31]
	v_mfma_f32_16x16x32_bf16 v[20:23], v[148:151], v[204:207], v[20:23]
	v_mfma_f32_16x16x32_bf16 v[12:15], v[156:159], v[204:207], v[12:15]
	v_mfma_f32_16x16x32_bf16 v[48:51], v[160:163], v[176:179], v[48:51]
	v_mfma_f32_16x16x32_bf16 v[40:43], v[168:171], v[176:179], v[40:43]
	v_mfma_f32_16x16x32_bf16 v[32:35], v[160:163], v[184:187], v[32:35]
	v_mfma_f32_16x16x32_bf16 v[24:27], v[168:171], v[184:187], v[24:27]
	v_mfma_f32_16x16x32_bf16 v[16:19], v[160:163], v[192:195], v[16:19]
	v_mfma_f32_16x16x32_bf16 v[8:11], v[168:171], v[192:195], v[8:11]
	v_mfma_f32_16x16x32_bf16 v[4:7], v[160:163], v[200:203], v[4:7]
	v_mfma_f32_16x16x32_bf16 v[0:3], v[168:171], v[200:203], v[0:3]
	v_mfma_f32_16x16x32_bf16 v[48:51], v[164:167], v[180:183], v[48:51]
	v_mfma_f32_16x16x32_bf16 v[40:43], v[172:175], v[180:183], v[40:43]
	v_mfma_f32_16x16x32_bf16 v[32:35], v[164:167], v[188:191], v[32:35]
	v_mfma_f32_16x16x32_bf16 v[24:27], v[172:175], v[188:191], v[24:27]
	v_mfma_f32_16x16x32_bf16 v[16:19], v[164:167], v[196:199], v[16:19]
	v_mfma_f32_16x16x32_bf16 v[8:11], v[172:175], v[196:199], v[8:11]
	v_mfma_f32_16x16x32_bf16 v[4:7], v[164:167], v[204:207], v[4:7]
	v_mfma_f32_16x16x32_bf16 v[0:3], v[172:175], v[204:207], v[0:3]
	s_barrier
	s_setprio 0
	s_add_i32 s61, s61, 2
	s_add_u32 s48, s48, 0x100
	s_addc_u32 s49, s49, 0
	s_add_u32 s37, s37, 0x100
	s_addc_u32 s39, s39, 0
	s_cmp_gt_u32 s61, 29
	s_cbranch_scc0 .LBB0_139
	s_and_b64 vcc, exec, s[22:23]
	s_cbranch_vccz .LBB0_142
	s_barrier

; #define PG8_STAGE(bufoff, gbase, voff) do { _Pragma("unroll") for (int _i = 0; _i < 2; ++_i) \
;         __builtin_amdgcn_global_load_lds((const unsigned*)((const char*)(gbase) + (voff)[_i]), (LAS unsigned*)(lds + (bufoff) + ldsw + _i * 8192), 16, 0, 0); } while (0)
; #define PG8_LDA(dst, b, h) do { _Pragma("unroll") for (int m = 0; m < 4; ++m) _Pragma("unroll") for (int k = 0; k < 2; ++k) dst[m][k] = *(const LAS bf16x8*)(lds + PG8_SA(b, h) + aoff + m * 2048 + k * 1024); } while (0)
; #define PG8_LDB(dst, b, h) do { _Pragma("unroll") for (int n = 0; n < 2; ++n) _Pragma("unroll") for (int k = 0; k < 2; ++k) dst[n][k] = *(const LAS bf16x8*)(lds + PG8_SB(b, h) + boff + n * 2048 + k * 1024); } while (0)
; #define PG8_MMA(ai, bj, At, Bt) do { __builtin_amdgcn_s_setprio(1); _Pragma("unroll") for (int m = 0; m < 4; ++m) _Pragma("unroll") for (int n = 0; n < 2; ++n) _Pragma("unroll") for (int k = 0; k < 2; ++k) \
;         acc[ai][bj][m][n] = __builtin_amdgcn_mfma_f32_16x16x32_bf16(Bt[n][k], At[m][k], acc[ai][bj][m][n], 0, 0, 0); __builtin_amdgcn_s_setprio(0); } while (0)
; #define PG8_WAIT_V(n) asm volatile("s_waitcnt vmcnt(" #n ")" ::: "memory")
; #define PG8_WAIT_L(n) asm volatile("s_waitcnt lgkmcnt(" #n ")" ::: "memory")
; #define PG8_BAR __builtin_amdgcn_s_barrier()
; #define PG8_SCHED __builtin_amdgcn_sched_barrier(0)
; template <class Epi, class Sched>
; DI void gemm_phase(LAS unsigned char* lds, const Sched& S, const Epi& E) {
;     ...
;     for (int t = 0; t < nt; t += 2) {
;       const bool last = (t == nt - 2);
;       const char* a1 = cA + (size_t)(t + 1) * kstep;
;       const char* a2 = last ? nA : cA + (size_t)(t + 2) * kstep; const char* b2 = last ? nB : cB + (size_t)(t + 2) * kstep;
;       const char* a3 = a2 + kstep; const char* b3 = b2 + kstep;
;       PG8_LDB(B0, 0, 0); PG8_LDB(B1, 0, 1); PG8_SCHED; PG8_LDA(At, 0, 0); PG8_STAGE(PG8_SA(1, 1), a1 + hstep, voffA);
;       PG8_WAIT_V(8); PG8_WAIT_L(0); PG8_BAR; PG8_MMA(0, 0, At, B0); PG8_MMA(0, 1, At, B1); PG8_BAR; PG8_SCHED;
;       PG8_LDA(At, 0, 1); PG8_STAGE(PG8_SB(0, 0), b2, voffB); PG8_STAGE(PG8_SB(0, 1), b2 + hstep, voffB); PG8_STAGE(PG8_SA(0, 0), a2, voffA);
;       PG8_WAIT_V(8); PG8_WAIT_L(0); PG8_BAR; PG8_MMA(1, 0, At, B0); PG8_MMA(1, 1, At, B1); PG8_BAR; PG8_SCHED;
.LBB0_256:
	s_add_u32 s26, s42, s22
	s_addc_u32 s27, s43, s23
	s_add_u32 s26, s26, 0x100
	s_addc_u32 s27, s27, 0
	s_add_u32 s67, s64, s22
	s_addc_u32 s72, s65, s23
	s_add_i32 s73, 0, 0x10000
	s_cmpk_eq_i32 s22, 0x2b00
	s_cselect_b32 s45, s1, s27
	s_cselect_b32 s44, s0, s26
	s_cselect_b32 s27, s41, s72
	s_cselect_b32 s26, s40, s67
	s_add_i32 s67, 0, 0x14000
	v_add_u32_e32 v156, s73, v134
	v_add_u32_e32 v172, s67, v134
	ds_read_b128 v[144:147], v156
	ds_read_b128 v[148:151], v156 offset:1024
	ds_read_b128 v[152:155], v156 offset:2048
	ds_read_b128 v[156:159], v156 offset:3072
	ds_read_b128 v[160:163], v172
	ds_read_b128 v[164:167], v172 offset:1024
	ds_read_b128 v[168:171], v172 offset:2048
	ds_read_b128 v[172:175], v172 offset:3072
	v_lshl_add_u64 v[210:211], v[130:131], 0, s[22:23]
	s_add_i32 m0, s51, 0xc000
	ds_read_b128 v[176:179], v135
	ds_read_b128 v[180:183], v135 offset:1024
	ds_read_b128 v[184:187], v135 offset:2048
	ds_read_b128 v[188:191], v135 offset:3072
	ds_read_b128 v[192:195], v135 offset:4096
	ds_read_b128 v[196:199], v135 offset:5120
	ds_read_b128 v[200:203], v135 offset:6144
	ds_read_b128 v[204:207], v135 offset:7168
	global_load_lds_dwordx4 v[210:211], off
	v_lshl_add_u64 v[210:211], v[132:133], 0, s[22:23]
	s_add_i32 m0, s51, 0xe000
	s_nop 0
	global_load_lds_dwordx4 v[210:211], off
	s_waitcnt vmcnt(8) lgkmcnt(0)
	s_setprio 1
	s_barrier
	v_mfma_f32_16x16x32_bf16 v[140:143], v[144:147], v[176:179], v[140:143]
	v_mfma_f32_16x16x32_bf16 v[136:139], v[152:155], v[176:179], v[136:139]
	v_mfma_f32_16x16x32_bf16 v[108:111], v[144:147], v[184:187], v[108:111]
	v_mfma_f32_16x16x32_bf16 v[104:107], v[152:155], v[184:187], v[104:107]
	v_mfma_f32_16x16x32_bf16 v[92:95], v[144:147], v[192:195], v[92:95]
	v_mfma_f32_16x16x32_bf16 v[88:91], v[152:155], v[192:195], v[88:91]
	v_mfma_f32_16x16x32_bf16 v[76:79], v[144:147], v[200:203], v[76:79]
	v_mfma_f32_16x16x32_bf16 v[72:75], v[152:155], v[200:203], v[72:75]
	v_mfma_f32_16x16x32_bf16 v[140:143], v[148:151], v[180:183], v[140:143]
	v_mfma_f32_16x16x32_bf16 v[136:139], v[156:159], v[180:183], v[136:139]
	v_mfma_f32_16x16x32_bf16 v[108:111], v[148:151], v[188:191], v[108:111]
	v_mfma_f32_16x16x32_bf16 v[104:107], v[156:159], v[188:191], v[104:107]
	v_mfma_f32_16x16x32_bf16 v[92:95], v[148:151], v[196:199], v[92:95]
	v_mfma_f32_16x16x32_bf16 v[88:91], v[156:159], v[196:199], v[88:91]
	v_mfma_f32_16x16x32_bf16 v[76:79], v[148:151], v[204:207], v[76:79]
	v_mfma_f32_16x16x32_bf16 v[72:75], v[156:159], v[204:207], v[72:75]
	v_mfma_f32_16x16x32_bf16 v[120:123], v[160:163], v[176:179], v[120:123]
	v_mfma_f32_16x16x32_bf16 v[112:115], v[168:171], v[176:179], v[112:115]
	v_mfma_f32_16x16x32_bf16 v[100:103], v[160:163], v[184:187], v[100:103]
	v_mfma_f32_16x16x32_bf16 v[96:99], v[168:171], v[184:187], v[96:99]
	v_mfma_f32_16x16x32_bf16 v[84:87], v[160:163], v[192:195], v[84:87]
	v_mfma_f32_16x16x32_bf16 v[80:83], v[168:171], v[192:195], v[80:83]
	v_mfma_f32_16x16x32_bf16 v[68:71], v[160:163], v[200:203], v[68:71]
	v_mfma_f32_16x16x32_bf16 v[64:67], v[168:171], v[200:203], v[64:67]
	v_mfma_f32_16x16x32_bf16 v[120:123], v[164:167], v[180:183], v[120:123]
	v_mfma_f32_16x16x32_bf16 v[112:115], v[172:175], v[180:183], v[112:115]
	v_mfma_f32_16x16x32_bf16 v[100:103], v[164:167], v[188:191], v[100:103]
	v_mfma_f32_16x16x32_bf16 v[96:99], v[172:175], v[188:191], v[96:99]
	v_mfma_f32_16x16x32_bf16 v[84:87], v[164:167], v[196:199], v[84:87]
	v_mfma_f32_16x16x32_bf16 v[80:83], v[172:175], v[196:199], v[80:83]
	v_mfma_f32_16x16x32_bf16 v[68:71], v[164:167], v[204:207], v[68:71]
	v_mfma_f32_16x16x32_bf16 v[64:67], v[172:175], v[204:207], v[64:67]
	s_barrier
	s_setprio 0
	s_add_i32 s72, s73, s50
	v_lshl_add_u64 v[210:211], s[26:27], 0, v[208:209]
	s_mov_b32 m0, s72
	ds_read_b128 v[176:179], v135 offset:16384
	ds_read_b128 v[180:183], v135 offset:17408
	ds_read_b128 v[184:187], v135 offset:18432
	ds_read_b128 v[188:191], v135 offset:19456
	ds_read_b128 v[192:195], v135 offset:20480
	ds_read_b128 v[196:199], v135 offset:21504
	ds_read_b128 v[200:203], v135 offset:22528
	ds_read_b128 v[204:207], v135 offset:23552
	global_load_lds_dwordx4 v[210:211], off
	s_add_i32 m0, s72, 0x2000
	s_add_u32 s72, s26, 0x160000
	v_lshl_add_u64 v[212:213], s[26:27], 0, v[124:125]
	s_addc_u32 s73, s27, 0
	s_add_i32 s67, s67, s50
	global_load_lds_dwordx4 v[212:213], off
	v_lshl_add_u64 v[214:215], s[72:73], 0, v[208:209]
	s_mov_b32 m0, s67
	v_lshl_add_u64 v[216:217], s[44:45], 0, v[118:119]
	global_load_lds_dwordx4 v[214:215], off
	v_lshl_add_u64 v[214:215], s[72:73], 0, v[124:125]
	s_add_i32 m0, s67, 0x2000
	s_nop 0
	global_load_lds_dwordx4 v[214:215], off
	v_lshl_add_u64 v[214:215], s[44:45], 0, v[116:117]
	s_mov_b32 m0, s51
	s_nop 0
	global_load_lds_dwordx4 v[214:215], off
	s_mov_b32 m0, s53
	s_nop 0
	global_load_lds_dwordx4 v[216:217], off
	s_waitcnt vmcnt(8) lgkmcnt(0)
	s_setprio 1
	s_barrier
; #define PG8_STAGE(bufoff, gbase, voff) do { _Pragma("unroll") for (int _i = 0; _i < 2; ++_i) \
;         __builtin_amdgcn_global_load_lds((const unsigned*)((const char*)(gbase) + (voff)[_i]), (LAS unsigned*)(lds + (bufoff) + ldsw + _i * 8192), 16, 0, 0); } while (0)
; #define PG8_LDA(dst, b, h) do { _Pragma("unroll") for (int m = 0; m < 4; ++m) _Pragma("unroll") for (int k = 0; k < 2; ++k) dst[m][k] = *(const LAS bf16x8*)(lds + PG8_SA(b, h) + aoff + m * 2048 + k * 1024); } while (0)
; #define PG8_LDB(dst, b, h) do { _Pragma("unroll") for (int n = 0; n < 2; ++n) _Pragma("unroll") for (int k = 0; k < 2; ++k) dst[n][k] = *(const LAS bf16x8*)(lds + PG8_SB(b, h) + boff + n * 2048 + k * 1024); } while (0)
; #define PG8_MMA(ai, bj, At, Bt) do { __builtin_amdgcn_s_setprio(1); _Pragma("unroll") for (int m = 0; m < 4; ++m) _Pragma("unroll") for (int n = 0; n < 2; ++n) _Pragma("unroll") for (int k = 0; k < 2; ++k) \
;         acc[ai][bj][m][n] = __builtin_amdgcn_mfma_f32_16x16x32_bf16(Bt[n][k], At[m][k], acc[ai][bj][m][n], 0, 0, 0); __builtin_amdgcn_s_setprio(0); } while (0)
; #define PG8_WAIT_V(n) asm volatile("s_waitcnt vmcnt(" #n ")" ::: "memory")
; #define PG8_WAIT_L(n) asm volatile("s_waitcnt lgkmcnt(" #n ")" ::: "memory")
; #define PG8_BAR __builtin_amdgcn_s_barrier()
; #define PG8_SCHED __builtin_amdgcn_sched_barrier(0)
; template <class Epi, class Sched>
; DI void gemm_phase(LAS unsigned char* lds, const Sched& S, const Epi& E) {
;     ...
;       PG8_WAIT_V(8); PG8_WAIT_L(0); PG8_BAR; PG8_MMA(0, 0, At, B0); PG8_MMA(0, 1, At, B1); PG8_BAR; PG8_SCHED;
;       PG8_LDA(At, 0, 1); PG8_STAGE(PG8_SB(0, 0), b2, voffB); PG8_STAGE(PG8_SB(0, 1), b2 + hstep, voffB); PG8_STAGE(PG8_SA(0, 0), a2, voffA);
;       PG8_WAIT_V(8); PG8_WAIT_L(0); PG8_BAR; PG8_MMA(1, 0, At, B0); PG8_MMA(1, 1, At, B1); PG8_BAR; PG8_SCHED;
;       PG8_LDB(B0, 1, 0); PG8_LDB(B1, 1, 1); PG8_SCHED; PG8_LDA(At, 1, 0); PG8_STAGE(PG8_SA(0, 1), a2 + hstep, voffA);
;       PG8_WAIT_V(8); PG8_WAIT_L(0); PG8_BAR; PG8_MMA(0, 0, At, B0); PG8_MMA(0, 1, At, B1); PG8_BAR; PG8_SCHED;
	v_mfma_f32_16x16x32_bf16 v[60:63], v[144:147], v[176:179], v[60:63]
	v_mfma_f32_16x16x32_bf16 v[56:59], v[152:155], v[176:179], v[56:59]
	v_mfma_f32_16x16x32_bf16 v[44:47], v[144:147], v[184:187], v[44:47]
	v_mfma_f32_16x16x32_bf16 v[40:43], v[152:155], v[184:187], v[40:43]
	v_mfma_f32_16x16x32_bf16 v[28:31], v[144:147], v[192:195], v[28:31]
	v_mfma_f32_16x16x32_bf16 v[24:27], v[152:155], v[192:195], v[24:27]
	v_mfma_f32_16x16x32_bf16 v[12:15], v[144:147], v[200:203], v[12:15]
	v_mfma_f32_16x16x32_bf16 v[8:11], v[152:155], v[200:203], v[8:11]
	v_mfma_f32_16x16x32_bf16 v[60:63], v[148:151], v[180:183], v[60:63]
	v_mfma_f32_16x16x32_bf16 v[56:59], v[156:159], v[180:183], v[56:59]
	v_mfma_f32_16x16x32_bf16 v[44:47], v[148:151], v[188:191], v[44:47]
	v_mfma_f32_16x16x32_bf16 v[40:43], v[156:159], v[188:191], v[40:43]
	v_mfma_f32_16x16x32_bf16 v[28:31], v[148:151], v[196:199], v[28:31]
	v_mfma_f32_16x16x32_bf16 v[24:27], v[156:159], v[196:199], v[24:27]
	v_mfma_f32_16x16x32_bf16 v[12:15], v[148:151], v[204:207], v[12:15]
	v_mfma_f32_16x16x32_bf16 v[8:11], v[156:159], v[204:207], v[8:11]
	v_mfma_f32_16x16x32_bf16 v[52:55], v[160:163], v[176:179], v[52:55]
	v_mfma_f32_16x16x32_bf16 v[48:51], v[168:171], v[176:179], v[48:51]
	v_mfma_f32_16x16x32_bf16 v[36:39], v[160:163], v[184:187], v[36:39]
	v_mfma_f32_16x16x32_bf16 v[32:35], v[168:171], v[184:187], v[32:35]
	v_mfma_f32_16x16x32_bf16 v[20:23], v[160:163], v[192:195], v[20:23]
	v_mfma_f32_16x16x32_bf16 v[16:19], v[168:171], v[192:195], v[16:19]
	v_mfma_f32_16x16x32_bf16 v[4:7], v[160:163], v[200:203], v[4:7]
	v_mfma_f32_16x16x32_bf16 v[0:3], v[168:171], v[200:203], v[0:3]
	v_mfma_f32_16x16x32_bf16 v[52:55], v[164:167], v[180:183], v[52:55]
	v_mfma_f32_16x16x32_bf16 v[48:51], v[172:175], v[180:183], v[48:51]
	v_mfma_f32_16x16x32_bf16 v[36:39], v[164:167], v[188:191], v[36:39]
	v_mfma_f32_16x16x32_bf16 v[32:35], v[172:175], v[188:191], v[32:35]
	v_mfma_f32_16x16x32_bf16 v[20:23], v[164:167], v[196:199], v[20:23]
	v_mfma_f32_16x16x32_bf16 v[16:19], v[172:175], v[196:199], v[16:19]
	v_mfma_f32_16x16x32_bf16 v[4:7], v[164:167], v[204:207], v[4:7]
	v_mfma_f32_16x16x32_bf16 v[0:3], v[172:175], v[204:207], v[0:3]
	s_barrier
	s_setprio 0
	s_add_i32 s67, 0, 0x18000
	s_add_i32 s72, 0, 0x1c000
	v_add_u32_e32 v156, s67, v134
	v_add_u32_e32 v172, s72, v134
	ds_read_b128 v[144:147], v156
	ds_read_b128 v[148:151], v156 offset:1024
	ds_read_b128 v[152:155], v156 offset:2048
	ds_read_b128 v[156:159], v156 offset:3072
	ds_read_b128 v[160:163], v172
	ds_read_b128 v[164:167], v172 offset:1024
	ds_read_b128 v[168:171], v172 offset:2048
	ds_read_b128 v[172:175], v172 offset:3072
	s_add_u32 s44, s44, 0x160000
	s_addc_u32 s45, s45, 0
	s_mov_b32 m0, s54
	v_lshl_add_u64 v[218:219], s[44:45], 0, v[116:117]
	ds_read_b128 v[176:179], v135 offset:32768
	ds_read_b128 v[180:183], v135 offset:33792
	ds_read_b128 v[184:187], v135 offset:34816
	ds_read_b128 v[188:191], v135 offset:35840
	ds_read_b128 v[192:195], v135 offset:36864
	ds_read_b128 v[196:199], v135 offset:37888
	ds_read_b128 v[200:203], v135 offset:38912
	ds_read_b128 v[204:207], v135 offset:39936
	global_load_lds_dwordx4 v[218:219], off
	v_lshl_add_u64 v[218:219], s[44:45], 0, v[118:119]
	s_mov_b32 m0, s55
	s_nop 0
	global_load_lds_dwordx4 v[218:219], off
	s_waitcnt vmcnt(8) lgkmcnt(0)
	s_setprio 1
	s_barrier
	v_mfma_f32_16x16x32_bf16 v[140:143], v[144:147], v[176:179], v[140:143]
	v_mfma_f32_16x16x32_bf16 v[136:139], v[152:155], v[176:179], v[136:139]
	v_mfma_f32_16x16x32_bf16 v[108:111], v[144:147], v[184:187], v[108:111]
	v_mfma_f32_16x16x32_bf16 v[104:107], v[152:155], v[184:187], v[104:107]
	v_mfma_f32_16x16x32_bf16 v[92:95], v[144:147], v[192:195], v[92:95]
	v_mfma_f32_16x16x32_bf16 v[88:91], v[152:155], v[192:195], v[88:91]
	v_mfma_f32_16x16x32_bf16 v[76:79], v[144:147], v[200:203], v[76:79]
	v_mfma_f32_16x16x32_bf16 v[72:75], v[152:155], v[200:203], v[72:75]
	v_mfma_f32_16x16x32_bf16 v[140:143], v[148:151], v[180:183], v[140:143]
	v_mfma_f32_16x16x32_bf16 v[136:139], v[156:159], v[180:183], v[136:139]
	v_mfma_f32_16x16x32_bf16 v[108:111], v[148:151], v[188:191], v[108:111]
	v_mfma_f32_16x16x32_bf16 v[104:107], v[156:159], v[188:191], v[104:107]
	v_mfma_f32_16x16x32_bf16 v[92:95], v[148:151], v[196:199], v[92:95]
	v_mfma_f32_16x16x32_bf16 v[88:91], v[156:159], v[196:199], v[88:91]
	v_mfma_f32_16x16x32_bf16 v[76:79], v[148:151], v[204:207], v[76:79]
	v_mfma_f32_16x16x32_bf16 v[72:75], v[156:159], v[204:207], v[72:75]
	v_mfma_f32_16x16x32_bf16 v[120:123], v[160:163], v[176:179], v[120:123]
	v_mfma_f32_16x16x32_bf16 v[112:115], v[168:171], v[176:179], v[112:115]
	v_mfma_f32_16x16x32_bf16 v[100:103], v[160:163], v[184:187], v[100:103]
	v_mfma_f32_16x16x32_bf16 v[96:99], v[168:171], v[184:187], v[96:99]
	v_mfma_f32_16x16x32_bf16 v[84:87], v[160:163], v[192:195], v[84:87]
	v_mfma_f32_16x16x32_bf16 v[80:83], v[168:171], v[192:195], v[80:83]
	v_mfma_f32_16x16x32_bf16 v[68:71], v[160:163], v[200:203], v[68:71]
	v_mfma_f32_16x16x32_bf16 v[64:67], v[168:171], v[200:203], v[64:67]
	v_mfma_f32_16x16x32_bf16 v[120:123], v[164:167], v[180:183], v[120:123]
	v_mfma_f32_16x16x32_bf16 v[112:115], v[172:175], v[180:183], v[112:115]
	v_mfma_f32_16x16x32_bf16 v[100:103], v[164:167], v[188:191], v[100:103]
	v_mfma_f32_16x16x32_bf16 v[96:99], v[172:175], v[188:191], v[96:99]
	v_mfma_f32_16x16x32_bf16 v[84:87], v[164:167], v[196:199], v[84:87]
	v_mfma_f32_16x16x32_bf16 v[80:83], v[172:175], v[196:199], v[80:83]
	v_mfma_f32_16x16x32_bf16 v[68:71], v[164:167], v[204:207], v[68:71]
	v_mfma_f32_16x16x32_bf16 v[64:67], v[172:175], v[204:207], v[64:67]
	s_barrier
; #define PG8_STAGE(bufoff, gbase, voff) do { _Pragma("unroll") for (int _i = 0; _i < 2; ++_i) \
;         __builtin_amdgcn_global_load_lds((const unsigned*)((const char*)(gbase) + (voff)[_i]), (LAS unsigned*)(lds + (bufoff) + ldsw + _i * 8192), 16, 0, 0); } while (0)
; #define PG8_LDA(dst, b, h) do { _Pragma("unroll") for (int m = 0; m < 4; ++m) _Pragma("unroll") for (int k = 0; k < 2; ++k) dst[m][k] = *(const LAS bf16x8*)(lds + PG8_SA(b, h) + aoff + m * 2048 + k * 1024); } while (0)
; #define PG8_LDB(dst, b, h) do { _Pragma("unroll") for (int n = 0; n < 2; ++n) _Pragma("unroll") for (int k = 0; k < 2; ++k) dst[n][k] = *(const LAS bf16x8*)(lds + PG8_SB(b, h) + boff + n * 2048 + k * 1024); } while (0)
; #define PG8_MMA(ai, bj, At, Bt) do { __builtin_amdgcn_s_setprio(1); _Pragma("unroll") for (int m = 0; m < 4; ++m) _Pragma("unroll") for (int n = 0; n < 2; ++n) _Pragma("unroll") for (int k = 0; k < 2; ++k) \
;         acc[ai][bj][m][n] = __builtin_amdgcn_mfma_f32_16x16x32_bf16(Bt[n][k], At[m][k], acc[ai][bj][m][n], 0, 0, 0); __builtin_amdgcn_s_setprio(0); } while (0)
; #define PG8_WAIT_V(n) asm volatile("s_waitcnt vmcnt(" #n ")" ::: "memory")
; #define PG8_WAIT_L(n) asm volatile("s_waitcnt lgkmcnt(" #n ")" ::: "memory")
; #define PG8_BAR __builtin_amdgcn_s_barrier()
; #define PG8_SCHED __builtin_amdgcn_sched_barrier(0)
; template <class Epi, class Sched>
; DI void gemm_phase(LAS unsigned char* lds, const Sched& S, const Epi& E) {
;     ...
;       PG8_LDB(B0, 1, 0); PG8_LDB(B1, 1, 1); PG8_SCHED; PG8_LDA(At, 1, 0); PG8_STAGE(PG8_SA(0, 1), a2 + hstep, voffA);
;       PG8_WAIT_V(8); PG8_WAIT_L(0); PG8_BAR; PG8_MMA(0, 0, At, B0); PG8_MMA(0, 1, At, B1); PG8_BAR; PG8_SCHED;
;       PG8_LDA(At, 1, 1); PG8_STAGE(PG8_SB(1, 0), b3, voffB); PG8_STAGE(PG8_SB(1, 1), b3 + hstep, voffB); PG8_STAGE(PG8_SA(1, 0), a3, voffA);
;       PG8_WAIT_V(8); PG8_WAIT_L(0); PG8_BAR; PG8_MMA(1, 0, At, B0); PG8_MMA(1, 1, At, B1); PG8_BAR; PG8_SCHED;
;     }
;     if (wr == 0) PG8_BAR;
;     if constexpr (Epi::CARRY) E.carry(acc, cur, wr, wc, fr, fq);
;     else if constexpr (!Epi::AFTER_DRAIN) E(acc, cur, wr, wc, fr, fq);
;     if (!has_next) break;
	s_setprio 0
	s_add_i32 s44, s67, s50
	v_lshl_add_u64 v[210:211], v[210:211], 0, s[6:7]
	s_mov_b32 m0, s44
	ds_read_b128 v[176:179], v135 offset:49152
	ds_read_b128 v[180:183], v135 offset:50176
	ds_read_b128 v[184:187], v135 offset:51200
	ds_read_b128 v[188:191], v135 offset:52224
	ds_read_b128 v[192:195], v135 offset:53248
	ds_read_b128 v[196:199], v135 offset:54272
	ds_read_b128 v[200:203], v135 offset:55296
	ds_read_b128 v[204:207], v135 offset:56320
	global_load_lds_dwordx4 v[210:211], off
	s_add_i32 m0, s44, 0x2000
	s_add_u32 s26, s26, 0x160080
	v_lshl_add_u64 v[210:211], v[212:213], 0, s[6:7]
	s_addc_u32 s27, s27, 0
	s_add_i32 s44, s72, s50
	global_load_lds_dwordx4 v[210:211], off
	v_lshl_add_u64 v[210:211], s[26:27], 0, v[208:209]
	s_mov_b32 m0, s44
	s_nop 0
	global_load_lds_dwordx4 v[210:211], off
	v_lshl_add_u64 v[210:211], s[26:27], 0, v[124:125]
	s_add_i32 m0, s44, 0x2000
	s_nop 0
	global_load_lds_dwordx4 v[210:211], off
	v_lshl_add_u64 v[210:211], v[214:215], 0, s[6:7]
	s_mov_b32 m0, s58
	s_nop 0
	global_load_lds_dwordx4 v[210:211], off
	v_lshl_add_u64 v[210:211], v[216:217], 0, s[6:7]
	s_mov_b32 m0, s59
	s_nop 0
	global_load_lds_dwordx4 v[210:211], off
	s_waitcnt vmcnt(8) lgkmcnt(0)
	s_setprio 1
	s_barrier
	v_mfma_f32_16x16x32_bf16 v[60:63], v[144:147], v[176:179], v[60:63]
	v_mfma_f32_16x16x32_bf16 v[56:59], v[152:155], v[176:179], v[56:59]
	v_mfma_f32_16x16x32_bf16 v[44:47], v[144:147], v[184:187], v[44:47]
	v_mfma_f32_16x16x32_bf16 v[40:43], v[152:155], v[184:187], v[40:43]
	v_mfma_f32_16x16x32_bf16 v[28:31], v[144:147], v[192:195], v[28:31]
	v_mfma_f32_16x16x32_bf16 v[24:27], v[152:155], v[192:195], v[24:27]
	v_mfma_f32_16x16x32_bf16 v[12:15], v[144:147], v[200:203], v[12:15]
	v_mfma_f32_16x16x32_bf16 v[8:11], v[152:155], v[200:203], v[8:11]
	v_mfma_f32_16x16x32_bf16 v[60:63], v[148:151], v[180:183], v[60:63]
	v_mfma_f32_16x16x32_bf16 v[56:59], v[156:159], v[180:183], v[56:59]
	v_mfma_f32_16x16x32_bf16 v[44:47], v[148:151], v[188:191], v[44:47]
	v_mfma_f32_16x16x32_bf16 v[40:43], v[156:159], v[188:191], v[40:43]
	v_mfma_f32_16x16x32_bf16 v[28:31], v[148:151], v[196:199], v[28:31]
	v_mfma_f32_16x16x32_bf16 v[24:27], v[156:159], v[196:199], v[24:27]
	v_mfma_f32_16x16x32_bf16 v[12:15], v[148:151], v[204:207], v[12:15]
	v_mfma_f32_16x16x32_bf16 v[8:11], v[156:159], v[204:207], v[8:11]
	v_mfma_f32_16x16x32_bf16 v[52:55], v[160:163], v[176:179], v[52:55]
	v_mfma_f32_16x16x32_bf16 v[48:51], v[168:171], v[176:179], v[48:51]
	v_mfma_f32_16x16x32_bf16 v[36:39], v[160:163], v[184:187], v[36:39]
	v_mfma_f32_16x16x32_bf16 v[32:35], v[168:171], v[184:187], v[32:35]
	v_mfma_f32_16x16x32_bf16 v[20:23], v[160:163], v[192:195], v[20:23]
	v_mfma_f32_16x16x32_bf16 v[16:19], v[168:171], v[192:195], v[16:19]
	v_mfma_f32_16x16x32_bf16 v[4:7], v[160:163], v[200:203], v[4:7]
	v_mfma_f32_16x16x32_bf16 v[0:3], v[168:171], v[200:203], v[0:3]
	v_mfma_f32_16x16x32_bf16 v[52:55], v[164:167], v[180:183], v[52:55]
	v_mfma_f32_16x16x32_bf16 v[48:51], v[172:175], v[180:183], v[48:51]
	v_mfma_f32_16x16x32_bf16 v[36:39], v[164:167], v[188:191], v[36:39]
	v_mfma_f32_16x16x32_bf16 v[32:35], v[172:175], v[188:191], v[32:35]
	v_mfma_f32_16x16x32_bf16 v[20:23], v[164:167], v[196:199], v[20:23]
	v_mfma_f32_16x16x32_bf16 v[16:19], v[172:175], v[196:199], v[16:19]
	v_mfma_f32_16x16x32_bf16 v[4:7], v[164:167], v[204:207], v[4:7]
	v_mfma_f32_16x16x32_bf16 v[0:3], v[172:175], v[204:207], v[0:3]
	s_barrier
	s_setprio 0
	s_add_i32 s66, s66, 2
	s_add_u32 s22, s22, 0x100
	s_addc_u32 s23, s23, 0
	s_cmpk_gt_u32 s66, 0x55
	s_cbranch_scc0 .LBB0_256
	s_and_b64 vcc, exec, s[38:39]
	s_cbranch_vccz .LBB0_259
	s_barrier

; #define PG8_STAGE(bufoff, gbase, voff) do { _Pragma("unroll") for (int _i = 0; _i < 2; ++_i) \
;         __builtin_amdgcn_global_load_lds((const unsigned*)((const char*)(gbase) + (voff)[_i]), (LAS unsigned*)(lds + (bufoff) + ldsw + _i * 8192), 16, 0, 0); } while (0)
; #define PG8_LDA(dst, b, h) do { _Pragma("unroll") for (int m = 0; m < 4; ++m) _Pragma("unroll") for (int k = 0; k < 2; ++k) dst[m][k] = *(const LAS bf16x8*)(lds + PG8_SA(b, h) + aoff + m * 2048 + k * 1024); } while (0)
; #define PG8_LDB(dst, b, h) do { _Pragma("unroll") for (int n = 0; n < 2; ++n) _Pragma("unroll") for (int k = 0; k < 2; ++k) dst[n][k] = *(const LAS bf16x8*)(lds + PG8_SB(b, h) + boff + n * 2048 + k * 1024); } while (0)
; #define PG8_MMA(ai, bj, At, Bt) do { __builtin_amdgcn_s_setprio(1); _Pragma("unroll") for (int m = 0; m < 4; ++m) _Pragma("unroll") for (int n = 0; n < 2; ++n) _Pragma("unroll") for (int k = 0; k < 2; ++k) \
;         acc[ai][bj][m][n] = __builtin_amdgcn_mfma_f32_16x16x32_bf16(Bt[n][k], At[m][k], acc[ai][bj][m][n], 0, 0, 0); __builtin_amdgcn_s_setprio(0); } while (0)
; #define PG8_WAIT_V(n) asm volatile("s_waitcnt vmcnt(" #n ")" ::: "memory")
; #define PG8_WAIT_L(n) asm volatile("s_waitcnt lgkmcnt(" #n ")" ::: "memory")
; #define PG8_BAR __builtin_amdgcn_s_barrier()
; #define PG8_SCHED __builtin_amdgcn_sched_barrier(0)
; template <class Epi, class Sched>
; DI void gemm_phase(LAS unsigned char* lds, const Sched& S, const Epi& E) {
;     ...
;     for (int t = 0; t < nt; t += 2) {
;       const bool last = (t == nt - 2);
;       const char* a1 = cA + (size_t)(t + 1) * kstep;
;       const char* a2 = last ? nA : cA + (size_t)(t + 2) * kstep; const char* b2 = last ? nB : cB + (size_t)(t + 2) * kstep;
;       const char* a3 = a2 + kstep; const char* b3 = b2 + kstep;
;       PG8_LDB(B0, 0, 0); PG8_LDB(B1, 0, 1); PG8_SCHED; PG8_LDA(At, 0, 0); PG8_STAGE(PG8_SA(1, 1), a1 + hstep, voffA);
;       PG8_WAIT_V(8); PG8_WAIT_L(0); PG8_BAR; PG8_MMA(0, 0, At, B0); PG8_MMA(0, 1, At, B1); PG8_BAR; PG8_SCHED;
;       PG8_LDA(At, 0, 1); PG8_STAGE(PG8_SB(0, 0), b2, voffB); PG8_STAGE(PG8_SB(0, 1), b2 + hstep, voffB); PG8_STAGE(PG8_SA(0, 0), a2, voffA);
;       PG8_WAIT_V(8); PG8_WAIT_L(0); PG8_BAR; PG8_MMA(1, 0, At, B0); PG8_MMA(1, 1, At, B1); PG8_BAR; PG8_SCHED;
.LBB0_444:
	s_add_u32 s22, s24, 0x100
	s_addc_u32 s23, s25, 0
	s_add_i32 s65, 0, 0x10000
	s_cmpk_eq_i32 s64, 0x54
	s_cselect_b32 s45, s1, s23
	s_cselect_b32 s44, s0, s22
	s_cselect_b32 s27, s43, s63
	s_cselect_b32 s26, s42, s62
	s_add_i32 s66, 0, 0x14000
	v_add_u32_e32 v154, s65, v143
	v_add_u32_e32 v170, s66, v143
	ds_read_b128 v[138:141], v154
	ds_read_b128 v[146:149], v154 offset:1024
	ds_read_b128 v[150:153], v154 offset:2048
	ds_read_b128 v[154:157], v154 offset:3072
	ds_read_b128 v[158:161], v170
	ds_read_b128 v[162:165], v170 offset:1024
	ds_read_b128 v[166:169], v170 offset:2048
	ds_read_b128 v[170:173], v170 offset:3072
	v_lshl_add_u64 v[206:207], s[24:25], 0, v[134:135]
	s_add_i32 m0, s51, 0xc000
	ds_read_b128 v[174:177], v145
	ds_read_b128 v[178:181], v145 offset:1024
	ds_read_b128 v[182:185], v145 offset:2048
	ds_read_b128 v[186:189], v145 offset:3072
	ds_read_b128 v[190:193], v145 offset:4096
	ds_read_b128 v[194:197], v145 offset:5120
	ds_read_b128 v[198:201], v145 offset:6144
	ds_read_b128 v[202:205], v145 offset:7168
	global_load_lds_dwordx4 v[206:207], off
	v_lshl_add_u64 v[206:207], s[24:25], 0, v[136:137]
	s_add_i32 m0, s51, 0xe000
	s_nop 0
	global_load_lds_dwordx4 v[206:207], off
	s_waitcnt vmcnt(8) lgkmcnt(0)
	s_setprio 1
	s_barrier
	v_mfma_f32_16x16x32_bf16 v[124:127], v[138:141], v[174:177], v[124:127]
	v_mfma_f32_16x16x32_bf16 v[120:123], v[150:153], v[174:177], v[120:123]
	v_mfma_f32_16x16x32_bf16 v[108:111], v[138:141], v[182:185], v[108:111]
	v_mfma_f32_16x16x32_bf16 v[104:107], v[150:153], v[182:185], v[104:107]
	v_mfma_f32_16x16x32_bf16 v[92:95], v[138:141], v[190:193], v[92:95]
	v_mfma_f32_16x16x32_bf16 v[88:91], v[150:153], v[190:193], v[88:91]
	v_mfma_f32_16x16x32_bf16 v[76:79], v[138:141], v[198:201], v[76:79]
	v_mfma_f32_16x16x32_bf16 v[72:75], v[150:153], v[198:201], v[72:75]
	v_mfma_f32_16x16x32_bf16 v[124:127], v[146:149], v[178:181], v[124:127]
	v_mfma_f32_16x16x32_bf16 v[120:123], v[154:157], v[178:181], v[120:123]
	v_mfma_f32_16x16x32_bf16 v[108:111], v[146:149], v[186:189], v[108:111]
	v_mfma_f32_16x16x32_bf16 v[104:107], v[154:157], v[186:189], v[104:107]
	v_mfma_f32_16x16x32_bf16 v[92:95], v[146:149], v[194:197], v[92:95]
	v_mfma_f32_16x16x32_bf16 v[88:91], v[154:157], v[194:197], v[88:91]
	v_mfma_f32_16x16x32_bf16 v[76:79], v[146:149], v[202:205], v[76:79]
	v_mfma_f32_16x16x32_bf16 v[72:75], v[154:157], v[202:205], v[72:75]
	v_mfma_f32_16x16x32_bf16 v[116:119], v[158:161], v[174:177], v[116:119]
	v_mfma_f32_16x16x32_bf16 v[112:115], v[166:169], v[174:177], v[112:115]
	v_mfma_f32_16x16x32_bf16 v[100:103], v[158:161], v[182:185], v[100:103]
	v_mfma_f32_16x16x32_bf16 v[96:99], v[166:169], v[182:185], v[96:99]
	v_mfma_f32_16x16x32_bf16 v[84:87], v[158:161], v[190:193], v[84:87]
	v_mfma_f32_16x16x32_bf16 v[80:83], v[166:169], v[190:193], v[80:83]
	v_mfma_f32_16x16x32_bf16 v[68:71], v[158:161], v[198:201], v[68:71]
	v_mfma_f32_16x16x32_bf16 v[64:67], v[166:169], v[198:201], v[64:67]
	v_mfma_f32_16x16x32_bf16 v[116:119], v[162:165], v[178:181], v[116:119]
	v_mfma_f32_16x16x32_bf16 v[112:115], v[170:173], v[178:181], v[112:115]
	v_mfma_f32_16x16x32_bf16 v[100:103], v[162:165], v[186:189], v[100:103]
	v_mfma_f32_16x16x32_bf16 v[96:99], v[170:173], v[186:189], v[96:99]
	v_mfma_f32_16x16x32_bf16 v[84:87], v[162:165], v[194:197], v[84:87]
	v_mfma_f32_16x16x32_bf16 v[80:83], v[170:173], v[194:197], v[80:83]
	v_mfma_f32_16x16x32_bf16 v[68:71], v[162:165], v[202:205], v[68:71]
	v_mfma_f32_16x16x32_bf16 v[64:67], v[170:173], v[202:205], v[64:67]
	s_barrier
	s_setprio 0
	s_add_i32 s24, s65, s50
	v_lshl_add_u64 v[206:207], s[26:27], 0, v[208:209]
	s_mov_b32 m0, s24
	ds_read_b128 v[174:177], v145 offset:16384
	ds_read_b128 v[178:181], v145 offset:17408
	ds_read_b128 v[182:185], v145 offset:18432
	ds_read_b128 v[186:189], v145 offset:19456
	ds_read_b128 v[190:193], v145 offset:20480
	ds_read_b128 v[194:197], v145 offset:21504
	ds_read_b128 v[198:201], v145 offset:22528
	ds_read_b128 v[202:205], v145 offset:23552
	global_load_lds_dwordx4 v[206:207], off
	s_add_i32 m0, s24, 0x2000
	s_add_u32 s24, s26, 0x160000
	v_lshl_add_u64 v[210:211], s[26:27], 0, v[132:133]
	s_addc_u32 s25, s27, 0
	s_add_i32 s65, s66, s50
	global_load_lds_dwordx4 v[210:211], off
	v_lshl_add_u64 v[212:213], s[24:25], 0, v[208:209]
	s_mov_b32 m0, s65
	v_lshl_add_u64 v[214:215], s[44:45], 0, v[130:131]
	global_load_lds_dwordx4 v[212:213], off
	v_lshl_add_u64 v[212:213], s[24:25], 0, v[132:133]
	s_add_i32 m0, s65, 0x2000
	s_nop 0
	global_load_lds_dwordx4 v[212:213], off
	v_lshl_add_u64 v[212:213], s[44:45], 0, v[128:129]
	s_mov_b32 m0, s51
	s_nop 0
	global_load_lds_dwordx4 v[212:213], off
	s_mov_b32 m0, s52
	s_nop 0
	global_load_lds_dwordx4 v[214:215], off
	s_waitcnt vmcnt(8) lgkmcnt(0)
	s_setprio 1
	s_barrier
; #define PG8_STAGE(bufoff, gbase, voff) do { _Pragma("unroll") for (int _i = 0; _i < 2; ++_i) \
;         __builtin_amdgcn_global_load_lds((const unsigned*)((const char*)(gbase) + (voff)[_i]), (LAS unsigned*)(lds + (bufoff) + ldsw + _i * 8192), 16, 0, 0); } while (0)
; #define PG8_LDA(dst, b, h) do { _Pragma("unroll") for (int m = 0; m < 4; ++m) _Pragma("unroll") for (int k = 0; k < 2; ++k) dst[m][k] = *(const LAS bf16x8*)(lds + PG8_SA(b, h) + aoff + m * 2048 + k * 1024); } while (0)
; #define PG8_LDB(dst, b, h) do { _Pragma("unroll") for (int n = 0; n < 2; ++n) _Pragma("unroll") for (int k = 0; k < 2; ++k) dst[n][k] = *(const LAS bf16x8*)(lds + PG8_SB(b, h) + boff + n * 2048 + k * 1024); } while (0)
; #define PG8_MMA(ai, bj, At, Bt) do { __builtin_amdgcn_s_setprio(1); _Pragma("unroll") for (int m = 0; m < 4; ++m) _Pragma("unroll") for (int n = 0; n < 2; ++n) _Pragma("unroll") for (int k = 0; k < 2; ++k) \
;         acc[ai][bj][m][n] = __builtin_amdgcn_mfma_f32_16x16x32_bf16(Bt[n][k], At[m][k], acc[ai][bj][m][n], 0, 0, 0); __builtin_amdgcn_s_setprio(0); } while (0)
; #define PG8_WAIT_V(n) asm volatile("s_waitcnt vmcnt(" #n ")" ::: "memory")
; #define PG8_WAIT_L(n) asm volatile("s_waitcnt lgkmcnt(" #n ")" ::: "memory")
; #define PG8_BAR __builtin_amdgcn_s_barrier()
; #define PG8_SCHED __builtin_amdgcn_sched_barrier(0)
; template <class Epi, class Sched>
; DI void gemm_phase(LAS unsigned char* lds, const Sched& S, const Epi& E) {
;     ...
;       PG8_WAIT_V(8); PG8_WAIT_L(0); PG8_BAR; PG8_MMA(0, 0, At, B0); PG8_MMA(0, 1, At, B1); PG8_BAR; PG8_SCHED;
;       PG8_LDA(At, 0, 1); PG8_STAGE(PG8_SB(0, 0), b2, voffB); PG8_STAGE(PG8_SB(0, 1), b2 + hstep, voffB); PG8_STAGE(PG8_SA(0, 0), a2, voffA);
;       PG8_WAIT_V(8); PG8_WAIT_L(0); PG8_BAR; PG8_MMA(1, 0, At, B0); PG8_MMA(1, 1, At, B1); PG8_BAR; PG8_SCHED;
;       PG8_LDB(B0, 1, 0); PG8_LDB(B1, 1, 1); PG8_SCHED; PG8_LDA(At, 1, 0); PG8_STAGE(PG8_SA(0, 1), a2 + hstep, voffA);
;       PG8_WAIT_V(8); PG8_WAIT_L(0); PG8_BAR; PG8_MMA(0, 0, At, B0); PG8_MMA(0, 1, At, B1); PG8_BAR; PG8_SCHED;
	v_mfma_f32_16x16x32_bf16 v[60:63], v[138:141], v[174:177], v[60:63]
	v_mfma_f32_16x16x32_bf16 v[56:59], v[150:153], v[174:177], v[56:59]
	v_mfma_f32_16x16x32_bf16 v[44:47], v[138:141], v[182:185], v[44:47]
	v_mfma_f32_16x16x32_bf16 v[40:43], v[150:153], v[182:185], v[40:43]
	v_mfma_f32_16x16x32_bf16 v[28:31], v[138:141], v[190:193], v[28:31]
	v_mfma_f32_16x16x32_bf16 v[24:27], v[150:153], v[190:193], v[24:27]
	v_mfma_f32_16x16x32_bf16 v[12:15], v[138:141], v[198:201], v[12:15]
	v_mfma_f32_16x16x32_bf16 v[8:11], v[150:153], v[198:201], v[8:11]
	v_mfma_f32_16x16x32_bf16 v[60:63], v[146:149], v[178:181], v[60:63]
	v_mfma_f32_16x16x32_bf16 v[56:59], v[154:157], v[178:181], v[56:59]
	v_mfma_f32_16x16x32_bf16 v[44:47], v[146:149], v[186:189], v[44:47]
	v_mfma_f32_16x16x32_bf16 v[40:43], v[154:157], v[186:189], v[40:43]
	v_mfma_f32_16x16x32_bf16 v[28:31], v[146:149], v[194:197], v[28:31]
	v_mfma_f32_16x16x32_bf16 v[24:27], v[154:157], v[194:197], v[24:27]
	v_mfma_f32_16x16x32_bf16 v[12:15], v[146:149], v[202:205], v[12:15]
	v_mfma_f32_16x16x32_bf16 v[8:11], v[154:157], v[202:205], v[8:11]
	v_mfma_f32_16x16x32_bf16 v[52:55], v[158:161], v[174:177], v[52:55]
	v_mfma_f32_16x16x32_bf16 v[48:51], v[166:169], v[174:177], v[48:51]
	v_mfma_f32_16x16x32_bf16 v[36:39], v[158:161], v[182:185], v[36:39]
	v_mfma_f32_16x16x32_bf16 v[32:35], v[166:169], v[182:185], v[32:35]
	v_mfma_f32_16x16x32_bf16 v[20:23], v[158:161], v[190:193], v[20:23]
	v_mfma_f32_16x16x32_bf16 v[16:19], v[166:169], v[190:193], v[16:19]
	v_mfma_f32_16x16x32_bf16 v[4:7], v[158:161], v[198:201], v[4:7]
	v_mfma_f32_16x16x32_bf16 v[0:3], v[166:169], v[198:201], v[0:3]
	v_mfma_f32_16x16x32_bf16 v[52:55], v[162:165], v[178:181], v[52:55]
	v_mfma_f32_16x16x32_bf16 v[48:51], v[170:173], v[178:181], v[48:51]
	v_mfma_f32_16x16x32_bf16 v[36:39], v[162:165], v[186:189], v[36:39]
	v_mfma_f32_16x16x32_bf16 v[32:35], v[170:173], v[186:189], v[32:35]
	v_mfma_f32_16x16x32_bf16 v[20:23], v[162:165], v[194:197], v[20:23]
	v_mfma_f32_16x16x32_bf16 v[16:19], v[170:173], v[194:197], v[16:19]
	v_mfma_f32_16x16x32_bf16 v[4:7], v[162:165], v[202:205], v[4:7]
	v_mfma_f32_16x16x32_bf16 v[0:3], v[170:173], v[202:205], v[0:3]
	s_barrier
	s_setprio 0
	s_add_i32 s65, 0, 0x18000
	s_add_i32 s66, 0, 0x1c000
	v_add_u32_e32 v154, s65, v143
	v_add_u32_e32 v170, s66, v143
	ds_read_b128 v[138:141], v154
	ds_read_b128 v[146:149], v154 offset:1024
	ds_read_b128 v[150:153], v154 offset:2048
	ds_read_b128 v[154:157], v154 offset:3072
	ds_read_b128 v[158:161], v170
	ds_read_b128 v[162:165], v170 offset:1024
	ds_read_b128 v[166:169], v170 offset:2048
	ds_read_b128 v[170:173], v170 offset:3072
	s_add_u32 s24, s44, 0x160000
	s_addc_u32 s25, s45, 0
	s_mov_b32 m0, s53
	v_lshl_add_u64 v[216:217], s[24:25], 0, v[128:129]
	ds_read_b128 v[174:177], v145 offset:32768
	ds_read_b128 v[178:181], v145 offset:33792
	ds_read_b128 v[182:185], v145 offset:34816
	ds_read_b128 v[186:189], v145 offset:35840
	ds_read_b128 v[190:193], v145 offset:36864
	ds_read_b128 v[194:197], v145 offset:37888
	ds_read_b128 v[198:201], v145 offset:38912
	ds_read_b128 v[202:205], v145 offset:39936
	global_load_lds_dwordx4 v[216:217], off
	v_lshl_add_u64 v[216:217], s[24:25], 0, v[130:131]
	s_mov_b32 m0, s54
	s_nop 0
	global_load_lds_dwordx4 v[216:217], off
	s_waitcnt vmcnt(8) lgkmcnt(0)
	s_setprio 1
	s_barrier
	v_mfma_f32_16x16x32_bf16 v[124:127], v[138:141], v[174:177], v[124:127]
	v_mfma_f32_16x16x32_bf16 v[120:123], v[150:153], v[174:177], v[120:123]
	v_mfma_f32_16x16x32_bf16 v[108:111], v[138:141], v[182:185], v[108:111]
	v_mfma_f32_16x16x32_bf16 v[104:107], v[150:153], v[182:185], v[104:107]
	v_mfma_f32_16x16x32_bf16 v[92:95], v[138:141], v[190:193], v[92:95]
	v_mfma_f32_16x16x32_bf16 v[88:91], v[150:153], v[190:193], v[88:91]
	v_mfma_f32_16x16x32_bf16 v[76:79], v[138:141], v[198:201], v[76:79]
	v_mfma_f32_16x16x32_bf16 v[72:75], v[150:153], v[198:201], v[72:75]
	v_mfma_f32_16x16x32_bf16 v[124:127], v[146:149], v[178:181], v[124:127]
	v_mfma_f32_16x16x32_bf16 v[120:123], v[154:157], v[178:181], v[120:123]
	v_mfma_f32_16x16x32_bf16 v[108:111], v[146:149], v[186:189], v[108:111]
	v_mfma_f32_16x16x32_bf16 v[104:107], v[154:157], v[186:189], v[104:107]
	v_mfma_f32_16x16x32_bf16 v[92:95], v[146:149], v[194:197], v[92:95]
	v_mfma_f32_16x16x32_bf16 v[88:91], v[154:157], v[194:197], v[88:91]
	v_mfma_f32_16x16x32_bf16 v[76:79], v[146:149], v[202:205], v[76:79]
	v_mfma_f32_16x16x32_bf16 v[72:75], v[154:157], v[202:205], v[72:75]
	v_mfma_f32_16x16x32_bf16 v[116:119], v[158:161], v[174:177], v[116:119]
	v_mfma_f32_16x16x32_bf16 v[112:115], v[166:169], v[174:177], v[112:115]
	v_mfma_f32_16x16x32_bf16 v[100:103], v[158:161], v[182:185], v[100:103]
	v_mfma_f32_16x16x32_bf16 v[96:99], v[166:169], v[182:185], v[96:99]
	v_mfma_f32_16x16x32_bf16 v[84:87], v[158:161], v[190:193], v[84:87]
	v_mfma_f32_16x16x32_bf16 v[80:83], v[166:169], v[190:193], v[80:83]
	v_mfma_f32_16x16x32_bf16 v[68:71], v[158:161], v[198:201], v[68:71]
	v_mfma_f32_16x16x32_bf16 v[64:67], v[166:169], v[198:201], v[64:67]
	v_mfma_f32_16x16x32_bf16 v[116:119], v[162:165], v[178:181], v[116:119]
	v_mfma_f32_16x16x32_bf16 v[112:115], v[170:173], v[178:181], v[112:115]
	v_mfma_f32_16x16x32_bf16 v[100:103], v[162:165], v[186:189], v[100:103]
	v_mfma_f32_16x16x32_bf16 v[96:99], v[170:173], v[186:189], v[96:99]
	v_mfma_f32_16x16x32_bf16 v[84:87], v[162:165], v[194:197], v[84:87]
	v_mfma_f32_16x16x32_bf16 v[80:83], v[170:173], v[194:197], v[80:83]
	v_mfma_f32_16x16x32_bf16 v[68:71], v[162:165], v[202:205], v[68:71]
	v_mfma_f32_16x16x32_bf16 v[64:67], v[170:173], v[202:205], v[64:67]
	s_barrier
; #define PG8_STAGE(bufoff, gbase, voff) do { _Pragma("unroll") for (int _i = 0; _i < 2; ++_i) \
;         __builtin_amdgcn_global_load_lds((const unsigned*)((const char*)(gbase) + (voff)[_i]), (LAS unsigned*)(lds + (bufoff) + ldsw + _i * 8192), 16, 0, 0); } while (0)
; #define PG8_LDA(dst, b, h) do { _Pragma("unroll") for (int m = 0; m < 4; ++m) _Pragma("unroll") for (int k = 0; k < 2; ++k) dst[m][k] = *(const LAS bf16x8*)(lds + PG8_SA(b, h) + aoff + m * 2048 + k * 1024); } while (0)
; #define PG8_LDB(dst, b, h) do { _Pragma("unroll") for (int n = 0; n < 2; ++n) _Pragma("unroll") for (int k = 0; k < 2; ++k) dst[n][k] = *(const LAS bf16x8*)(lds + PG8_SB(b, h) + boff + n * 2048 + k * 1024); } while (0)
; #define PG8_MMA(ai, bj, At, Bt) do { __builtin_amdgcn_s_setprio(1); _Pragma("unroll") for (int m = 0; m < 4; ++m) _Pragma("unroll") for (int n = 0; n < 2; ++n) _Pragma("unroll") for (int k = 0; k < 2; ++k) \
;         acc[ai][bj][m][n] = __builtin_amdgcn_mfma_f32_16x16x32_bf16(Bt[n][k], At[m][k], acc[ai][bj][m][n], 0, 0, 0); __builtin_amdgcn_s_setprio(0); } while (0)
; #define PG8_WAIT_V(n) asm volatile("s_waitcnt vmcnt(" #n ")" ::: "memory")
; #define PG8_WAIT_L(n) asm volatile("s_waitcnt lgkmcnt(" #n ")" ::: "memory")
; #define PG8_BAR __builtin_amdgcn_s_barrier()
; #define PG8_SCHED __builtin_amdgcn_sched_barrier(0)
; template <class Epi, class Sched>
; DI void gemm_phase(LAS unsigned char* lds, const Sched& S, const Epi& E) {
;     ...
;       PG8_LDB(B0, 1, 0); PG8_LDB(B1, 1, 1); PG8_SCHED; PG8_LDA(At, 1, 0); PG8_STAGE(PG8_SA(0, 1), a2 + hstep, voffA);
;       PG8_WAIT_V(8); PG8_WAIT_L(0); PG8_BAR; PG8_MMA(0, 0, At, B0); PG8_MMA(0, 1, At, B1); PG8_BAR; PG8_SCHED;
;       PG8_LDA(At, 1, 1); PG8_STAGE(PG8_SB(1, 0), b3, voffB); PG8_STAGE(PG8_SB(1, 1), b3 + hstep, voffB); PG8_STAGE(PG8_SA(1, 0), a3, voffA);
;       PG8_WAIT_V(8); PG8_WAIT_L(0); PG8_BAR; PG8_MMA(1, 0, At, B0); PG8_MMA(1, 1, At, B1); PG8_BAR; PG8_SCHED;
;     }
;     if (wr == 0) PG8_BAR;
;     if constexpr (Epi::CARRY) E.carry(acc, cur, wr, wc, fr, fq);
;     else if constexpr (!Epi::AFTER_DRAIN) E(acc, cur, wr, wc, fr, fq);
;     if (!has_next) break;
	s_setprio 0
	s_add_i32 s24, s65, s50
	v_lshl_add_u64 v[206:207], v[206:207], 0, s[6:7]
	s_mov_b32 m0, s24
	ds_read_b128 v[174:177], v145 offset:49152
	ds_read_b128 v[178:181], v145 offset:50176
	ds_read_b128 v[182:185], v145 offset:51200
	ds_read_b128 v[186:189], v145 offset:52224
	ds_read_b128 v[190:193], v145 offset:53248
	ds_read_b128 v[194:197], v145 offset:54272
	ds_read_b128 v[198:201], v145 offset:55296
	ds_read_b128 v[202:205], v145 offset:56320
	global_load_lds_dwordx4 v[206:207], off
	s_add_i32 m0, s24, 0x2000
	s_add_u32 s24, s26, 0x160080
	v_lshl_add_u64 v[206:207], v[210:211], 0, s[6:7]
	s_addc_u32 s25, s27, 0
	s_add_i32 s26, s66, s50
	global_load_lds_dwordx4 v[206:207], off
	v_lshl_add_u64 v[206:207], s[24:25], 0, v[208:209]
	s_mov_b32 m0, s26
	s_nop 0
	global_load_lds_dwordx4 v[206:207], off
	v_lshl_add_u64 v[206:207], s[24:25], 0, v[132:133]
	s_add_i32 m0, s26, 0x2000
	s_nop 0
	global_load_lds_dwordx4 v[206:207], off
	v_lshl_add_u64 v[206:207], v[212:213], 0, s[6:7]
	s_mov_b32 m0, s56
	s_nop 0
	global_load_lds_dwordx4 v[206:207], off
	v_lshl_add_u64 v[206:207], v[214:215], 0, s[6:7]
	s_mov_b32 m0, s57
	s_nop 0
	global_load_lds_dwordx4 v[206:207], off
	s_waitcnt vmcnt(8) lgkmcnt(0)
	s_setprio 1
	s_barrier
	v_mfma_f32_16x16x32_bf16 v[60:63], v[138:141], v[174:177], v[60:63]
	v_mfma_f32_16x16x32_bf16 v[56:59], v[150:153], v[174:177], v[56:59]
	v_mfma_f32_16x16x32_bf16 v[44:47], v[138:141], v[182:185], v[44:47]
	v_mfma_f32_16x16x32_bf16 v[40:43], v[150:153], v[182:185], v[40:43]
	v_mfma_f32_16x16x32_bf16 v[28:31], v[138:141], v[190:193], v[28:31]
	v_mfma_f32_16x16x32_bf16 v[24:27], v[150:153], v[190:193], v[24:27]
	v_mfma_f32_16x16x32_bf16 v[12:15], v[138:141], v[198:201], v[12:15]
	v_mfma_f32_16x16x32_bf16 v[8:11], v[150:153], v[198:201], v[8:11]
	v_mfma_f32_16x16x32_bf16 v[60:63], v[146:149], v[178:181], v[60:63]
	v_mfma_f32_16x16x32_bf16 v[56:59], v[154:157], v[178:181], v[56:59]
	v_mfma_f32_16x16x32_bf16 v[44:47], v[146:149], v[186:189], v[44:47]
	v_mfma_f32_16x16x32_bf16 v[40:43], v[154:157], v[186:189], v[40:43]
	v_mfma_f32_16x16x32_bf16 v[28:31], v[146:149], v[194:197], v[28:31]
	v_mfma_f32_16x16x32_bf16 v[24:27], v[154:157], v[194:197], v[24:27]
	v_mfma_f32_16x16x32_bf16 v[12:15], v[146:149], v[202:205], v[12:15]
	v_mfma_f32_16x16x32_bf16 v[8:11], v[154:157], v[202:205], v[8:11]
	v_mfma_f32_16x16x32_bf16 v[52:55], v[158:161], v[174:177], v[52:55]
	v_mfma_f32_16x16x32_bf16 v[48:51], v[166:169], v[174:177], v[48:51]
	v_mfma_f32_16x16x32_bf16 v[36:39], v[158:161], v[182:185], v[36:39]
	v_mfma_f32_16x16x32_bf16 v[32:35], v[166:169], v[182:185], v[32:35]
	v_mfma_f32_16x16x32_bf16 v[20:23], v[158:161], v[190:193], v[20:23]
	v_mfma_f32_16x16x32_bf16 v[16:19], v[166:169], v[190:193], v[16:19]
	v_mfma_f32_16x16x32_bf16 v[4:7], v[158:161], v[198:201], v[4:7]
	v_mfma_f32_16x16x32_bf16 v[0:3], v[166:169], v[198:201], v[0:3]
	v_mfma_f32_16x16x32_bf16 v[52:55], v[162:165], v[178:181], v[52:55]
	v_mfma_f32_16x16x32_bf16 v[48:51], v[170:173], v[178:181], v[48:51]
	v_mfma_f32_16x16x32_bf16 v[36:39], v[162:165], v[186:189], v[36:39]
	v_mfma_f32_16x16x32_bf16 v[32:35], v[170:173], v[186:189], v[32:35]
	v_mfma_f32_16x16x32_bf16 v[20:23], v[162:165], v[194:197], v[20:23]
	v_mfma_f32_16x16x32_bf16 v[16:19], v[170:173], v[194:197], v[16:19]
	v_mfma_f32_16x16x32_bf16 v[4:7], v[162:165], v[202:205], v[4:7]
	v_mfma_f32_16x16x32_bf16 v[0:3], v[170:173], v[202:205], v[0:3]
	s_barrier
	s_setprio 0
	s_add_i32 s64, s64, 2
	s_add_u32 s62, s62, 0x100
	s_addc_u32 s63, s63, 0
	s_cmpk_gt_u32 s64, 0x55
	s_mov_b64 s[24:25], s[22:23]
	s_cbranch_scc0 .LBB0_444
	s_and_b64 vcc, exec, s[40:41]
	s_cbranch_vccz .LBB0_447
	s_barrier

; #define PG8_STAGE(bufoff, gbase, voff) do { _Pragma("unroll") for (int _i = 0; _i < 2; ++_i) \
;         __builtin_amdgcn_global_load_lds((const unsigned*)((const char*)(gbase) + (voff)[_i]), (LAS unsigned*)(lds + (bufoff) + ldsw + _i * 8192), 16, 0, 0); } while (0)
; #define PG8_LDA(dst, b, h) do { _Pragma("unroll") for (int m = 0; m < 4; ++m) _Pragma("unroll") for (int k = 0; k < 2; ++k) dst[m][k] = *(const LAS bf16x8*)(lds + PG8_SA(b, h) + aoff + m * 2048 + k * 1024); } while (0)
; #define PG8_LDB(dst, b, h) do { _Pragma("unroll") for (int n = 0; n < 2; ++n) _Pragma("unroll") for (int k = 0; k < 2; ++k) dst[n][k] = *(const LAS bf16x8*)(lds + PG8_SB(b, h) + boff + n * 2048 + k * 1024); } while (0)
; #define PG8_MMA(ai, bj, At, Bt) do { __builtin_amdgcn_s_setprio(1); _Pragma("unroll") for (int m = 0; m < 4; ++m) _Pragma("unroll") for (int n = 0; n < 2; ++n) _Pragma("unroll") for (int k = 0; k < 2; ++k) \
;         acc[ai][bj][m][n] = __builtin_amdgcn_mfma_f32_16x16x32_bf16(Bt[n][k], At[m][k], acc[ai][bj][m][n], 0, 0, 0); __builtin_amdgcn_s_setprio(0); } while (0)
; #define PG8_WAIT_V(n) asm volatile("s_waitcnt vmcnt(" #n ")" ::: "memory")
; #define PG8_WAIT_L(n) asm volatile("s_waitcnt lgkmcnt(" #n ")" ::: "memory")
; #define PG8_BAR __builtin_amdgcn_s_barrier()
; #define PG8_SCHED __builtin_amdgcn_sched_barrier(0)
; template <class Epi, class Sched>
; DI void gemm_phase(LAS unsigned char* lds, const Sched& S, const Epi& E) {
;     ...
;     for (int t = 0; t < nt; t += 2) {
;       const bool last = (t == nt - 2);
;       const char* a1 = cA + (size_t)(t + 1) * kstep;
;       const char* a2 = last ? nA : cA + (size_t)(t + 2) * kstep; const char* b2 = last ? nB : cB + (size_t)(t + 2) * kstep;
;       const char* a3 = a2 + kstep; const char* b3 = b2 + kstep;
;       PG8_LDB(B0, 0, 0); PG8_LDB(B1, 0, 1); PG8_SCHED; PG8_LDA(At, 0, 0); PG8_STAGE(PG8_SA(1, 1), a1 + hstep, voffA);
;       PG8_WAIT_V(8); PG8_WAIT_L(0); PG8_BAR; PG8_MMA(0, 0, At, B0); PG8_MMA(0, 1, At, B1); PG8_BAR; PG8_SCHED;
;       PG8_LDA(At, 0, 1); PG8_STAGE(PG8_SB(0, 0), b2, voffB); PG8_STAGE(PG8_SB(0, 1), b2 + hstep, voffB); PG8_STAGE(PG8_SA(0, 0), a2, voffA);
;       PG8_WAIT_V(8); PG8_WAIT_L(0); PG8_BAR; PG8_MMA(1, 0, At, B0); PG8_MMA(1, 1, At, B1); PG8_BAR; PG8_SCHED;
.LBB0_479:
	s_add_u32 s22, vcc_lo, 0xfff80080
	s_addc_u32 s23, vcc_hi, -1
	s_add_i32 s80, 0, 0x10000
	s_cmp_eq_u32 s79, 28
	s_cselect_b32 s27, s44, s23
	s_cselect_b32 s26, s45, s22
	s_cselect_b32 s23, s67, s78
	s_cselect_b32 s22, s76, s77
	s_add_i32 s82, 0, 0x14000
	v_add_u32_e32 v44, s80, v167
	v_add_u32_e32 v68, s82, v167
	ds_read_b128 v[24:27], v44
	ds_read_b128 v[36:39], v44 offset:1024
	ds_read_b128 v[40:43], v44 offset:2048
	ds_read_b128 v[44:47], v44 offset:3072
	ds_read_b128 v[52:55], v68
	ds_read_b128 v[60:63], v68 offset:1024
	ds_read_b128 v[64:67], v68 offset:2048
	ds_read_b128 v[68:71], v68 offset:3072
	v_lshl_add_u64 v[210:211], vcc, 0, v[170:171]
	s_add_i32 m0, s51, 0xc000
	ds_read_b128 v[174:177], v195
	ds_read_b128 v[178:181], v195 offset:1024
	ds_read_b128 v[182:185], v195 offset:2048
	ds_read_b128 v[186:189], v195 offset:3072
	ds_read_b128 v[190:193], v195 offset:4096
	ds_read_b128 v[196:199], v195 offset:5120
	ds_read_b128 v[200:203], v195 offset:6144
	ds_read_b128 v[204:207], v195 offset:7168
	global_load_lds_dwordx4 v[210:211], off
	v_lshl_add_u64 v[210:211], vcc, 0, v[172:173]
	s_add_i32 m0, s51, 0xe000
	s_nop 0
	global_load_lds_dwordx4 v[210:211], off
	s_waitcnt vmcnt(8) lgkmcnt(0)
	s_setprio 1
	s_barrier
	v_mfma_f32_16x16x32_bf16 v[156:159], v[24:27], v[174:177], v[156:159]
	v_mfma_f32_16x16x32_bf16 v[152:155], v[40:43], v[174:177], v[152:155]
	v_mfma_f32_16x16x32_bf16 v[148:151], v[24:27], v[182:185], v[148:151]
	v_mfma_f32_16x16x32_bf16 v[140:143], v[40:43], v[182:185], v[140:143]
	v_mfma_f32_16x16x32_bf16 v[128:131], v[24:27], v[190:193], v[128:131]
	v_mfma_f32_16x16x32_bf16 v[120:123], v[40:43], v[190:193], v[120:123]
	v_mfma_f32_16x16x32_bf16 v[112:115], v[24:27], v[200:203], v[112:115]
	v_mfma_f32_16x16x32_bf16 v[104:107], v[40:43], v[200:203], v[104:107]
	v_mfma_f32_16x16x32_bf16 v[156:159], v[36:39], v[178:181], v[156:159]
	v_mfma_f32_16x16x32_bf16 v[152:155], v[44:47], v[178:181], v[152:155]
	v_mfma_f32_16x16x32_bf16 v[148:151], v[36:39], v[186:189], v[148:151]
	v_mfma_f32_16x16x32_bf16 v[140:143], v[44:47], v[186:189], v[140:143]
	v_mfma_f32_16x16x32_bf16 v[128:131], v[36:39], v[196:199], v[128:131]
	v_mfma_f32_16x16x32_bf16 v[120:123], v[44:47], v[196:199], v[120:123]
	v_mfma_f32_16x16x32_bf16 v[112:115], v[36:39], v[204:207], v[112:115]
	v_mfma_f32_16x16x32_bf16 v[104:107], v[44:47], v[204:207], v[104:107]
	v_mfma_f32_16x16x32_bf16 v[144:147], v[52:55], v[174:177], v[144:147]
	v_mfma_f32_16x16x32_bf16 v[136:139], v[64:67], v[174:177], v[136:139]
	v_mfma_f32_16x16x32_bf16 v[124:127], v[52:55], v[182:185], v[124:127]
	v_mfma_f32_16x16x32_bf16 v[132:135], v[64:67], v[182:185], v[132:135]
	v_mfma_f32_16x16x32_bf16 v[108:111], v[52:55], v[190:193], v[108:111]
	v_mfma_f32_16x16x32_bf16 v[116:119], v[64:67], v[190:193], v[116:119]
	v_mfma_f32_16x16x32_bf16 v[96:99], v[52:55], v[200:203], v[96:99]
	v_mfma_f32_16x16x32_bf16 v[100:103], v[64:67], v[200:203], v[100:103]
	v_mfma_f32_16x16x32_bf16 v[144:147], v[60:63], v[178:181], v[144:147]
	v_mfma_f32_16x16x32_bf16 v[136:139], v[68:71], v[178:181], v[136:139]
	v_mfma_f32_16x16x32_bf16 v[124:127], v[60:63], v[186:189], v[124:127]
	v_mfma_f32_16x16x32_bf16 v[132:135], v[68:71], v[186:189], v[132:135]
	v_mfma_f32_16x16x32_bf16 v[108:111], v[60:63], v[196:199], v[108:111]
	v_mfma_f32_16x16x32_bf16 v[116:119], v[68:71], v[196:199], v[116:119]
	v_mfma_f32_16x16x32_bf16 v[96:99], v[60:63], v[204:207], v[96:99]
	v_mfma_f32_16x16x32_bf16 v[100:103], v[68:71], v[204:207], v[100:103]
	s_barrier
	s_setprio 0
	s_add_i32 s80, s80, s47
	v_lshl_add_u64 v[214:215], s[22:23], 0, v[208:209]
	s_mov_b32 m0, s80
	ds_read_b128 v[174:177], v195 offset:16384
	ds_read_b128 v[178:181], v195 offset:17408
	ds_read_b128 v[182:185], v195 offset:18432
	ds_read_b128 v[186:189], v195 offset:19456
	ds_read_b128 v[190:193], v195 offset:20480
	ds_read_b128 v[196:199], v195 offset:21504
	ds_read_b128 v[200:203], v195 offset:22528
	ds_read_b128 v[204:207], v195 offset:23552
	global_load_lds_dwordx4 v[214:215], off
	s_add_i32 m0, s80, 0x2000
	s_add_u32 s80, s22, 0x80000
	v_lshl_add_u64 v[216:217], s[22:23], 0, v[160:161]
	s_addc_u32 s81, s23, 0
	s_add_i32 s82, s82, s47
	global_load_lds_dwordx4 v[216:217], off
	v_lshl_add_u64 v[210:211], s[80:81], 0, v[208:209]
	s_mov_b32 m0, s82
	v_lshl_add_u64 v[218:219], s[26:27], 0, v[164:165]
	global_load_lds_dwordx4 v[210:211], off
	v_lshl_add_u64 v[210:211], s[80:81], 0, v[160:161]
	s_add_i32 m0, s82, 0x2000
	v_lshl_add_u64 v[220:221], s[26:27], 0, v[162:163]
	global_load_lds_dwordx4 v[210:211], off
	s_mov_b32 m0, s51
	s_nop 0
	global_load_lds_dwordx4 v[218:219], off
	s_mov_b32 m0, s54
	s_nop 0
	global_load_lds_dwordx4 v[220:221], off
	s_waitcnt vmcnt(8) lgkmcnt(0)
	s_setprio 1
	s_barrier
; #define PG8_STAGE(bufoff, gbase, voff) do { _Pragma("unroll") for (int _i = 0; _i < 2; ++_i) \
;         __builtin_amdgcn_global_load_lds((const unsigned*)((const char*)(gbase) + (voff)[_i]), (LAS unsigned*)(lds + (bufoff) + ldsw + _i * 8192), 16, 0, 0); } while (0)
; #define PG8_LDA(dst, b, h) do { _Pragma("unroll") for (int m = 0; m < 4; ++m) _Pragma("unroll") for (int k = 0; k < 2; ++k) dst[m][k] = *(const LAS bf16x8*)(lds + PG8_SA(b, h) + aoff + m * 2048 + k * 1024); } while (0)
; #define PG8_LDB(dst, b, h) do { _Pragma("unroll") for (int n = 0; n < 2; ++n) _Pragma("unroll") for (int k = 0; k < 2; ++k) dst[n][k] = *(const LAS bf16x8*)(lds + PG8_SB(b, h) + boff + n * 2048 + k * 1024); } while (0)
; #define PG8_MMA(ai, bj, At, Bt) do { __builtin_amdgcn_s_setprio(1); _Pragma("unroll") for (int m = 0; m < 4; ++m) _Pragma("unroll") for (int n = 0; n < 2; ++n) _Pragma("unroll") for (int k = 0; k < 2; ++k) \
;         acc[ai][bj][m][n] = __builtin_amdgcn_mfma_f32_16x16x32_bf16(Bt[n][k], At[m][k], acc[ai][bj][m][n], 0, 0, 0); __builtin_amdgcn_s_setprio(0); } while (0)
; #define PG8_WAIT_V(n) asm volatile("s_waitcnt vmcnt(" #n ")" ::: "memory")
; #define PG8_WAIT_L(n) asm volatile("s_waitcnt lgkmcnt(" #n ")" ::: "memory")
; #define PG8_BAR __builtin_amdgcn_s_barrier()
; #define PG8_SCHED __builtin_amdgcn_sched_barrier(0)
; template <class Epi, class Sched>
; DI void gemm_phase(LAS unsigned char* lds, const Sched& S, const Epi& E) {
;     ...
;       PG8_WAIT_V(8); PG8_WAIT_L(0); PG8_BAR; PG8_MMA(0, 0, At, B0); PG8_MMA(0, 1, At, B1); PG8_BAR; PG8_SCHED;
;       PG8_LDA(At, 0, 1); PG8_STAGE(PG8_SB(0, 0), b2, voffB); PG8_STAGE(PG8_SB(0, 1), b2 + hstep, voffB); PG8_STAGE(PG8_SA(0, 0), a2, voffA);
;       PG8_WAIT_V(8); PG8_WAIT_L(0); PG8_BAR; PG8_MMA(1, 0, At, B0); PG8_MMA(1, 1, At, B1); PG8_BAR; PG8_SCHED;
;       PG8_LDB(B0, 1, 0); PG8_LDB(B1, 1, 1); PG8_SCHED; PG8_LDA(At, 1, 0); PG8_STAGE(PG8_SA(0, 1), a2 + hstep, voffA);
;       PG8_WAIT_V(8); PG8_WAIT_L(0); PG8_BAR; PG8_MMA(0, 0, At, B0); PG8_MMA(0, 1, At, B1); PG8_BAR; PG8_SCHED;
	v_mfma_f32_16x16x32_bf16 v[92:95], v[24:27], v[174:177], v[92:95]
	v_mfma_f32_16x16x32_bf16 v[88:91], v[40:43], v[174:177], v[88:91]
	v_mfma_f32_16x16x32_bf16 v[84:87], v[24:27], v[182:185], v[84:87]
	v_mfma_f32_16x16x32_bf16 v[76:79], v[40:43], v[182:185], v[76:79]
	v_mfma_f32_16x16x32_bf16 v[48:51], v[24:27], v[190:193], v[48:51]
	v_mfma_f32_16x16x32_bf16 v[28:31], v[40:43], v[190:193], v[28:31]
	v_mfma_f32_16x16x32_bf16 v[16:19], v[24:27], v[200:203], v[16:19]
	v_mfma_f32_16x16x32_bf16 v[8:11], v[40:43], v[200:203], v[8:11]
	v_mfma_f32_16x16x32_bf16 v[92:95], v[36:39], v[178:181], v[92:95]
	v_mfma_f32_16x16x32_bf16 v[88:91], v[44:47], v[178:181], v[88:91]
	v_mfma_f32_16x16x32_bf16 v[84:87], v[36:39], v[186:189], v[84:87]
	v_mfma_f32_16x16x32_bf16 v[76:79], v[44:47], v[186:189], v[76:79]
	v_mfma_f32_16x16x32_bf16 v[48:51], v[36:39], v[196:199], v[48:51]
	v_mfma_f32_16x16x32_bf16 v[28:31], v[44:47], v[196:199], v[28:31]
	v_mfma_f32_16x16x32_bf16 v[16:19], v[36:39], v[204:207], v[16:19]
	v_mfma_f32_16x16x32_bf16 v[8:11], v[44:47], v[204:207], v[8:11]
	v_mfma_f32_16x16x32_bf16 v[32:35], v[52:55], v[182:185], v[32:35]
	v_mfma_f32_16x16x32_bf16 v[12:15], v[52:55], v[190:193], v[12:15]
	v_mfma_f32_16x16x32_bf16 v[20:23], v[64:67], v[190:193], v[20:23]
	v_mfma_f32_16x16x32_bf16 v[0:3], v[52:55], v[200:203], v[0:3]
	v_mfma_f32_16x16x32_bf16 v[4:7], v[64:67], v[200:203], v[4:7]
	v_mfma_f32_16x16x32_bf16 v[24:27], v[52:55], v[174:177], v[80:83]
	v_mfma_f32_16x16x32_bf16 v[36:39], v[64:67], v[174:177], v[72:75]
	v_mfma_f32_16x16x32_bf16 v[32:35], v[60:63], v[186:189], v[32:35]
	v_mfma_f32_16x16x32_bf16 v[40:43], v[64:67], v[182:185], v[56:59]
	v_mfma_f32_16x16x32_bf16 v[12:15], v[60:63], v[196:199], v[12:15]
	v_mfma_f32_16x16x32_bf16 v[20:23], v[68:71], v[196:199], v[20:23]
	v_mfma_f32_16x16x32_bf16 v[0:3], v[60:63], v[204:207], v[0:3]
	v_mfma_f32_16x16x32_bf16 v[4:7], v[68:71], v[204:207], v[4:7]
	v_mfma_f32_16x16x32_bf16 v[24:27], v[60:63], v[178:181], v[24:27]
	v_mfma_f32_16x16x32_bf16 v[36:39], v[68:71], v[178:181], v[36:39]
	v_mfma_f32_16x16x32_bf16 v[40:43], v[68:71], v[186:189], v[40:43]
	s_barrier
	s_setprio 0
	s_add_i32 s80, 0, 0x18000
	s_add_i32 s81, 0, 0x1c000
	v_add_u32_e32 v60, s80, v167
	v_add_u32_e32 v72, s81, v167
	ds_read_b128 v[44:47], v60
	ds_read_b128 v[52:55], v60 offset:1024
	ds_read_b128 v[56:59], v60 offset:2048
	ds_read_b128 v[60:63], v60 offset:3072
	ds_read_b128 v[64:67], v72
	ds_read_b128 v[68:71], v72 offset:1024
	ds_read_b128 v[174:177], v72 offset:2048
	ds_read_b128 v[178:181], v72 offset:3072
	s_add_u32 s26, s26, 0x80000
	s_addc_u32 s27, s27, 0
	s_mov_b32 m0, s55
	v_lshl_add_u64 v[210:211], s[26:27], 0, v[164:165]
	ds_read_b128 v[72:75], v195 offset:32768
	ds_read_b128 v[80:83], v195 offset:33792
	ds_read_b128 v[182:185], v195 offset:34816
	ds_read_b128 v[186:189], v195 offset:35840
	ds_read_b128 v[190:193], v195 offset:36864
	ds_read_b128 v[196:199], v195 offset:37888
	ds_read_b128 v[200:203], v195 offset:38912
	ds_read_b128 v[204:207], v195 offset:39936
	global_load_lds_dwordx4 v[210:211], off
	v_lshl_add_u64 v[210:211], s[26:27], 0, v[162:163]
	s_mov_b32 m0, s72
	s_nop 0
	global_load_lds_dwordx4 v[210:211], off
	s_waitcnt vmcnt(8) lgkmcnt(0)
	s_setprio 1
	s_barrier
	v_mfma_f32_16x16x32_bf16 v[156:159], v[44:47], v[72:75], v[156:159]
	v_mfma_f32_16x16x32_bf16 v[152:155], v[56:59], v[72:75], v[152:155]
	v_mfma_f32_16x16x32_bf16 v[148:151], v[44:47], v[182:185], v[148:151]
	v_mfma_f32_16x16x32_bf16 v[140:143], v[56:59], v[182:185], v[140:143]
	v_mfma_f32_16x16x32_bf16 v[128:131], v[44:47], v[190:193], v[128:131]
	v_mfma_f32_16x16x32_bf16 v[120:123], v[56:59], v[190:193], v[120:123]
	v_mfma_f32_16x16x32_bf16 v[112:115], v[44:47], v[200:203], v[112:115]
	v_mfma_f32_16x16x32_bf16 v[104:107], v[56:59], v[200:203], v[104:107]
	v_mfma_f32_16x16x32_bf16 v[156:159], v[52:55], v[80:83], v[156:159]
	v_mfma_f32_16x16x32_bf16 v[152:155], v[60:63], v[80:83], v[152:155]
	v_mfma_f32_16x16x32_bf16 v[148:151], v[52:55], v[186:189], v[148:151]
	v_mfma_f32_16x16x32_bf16 v[140:143], v[60:63], v[186:189], v[140:143]
	v_mfma_f32_16x16x32_bf16 v[128:131], v[52:55], v[196:199], v[128:131]
	v_mfma_f32_16x16x32_bf16 v[120:123], v[60:63], v[196:199], v[120:123]
	v_mfma_f32_16x16x32_bf16 v[112:115], v[52:55], v[204:207], v[112:115]
	v_mfma_f32_16x16x32_bf16 v[104:107], v[60:63], v[204:207], v[104:107]
	v_mfma_f32_16x16x32_bf16 v[144:147], v[64:67], v[72:75], v[144:147]
	v_mfma_f32_16x16x32_bf16 v[72:75], v[174:177], v[72:75], v[136:139]
	v_mfma_f32_16x16x32_bf16 v[136:139], v[178:181], v[80:83], v[72:75]
	v_mfma_f32_16x16x32_bf16 v[72:75], v[64:67], v[182:185], v[124:127]
	v_mfma_f32_16x16x32_bf16 v[124:127], v[68:71], v[186:189], v[72:75]
	v_mfma_f32_16x16x32_bf16 v[72:75], v[174:177], v[182:185], v[132:135]
	v_mfma_f32_16x16x32_bf16 v[132:135], v[178:181], v[186:189], v[72:75]
	v_mfma_f32_16x16x32_bf16 v[72:75], v[64:67], v[190:193], v[108:111]
	v_mfma_f32_16x16x32_bf16 v[108:111], v[68:71], v[196:199], v[72:75]
	v_mfma_f32_16x16x32_bf16 v[72:75], v[174:177], v[190:193], v[116:119]
	v_mfma_f32_16x16x32_bf16 v[116:119], v[178:181], v[196:199], v[72:75]
	v_mfma_f32_16x16x32_bf16 v[72:75], v[64:67], v[200:203], v[96:99]
	v_mfma_f32_16x16x32_bf16 v[96:99], v[68:71], v[204:207], v[72:75]
	v_mfma_f32_16x16x32_bf16 v[72:75], v[174:177], v[200:203], v[100:103]
	v_mfma_f32_16x16x32_bf16 v[144:147], v[68:71], v[80:83], v[144:147]
	v_mfma_f32_16x16x32_bf16 v[100:103], v[178:181], v[204:207], v[72:75]
	s_barrier
; #define PG8_STAGE(bufoff, gbase, voff) do { _Pragma("unroll") for (int _i = 0; _i < 2; ++_i) \
;         __builtin_amdgcn_global_load_lds((const unsigned*)((const char*)(gbase) + (voff)[_i]), (LAS unsigned*)(lds + (bufoff) + ldsw + _i * 8192), 16, 0, 0); } while (0)
; #define PG8_LDA(dst, b, h) do { _Pragma("unroll") for (int m = 0; m < 4; ++m) _Pragma("unroll") for (int k = 0; k < 2; ++k) dst[m][k] = *(const LAS bf16x8*)(lds + PG8_SA(b, h) + aoff + m * 2048 + k * 1024); } while (0)
; #define PG8_LDB(dst, b, h) do { _Pragma("unroll") for (int n = 0; n < 2; ++n) _Pragma("unroll") for (int k = 0; k < 2; ++k) dst[n][k] = *(const LAS bf16x8*)(lds + PG8_SB(b, h) + boff + n * 2048 + k * 1024); } while (0)
; #define PG8_MMA(ai, bj, At, Bt) do { __builtin_amdgcn_s_setprio(1); _Pragma("unroll") for (int m = 0; m < 4; ++m) _Pragma("unroll") for (int n = 0; n < 2; ++n) _Pragma("unroll") for (int k = 0; k < 2; ++k) \
;         acc[ai][bj][m][n] = __builtin_amdgcn_mfma_f32_16x16x32_bf16(Bt[n][k], At[m][k], acc[ai][bj][m][n], 0, 0, 0); __builtin_amdgcn_s_setprio(0); } while (0)
; #define PG8_WAIT_V(n) asm volatile("s_waitcnt vmcnt(" #n ")" ::: "memory")
; #define PG8_WAIT_L(n) asm volatile("s_waitcnt lgkmcnt(" #n ")" ::: "memory")
; #define PG8_BAR __builtin_amdgcn_s_barrier()
; #define PG8_SCHED __builtin_amdgcn_sched_barrier(0)
; template <class Epi, class Sched>
; DI void gemm_phase(LAS unsigned char* lds, const Sched& S, const Epi& E) {
;     ...
;       PG8_LDB(B0, 1, 0); PG8_LDB(B1, 1, 1); PG8_SCHED; PG8_LDA(At, 1, 0); PG8_STAGE(PG8_SA(0, 1), a2 + hstep, voffA);
;       PG8_WAIT_V(8); PG8_WAIT_L(0); PG8_BAR; PG8_MMA(0, 0, At, B0); PG8_MMA(0, 1, At, B1); PG8_BAR; PG8_SCHED;
;       PG8_LDA(At, 1, 1); PG8_STAGE(PG8_SB(1, 0), b3, voffB); PG8_STAGE(PG8_SB(1, 1), b3 + hstep, voffB); PG8_STAGE(PG8_SA(1, 0), a3, voffA);
;       PG8_WAIT_V(8); PG8_WAIT_L(0); PG8_BAR; PG8_MMA(1, 0, At, B0); PG8_MMA(1, 1, At, B1); PG8_BAR; PG8_SCHED;
;     }
;     if (wr == 0) PG8_BAR;
;     if constexpr (Epi::CARRY) E.carry(acc, cur, wr, wc, fr, fq);
;     else if constexpr (!Epi::AFTER_DRAIN) E(acc, cur, wr, wc, fr, fq);
;     if (!has_next) break;
	s_setprio 0
	s_add_i32 s26, s80, s47
	v_lshl_add_u64 v[80:81], v[214:215], 0, s[6:7]
	s_mov_b32 m0, s26
	s_nop 0
	ds_read_b128 v[72:75], v195 offset:49152
	ds_read_b128 v[182:185], v195 offset:50176
	ds_read_b128 v[186:189], v195 offset:51200
	ds_read_b128 v[190:193], v195 offset:52224
	ds_read_b128 v[196:199], v195 offset:53248
	ds_read_b128 v[200:203], v195 offset:54272
	ds_read_b128 v[204:207], v195 offset:55296
	ds_read_b128 v[210:213], v195 offset:56320
	global_load_lds_dwordx4 v[80:81], off
	s_add_i32 m0, s26, 0x2000
	s_add_u32 s22, s22, 0x80080
	v_lshl_add_u64 v[80:81], v[216:217], 0, s[6:7]
	s_addc_u32 s23, s23, 0
	s_add_i32 s26, s81, s47
	global_load_lds_dwordx4 v[80:81], off
	v_lshl_add_u64 v[80:81], s[22:23], 0, v[208:209]
	s_mov_b32 m0, s26
	s_nop 0
	global_load_lds_dwordx4 v[80:81], off
	v_lshl_add_u64 v[80:81], s[22:23], 0, v[160:161]
	s_add_i32 m0, s26, 0x2000
	s_nop 0
	global_load_lds_dwordx4 v[80:81], off
	v_lshl_add_u64 v[80:81], v[218:219], 0, s[6:7]
	s_mov_b32 m0, s73
	s_nop 0
	global_load_lds_dwordx4 v[80:81], off
	v_lshl_add_u64 v[80:81], v[220:221], 0, s[6:7]
	s_mov_b32 m0, s74
	s_nop 0
	global_load_lds_dwordx4 v[80:81], off
	s_waitcnt vmcnt(8) lgkmcnt(0)
	s_setprio 1
	s_barrier
	v_mfma_f32_16x16x32_bf16 v[80:83], v[44:47], v[72:75], v[92:95]
	v_mfma_f32_16x16x32_bf16 v[92:95], v[52:55], v[182:185], v[80:83]
	v_mfma_f32_16x16x32_bf16 v[80:83], v[56:59], v[72:75], v[88:91]
	v_mfma_f32_16x16x32_bf16 v[88:91], v[60:63], v[182:185], v[80:83]
	v_mfma_f32_16x16x32_bf16 v[80:83], v[44:47], v[186:189], v[84:87]
	v_mfma_f32_16x16x32_bf16 v[76:79], v[56:59], v[186:189], v[76:79]
	v_mfma_f32_16x16x32_bf16 v[48:51], v[44:47], v[196:199], v[48:51]
	v_mfma_f32_16x16x32_bf16 v[28:31], v[56:59], v[196:199], v[28:31]
	v_mfma_f32_16x16x32_bf16 v[16:19], v[44:47], v[204:207], v[16:19]
	v_mfma_f32_16x16x32_bf16 v[8:11], v[56:59], v[204:207], v[8:11]
	v_mfma_f32_16x16x32_bf16 v[84:87], v[52:55], v[190:193], v[80:83]
	v_mfma_f32_16x16x32_bf16 v[76:79], v[60:63], v[190:193], v[76:79]
	v_mfma_f32_16x16x32_bf16 v[48:51], v[52:55], v[200:203], v[48:51]
	v_mfma_f32_16x16x32_bf16 v[28:31], v[60:63], v[200:203], v[28:31]
	v_mfma_f32_16x16x32_bf16 v[16:19], v[52:55], v[210:213], v[16:19]
	v_mfma_f32_16x16x32_bf16 v[8:11], v[60:63], v[210:213], v[8:11]
	v_mfma_f32_16x16x32_bf16 v[24:27], v[64:67], v[72:75], v[24:27]
	v_mfma_f32_16x16x32_bf16 v[80:83], v[68:71], v[182:185], v[24:27]
	v_mfma_f32_16x16x32_bf16 v[24:27], v[174:177], v[72:75], v[36:39]
	v_mfma_f32_16x16x32_bf16 v[72:75], v[178:181], v[182:185], v[24:27]
	v_mfma_f32_16x16x32_bf16 v[24:27], v[64:67], v[186:189], v[32:35]
	v_mfma_f32_16x16x32_bf16 v[32:35], v[68:71], v[190:193], v[24:27]
	v_mfma_f32_16x16x32_bf16 v[24:27], v[174:177], v[186:189], v[40:43]
	v_mfma_f32_16x16x32_bf16 v[12:15], v[64:67], v[196:199], v[12:15]
	v_mfma_f32_16x16x32_bf16 v[20:23], v[174:177], v[196:199], v[20:23]
	v_mfma_f32_16x16x32_bf16 v[0:3], v[64:67], v[204:207], v[0:3]
	v_mfma_f32_16x16x32_bf16 v[4:7], v[174:177], v[204:207], v[4:7]
	v_mfma_f32_16x16x32_bf16 v[56:59], v[178:181], v[190:193], v[24:27]
	v_mfma_f32_16x16x32_bf16 v[12:15], v[68:71], v[200:203], v[12:15]
	v_mfma_f32_16x16x32_bf16 v[20:23], v[178:181], v[200:203], v[20:23]
	v_mfma_f32_16x16x32_bf16 v[0:3], v[68:71], v[210:213], v[0:3]
	v_mfma_f32_16x16x32_bf16 v[4:7], v[178:181], v[210:213], v[4:7]
	s_barrier
	s_setprio 0
	s_add_i32 s79, s79, 2
	s_add_u32 vcc_lo, vcc_lo, 0x100
	s_addc_u32 vcc_hi, vcc_hi, 0
	s_add_u32 s77, s77, 0x100
	s_addc_u32 s78, s78, 0
	s_cmp_gt_u32 s79, 29
	s_cbranch_scc0 .LBB0_479
	s_and_b64 vcc, exec, s[60:61]
	s_cbranch_vccz .LBB0_482
	s_barrier

; #define PG8_STAGE(bufoff, gbase, voff) do { _Pragma("unroll") for (int _i = 0; _i < 2; ++_i) \
;         __builtin_amdgcn_global_load_lds((const unsigned*)((const char*)(gbase) + (voff)[_i]), (LAS unsigned*)(lds + (bufoff) + ldsw + _i * 8192), 16, 0, 0); } while (0)
; #define PG8_LDA(dst, b, h) do { _Pragma("unroll") for (int m = 0; m < 4; ++m) _Pragma("unroll") for (int k = 0; k < 2; ++k) dst[m][k] = *(const LAS bf16x8*)(lds + PG8_SA(b, h) + aoff + m * 2048 + k * 1024); } while (0)
; #define PG8_LDB(dst, b, h) do { _Pragma("unroll") for (int n = 0; n < 2; ++n) _Pragma("unroll") for (int k = 0; k < 2; ++k) dst[n][k] = *(const LAS bf16x8*)(lds + PG8_SB(b, h) + boff + n * 2048 + k * 1024); } while (0)
; #define PG8_MMA(ai, bj, At, Bt) do { __builtin_amdgcn_s_setprio(1); _Pragma("unroll") for (int m = 0; m < 4; ++m) _Pragma("unroll") for (int n = 0; n < 2; ++n) _Pragma("unroll") for (int k = 0; k < 2; ++k) \
;         acc[ai][bj][m][n] = __builtin_amdgcn_mfma_f32_16x16x32_bf16(Bt[n][k], At[m][k], acc[ai][bj][m][n], 0, 0, 0); __builtin_amdgcn_s_setprio(0); } while (0)
; #define PG8_WAIT_V(n) asm volatile("s_waitcnt vmcnt(" #n ")" ::: "memory")
; #define PG8_WAIT_L(n) asm volatile("s_waitcnt lgkmcnt(" #n ")" ::: "memory")
; #define PG8_BAR __builtin_amdgcn_s_barrier()
; #define PG8_SCHED __builtin_amdgcn_sched_barrier(0)
; template <class Epi, class Sched>
; DI void gemm_phase(LAS unsigned char* lds, const Sched& S, const Epi& E) {
;     ...
;     for (int t = 0; t < nt; t += 2) {
;       const bool last = (t == nt - 2);
;       const char* a1 = cA + (size_t)(t + 1) * kstep;
;       const char* a2 = last ? nA : cA + (size_t)(t + 2) * kstep; const char* b2 = last ? nB : cB + (size_t)(t + 2) * kstep;
;       const char* a3 = a2 + kstep; const char* b3 = b2 + kstep;
;       PG8_LDB(B0, 0, 0); PG8_LDB(B1, 0, 1); PG8_SCHED; PG8_LDA(At, 0, 0); PG8_STAGE(PG8_SA(1, 1), a1 + hstep, voffA);
;       PG8_WAIT_V(8); PG8_WAIT_L(0); PG8_BAR; PG8_MMA(0, 0, At, B0); PG8_MMA(0, 1, At, B1); PG8_BAR; PG8_SCHED;
;       PG8_LDA(At, 0, 1); PG8_STAGE(PG8_SB(0, 0), b2, voffB); PG8_STAGE(PG8_SB(0, 1), b2 + hstep, voffB); PG8_STAGE(PG8_SA(0, 0), a2, voffA);
;       PG8_WAIT_V(8); PG8_WAIT_L(0); PG8_BAR; PG8_MMA(1, 0, At, B0); PG8_MMA(1, 1, At, B1); PG8_BAR; PG8_SCHED;
.LBB0_538:
	s_add_u32 s26, s62, s22
	s_addc_u32 s27, s63, s23
	s_add_u32 s26, s26, 0x100
	s_addc_u32 s27, s27, 0
	s_add_u32 s78, s73, s22
	s_addc_u32 s79, s74, s23
	s_add_i32 s80, 0, 0x10000
	s_cmpk_eq_i32 s22, 0xf00
	s_cselect_b32 s45, s57, s27
	s_cselect_b32 s44, s75, s26
	s_cselect_b32 s27, s53, s79
	s_cselect_b32 s26, s76, s78
	s_add_i32 s81, 0, 0x14000
	v_add_u32_e32 v150, s80, v136
	v_add_u32_e32 v166, s81, v136
	ds_read_b128 v[138:141], v150
	ds_read_b128 v[142:145], v150 offset:1024
	ds_read_b128 v[146:149], v150 offset:2048
	ds_read_b128 v[150:153], v150 offset:3072
	ds_read_b128 v[154:157], v166
	ds_read_b128 v[158:161], v166 offset:1024
	ds_read_b128 v[162:165], v166 offset:2048
	ds_read_b128 v[166:169], v166 offset:3072
	v_lshl_add_u64 v[202:203], v[132:133], 0, s[22:23]
	s_add_i32 m0, s43, 0xc000
	ds_read_b128 v[170:173], v137
	ds_read_b128 v[174:177], v137 offset:1024
	ds_read_b128 v[178:181], v137 offset:2048
	ds_read_b128 v[182:185], v137 offset:3072
	ds_read_b128 v[186:189], v137 offset:4096
	ds_read_b128 v[190:193], v137 offset:5120
	ds_read_b128 v[194:197], v137 offset:6144
	ds_read_b128 v[198:201], v137 offset:7168
	global_load_lds_dwordx4 v[202:203], off
	v_lshl_add_u64 v[202:203], v[134:135], 0, s[22:23]
	s_add_i32 m0, s43, 0xe000
	s_nop 0
	global_load_lds_dwordx4 v[202:203], off
	s_waitcnt vmcnt(8) lgkmcnt(0)
	s_setprio 1
	s_barrier
	v_mfma_f32_16x16x32_bf16 v[124:127], v[138:141], v[170:173], v[124:127]
	v_mfma_f32_16x16x32_bf16 v[120:123], v[146:149], v[170:173], v[120:123]
	v_mfma_f32_16x16x32_bf16 v[108:111], v[138:141], v[178:181], v[108:111]
	v_mfma_f32_16x16x32_bf16 v[104:107], v[146:149], v[178:181], v[104:107]
	v_mfma_f32_16x16x32_bf16 v[92:95], v[138:141], v[186:189], v[92:95]
	v_mfma_f32_16x16x32_bf16 v[88:91], v[146:149], v[186:189], v[88:91]
	v_mfma_f32_16x16x32_bf16 v[76:79], v[138:141], v[194:197], v[76:79]
	v_mfma_f32_16x16x32_bf16 v[72:75], v[146:149], v[194:197], v[72:75]
	v_mfma_f32_16x16x32_bf16 v[124:127], v[142:145], v[174:177], v[124:127]
	v_mfma_f32_16x16x32_bf16 v[120:123], v[150:153], v[174:177], v[120:123]
	v_mfma_f32_16x16x32_bf16 v[108:111], v[142:145], v[182:185], v[108:111]
	v_mfma_f32_16x16x32_bf16 v[104:107], v[150:153], v[182:185], v[104:107]
	v_mfma_f32_16x16x32_bf16 v[92:95], v[142:145], v[190:193], v[92:95]
	v_mfma_f32_16x16x32_bf16 v[88:91], v[150:153], v[190:193], v[88:91]
	v_mfma_f32_16x16x32_bf16 v[76:79], v[142:145], v[198:201], v[76:79]
	v_mfma_f32_16x16x32_bf16 v[72:75], v[150:153], v[198:201], v[72:75]
	v_mfma_f32_16x16x32_bf16 v[116:119], v[154:157], v[170:173], v[116:119]
	v_mfma_f32_16x16x32_bf16 v[112:115], v[162:165], v[170:173], v[112:115]
	v_mfma_f32_16x16x32_bf16 v[100:103], v[154:157], v[178:181], v[100:103]
	v_mfma_f32_16x16x32_bf16 v[96:99], v[162:165], v[178:181], v[96:99]
	v_mfma_f32_16x16x32_bf16 v[84:87], v[154:157], v[186:189], v[84:87]
	v_mfma_f32_16x16x32_bf16 v[80:83], v[162:165], v[186:189], v[80:83]
	v_mfma_f32_16x16x32_bf16 v[68:71], v[154:157], v[194:197], v[68:71]
	v_mfma_f32_16x16x32_bf16 v[64:67], v[162:165], v[194:197], v[64:67]
	v_mfma_f32_16x16x32_bf16 v[116:119], v[158:161], v[174:177], v[116:119]
	v_mfma_f32_16x16x32_bf16 v[112:115], v[166:169], v[174:177], v[112:115]
	v_mfma_f32_16x16x32_bf16 v[100:103], v[158:161], v[182:185], v[100:103]
	v_mfma_f32_16x16x32_bf16 v[96:99], v[166:169], v[182:185], v[96:99]
	v_mfma_f32_16x16x32_bf16 v[84:87], v[158:161], v[190:193], v[84:87]
	v_mfma_f32_16x16x32_bf16 v[80:83], v[166:169], v[190:193], v[80:83]
	v_mfma_f32_16x16x32_bf16 v[68:71], v[158:161], v[198:201], v[68:71]
	v_mfma_f32_16x16x32_bf16 v[64:67], v[166:169], v[198:201], v[64:67]
	s_barrier
	s_setprio 0
	s_add_i32 s78, s80, s11
	v_lshl_add_u64 v[202:203], s[26:27], 0, v[208:209]
	s_mov_b32 m0, s78
	ds_read_b128 v[170:173], v137 offset:16384
	ds_read_b128 v[174:177], v137 offset:17408
	ds_read_b128 v[178:181], v137 offset:18432
	ds_read_b128 v[182:185], v137 offset:19456
	ds_read_b128 v[186:189], v137 offset:20480
	ds_read_b128 v[190:193], v137 offset:21504
	ds_read_b128 v[194:197], v137 offset:22528
	ds_read_b128 v[198:201], v137 offset:23552
	global_load_lds_dwordx4 v[202:203], off
	s_add_i32 m0, s78, 0x2000
	s_add_u32 s78, s26, 0x80000
	v_lshl_add_u64 v[204:205], s[26:27], 0, v[218:219]
	s_addc_u32 s79, s27, 0
	s_add_i32 s80, s81, s11
	global_load_lds_dwordx4 v[204:205], off
	v_lshl_add_u64 v[206:207], s[78:79], 0, v[208:209]
	s_mov_b32 m0, s80
	v_lshl_add_u64 v[210:211], s[44:45], 0, v[216:217]
	global_load_lds_dwordx4 v[206:207], off
	v_lshl_add_u64 v[206:207], s[78:79], 0, v[218:219]
	s_add_i32 m0, s80, 0x2000
	s_nop 0
	global_load_lds_dwordx4 v[206:207], off
	v_lshl_add_u64 v[206:207], s[44:45], 0, v[214:215]
	s_mov_b32 m0, s43
	s_nop 0
	global_load_lds_dwordx4 v[206:207], off
	s_mov_b32 m0, s51
	s_nop 0
	global_load_lds_dwordx4 v[210:211], off
	s_waitcnt vmcnt(8) lgkmcnt(0)
	s_setprio 1
	s_barrier
; #define PG8_STAGE(bufoff, gbase, voff) do { _Pragma("unroll") for (int _i = 0; _i < 2; ++_i) \
;         __builtin_amdgcn_global_load_lds((const unsigned*)((const char*)(gbase) + (voff)[_i]), (LAS unsigned*)(lds + (bufoff) + ldsw + _i * 8192), 16, 0, 0); } while (0)
; #define PG8_LDA(dst, b, h) do { _Pragma("unroll") for (int m = 0; m < 4; ++m) _Pragma("unroll") for (int k = 0; k < 2; ++k) dst[m][k] = *(const LAS bf16x8*)(lds + PG8_SA(b, h) + aoff + m * 2048 + k * 1024); } while (0)
; #define PG8_LDB(dst, b, h) do { _Pragma("unroll") for (int n = 0; n < 2; ++n) _Pragma("unroll") for (int k = 0; k < 2; ++k) dst[n][k] = *(const LAS bf16x8*)(lds + PG8_SB(b, h) + boff + n * 2048 + k * 1024); } while (0)
; #define PG8_MMA(ai, bj, At, Bt) do { __builtin_amdgcn_s_setprio(1); _Pragma("unroll") for (int m = 0; m < 4; ++m) _Pragma("unroll") for (int n = 0; n < 2; ++n) _Pragma("unroll") for (int k = 0; k < 2; ++k) \
;         acc[ai][bj][m][n] = __builtin_amdgcn_mfma_f32_16x16x32_bf16(Bt[n][k], At[m][k], acc[ai][bj][m][n], 0, 0, 0); __builtin_amdgcn_s_setprio(0); } while (0)
; #define PG8_WAIT_V(n) asm volatile("s_waitcnt vmcnt(" #n ")" ::: "memory")
; #define PG8_WAIT_L(n) asm volatile("s_waitcnt lgkmcnt(" #n ")" ::: "memory")
; #define PG8_BAR __builtin_amdgcn_s_barrier()
; #define PG8_SCHED __builtin_amdgcn_sched_barrier(0)
; template <class Epi, class Sched>
; DI void gemm_phase(LAS unsigned char* lds, const Sched& S, const Epi& E) {
;     ...
;       PG8_WAIT_V(8); PG8_WAIT_L(0); PG8_BAR; PG8_MMA(0, 0, At, B0); PG8_MMA(0, 1, At, B1); PG8_BAR; PG8_SCHED;
;       PG8_LDA(At, 0, 1); PG8_STAGE(PG8_SB(0, 0), b2, voffB); PG8_STAGE(PG8_SB(0, 1), b2 + hstep, voffB); PG8_STAGE(PG8_SA(0, 0), a2, voffA);
;       PG8_WAIT_V(8); PG8_WAIT_L(0); PG8_BAR; PG8_MMA(1, 0, At, B0); PG8_MMA(1, 1, At, B1); PG8_BAR; PG8_SCHED;
;       PG8_LDB(B0, 1, 0); PG8_LDB(B1, 1, 1); PG8_SCHED; PG8_LDA(At, 1, 0); PG8_STAGE(PG8_SA(0, 1), a2 + hstep, voffA);
;       PG8_WAIT_V(8); PG8_WAIT_L(0); PG8_BAR; PG8_MMA(0, 0, At, B0); PG8_MMA(0, 1, At, B1); PG8_BAR; PG8_SCHED;
	v_mfma_f32_16x16x32_bf16 v[60:63], v[138:141], v[170:173], v[60:63]
	v_mfma_f32_16x16x32_bf16 v[56:59], v[146:149], v[170:173], v[56:59]
	v_mfma_f32_16x16x32_bf16 v[44:47], v[138:141], v[178:181], v[44:47]
	v_mfma_f32_16x16x32_bf16 v[40:43], v[146:149], v[178:181], v[40:43]
	v_mfma_f32_16x16x32_bf16 v[28:31], v[138:141], v[186:189], v[28:31]
	v_mfma_f32_16x16x32_bf16 v[24:27], v[146:149], v[186:189], v[24:27]
	v_mfma_f32_16x16x32_bf16 v[12:15], v[138:141], v[194:197], v[12:15]
	v_mfma_f32_16x16x32_bf16 v[8:11], v[146:149], v[194:197], v[8:11]
	v_mfma_f32_16x16x32_bf16 v[60:63], v[142:145], v[174:177], v[60:63]
	v_mfma_f32_16x16x32_bf16 v[56:59], v[150:153], v[174:177], v[56:59]
	v_mfma_f32_16x16x32_bf16 v[44:47], v[142:145], v[182:185], v[44:47]
	v_mfma_f32_16x16x32_bf16 v[40:43], v[150:153], v[182:185], v[40:43]
	v_mfma_f32_16x16x32_bf16 v[28:31], v[142:145], v[190:193], v[28:31]
	v_mfma_f32_16x16x32_bf16 v[24:27], v[150:153], v[190:193], v[24:27]
	v_mfma_f32_16x16x32_bf16 v[12:15], v[142:145], v[198:201], v[12:15]
	v_mfma_f32_16x16x32_bf16 v[8:11], v[150:153], v[198:201], v[8:11]
	v_mfma_f32_16x16x32_bf16 v[52:55], v[154:157], v[170:173], v[52:55]
	v_mfma_f32_16x16x32_bf16 v[48:51], v[162:165], v[170:173], v[48:51]
	v_mfma_f32_16x16x32_bf16 v[36:39], v[154:157], v[178:181], v[36:39]
	v_mfma_f32_16x16x32_bf16 v[32:35], v[162:165], v[178:181], v[32:35]
	v_mfma_f32_16x16x32_bf16 v[20:23], v[154:157], v[186:189], v[20:23]
	v_mfma_f32_16x16x32_bf16 v[16:19], v[162:165], v[186:189], v[16:19]
	v_mfma_f32_16x16x32_bf16 v[4:7], v[154:157], v[194:197], v[4:7]
	v_mfma_f32_16x16x32_bf16 v[0:3], v[162:165], v[194:197], v[0:3]
	v_mfma_f32_16x16x32_bf16 v[52:55], v[158:161], v[174:177], v[52:55]
	v_mfma_f32_16x16x32_bf16 v[48:51], v[166:169], v[174:177], v[48:51]
	v_mfma_f32_16x16x32_bf16 v[36:39], v[158:161], v[182:185], v[36:39]
	v_mfma_f32_16x16x32_bf16 v[32:35], v[166:169], v[182:185], v[32:35]
	v_mfma_f32_16x16x32_bf16 v[20:23], v[158:161], v[190:193], v[20:23]
	v_mfma_f32_16x16x32_bf16 v[16:19], v[166:169], v[190:193], v[16:19]
	v_mfma_f32_16x16x32_bf16 v[4:7], v[158:161], v[198:201], v[4:7]
	v_mfma_f32_16x16x32_bf16 v[0:3], v[166:169], v[198:201], v[0:3]
	s_barrier
	s_setprio 0
	s_add_i32 s78, 0, 0x18000
	s_add_i32 s79, 0, 0x1c000
	v_add_u32_e32 v150, s78, v136
	v_add_u32_e32 v166, s79, v136
	ds_read_b128 v[138:141], v150
	ds_read_b128 v[142:145], v150 offset:1024
	ds_read_b128 v[146:149], v150 offset:2048
	ds_read_b128 v[150:153], v150 offset:3072
	ds_read_b128 v[154:157], v166
	ds_read_b128 v[158:161], v166 offset:1024
	ds_read_b128 v[162:165], v166 offset:2048
	ds_read_b128 v[166:169], v166 offset:3072
	s_add_u32 s44, s44, 0x80000
	s_addc_u32 s45, s45, 0
	s_mov_b32 m0, s54
	v_lshl_add_u64 v[212:213], s[44:45], 0, v[214:215]
	ds_read_b128 v[170:173], v137 offset:32768
	ds_read_b128 v[174:177], v137 offset:33792
	ds_read_b128 v[178:181], v137 offset:34816
	ds_read_b128 v[182:185], v137 offset:35840
	ds_read_b128 v[186:189], v137 offset:36864
	ds_read_b128 v[190:193], v137 offset:37888
	ds_read_b128 v[194:197], v137 offset:38912
	ds_read_b128 v[198:201], v137 offset:39936
	global_load_lds_dwordx4 v[212:213], off
	v_lshl_add_u64 v[212:213], s[44:45], 0, v[216:217]
	s_mov_b32 m0, s55
	s_nop 0
	global_load_lds_dwordx4 v[212:213], off
	s_waitcnt vmcnt(8) lgkmcnt(0)
	s_setprio 1
	s_barrier
	v_mfma_f32_16x16x32_bf16 v[124:127], v[138:141], v[170:173], v[124:127]
	v_mfma_f32_16x16x32_bf16 v[120:123], v[146:149], v[170:173], v[120:123]
	v_mfma_f32_16x16x32_bf16 v[108:111], v[138:141], v[178:181], v[108:111]
	v_mfma_f32_16x16x32_bf16 v[104:107], v[146:149], v[178:181], v[104:107]
	v_mfma_f32_16x16x32_bf16 v[92:95], v[138:141], v[186:189], v[92:95]
	v_mfma_f32_16x16x32_bf16 v[88:91], v[146:149], v[186:189], v[88:91]
	v_mfma_f32_16x16x32_bf16 v[76:79], v[138:141], v[194:197], v[76:79]
	v_mfma_f32_16x16x32_bf16 v[72:75], v[146:149], v[194:197], v[72:75]
	v_mfma_f32_16x16x32_bf16 v[124:127], v[142:145], v[174:177], v[124:127]
	v_mfma_f32_16x16x32_bf16 v[120:123], v[150:153], v[174:177], v[120:123]
	v_mfma_f32_16x16x32_bf16 v[108:111], v[142:145], v[182:185], v[108:111]
	v_mfma_f32_16x16x32_bf16 v[104:107], v[150:153], v[182:185], v[104:107]
	v_mfma_f32_16x16x32_bf16 v[92:95], v[142:145], v[190:193], v[92:95]
	v_mfma_f32_16x16x32_bf16 v[88:91], v[150:153], v[190:193], v[88:91]
	v_mfma_f32_16x16x32_bf16 v[76:79], v[142:145], v[198:201], v[76:79]
	v_mfma_f32_16x16x32_bf16 v[72:75], v[150:153], v[198:201], v[72:75]
	v_mfma_f32_16x16x32_bf16 v[116:119], v[154:157], v[170:173], v[116:119]
	v_mfma_f32_16x16x32_bf16 v[112:115], v[162:165], v[170:173], v[112:115]
	v_mfma_f32_16x16x32_bf16 v[100:103], v[154:157], v[178:181], v[100:103]
	v_mfma_f32_16x16x32_bf16 v[96:99], v[162:165], v[178:181], v[96:99]
	v_mfma_f32_16x16x32_bf16 v[84:87], v[154:157], v[186:189], v[84:87]
	v_mfma_f32_16x16x32_bf16 v[80:83], v[162:165], v[186:189], v[80:83]
	v_mfma_f32_16x16x32_bf16 v[68:71], v[154:157], v[194:197], v[68:71]
	v_mfma_f32_16x16x32_bf16 v[64:67], v[162:165], v[194:197], v[64:67]
	v_mfma_f32_16x16x32_bf16 v[116:119], v[158:161], v[174:177], v[116:119]
	v_mfma_f32_16x16x32_bf16 v[112:115], v[166:169], v[174:177], v[112:115]
	v_mfma_f32_16x16x32_bf16 v[100:103], v[158:161], v[182:185], v[100:103]
	v_mfma_f32_16x16x32_bf16 v[96:99], v[166:169], v[182:185], v[96:99]
	v_mfma_f32_16x16x32_bf16 v[84:87], v[158:161], v[190:193], v[84:87]
	v_mfma_f32_16x16x32_bf16 v[80:83], v[166:169], v[190:193], v[80:83]
	v_mfma_f32_16x16x32_bf16 v[68:71], v[158:161], v[198:201], v[68:71]
	v_mfma_f32_16x16x32_bf16 v[64:67], v[166:169], v[198:201], v[64:67]
	s_barrier
; #define PG8_STAGE(bufoff, gbase, voff) do { _Pragma("unroll") for (int _i = 0; _i < 2; ++_i) \
;         __builtin_amdgcn_global_load_lds((const unsigned*)((const char*)(gbase) + (voff)[_i]), (LAS unsigned*)(lds + (bufoff) + ldsw + _i * 8192), 16, 0, 0); } while (0)
; #define PG8_LDA(dst, b, h) do { _Pragma("unroll") for (int m = 0; m < 4; ++m) _Pragma("unroll") for (int k = 0; k < 2; ++k) dst[m][k] = *(const LAS bf16x8*)(lds + PG8_SA(b, h) + aoff + m * 2048 + k * 1024); } while (0)
; #define PG8_LDB(dst, b, h) do { _Pragma("unroll") for (int n = 0; n < 2; ++n) _Pragma("unroll") for (int k = 0; k < 2; ++k) dst[n][k] = *(const LAS bf16x8*)(lds + PG8_SB(b, h) + boff + n * 2048 + k * 1024); } while (0)
; #define PG8_MMA(ai, bj, At, Bt) do { __builtin_amdgcn_s_setprio(1); _Pragma("unroll") for (int m = 0; m < 4; ++m) _Pragma("unroll") for (int n = 0; n < 2; ++n) _Pragma("unroll") for (int k = 0; k < 2; ++k) \
;         acc[ai][bj][m][n] = __builtin_amdgcn_mfma_f32_16x16x32_bf16(Bt[n][k], At[m][k], acc[ai][bj][m][n], 0, 0, 0); __builtin_amdgcn_s_setprio(0); } while (0)
; #define PG8_WAIT_V(n) asm volatile("s_waitcnt vmcnt(" #n ")" ::: "memory")
; #define PG8_WAIT_L(n) asm volatile("s_waitcnt lgkmcnt(" #n ")" ::: "memory")
; #define PG8_BAR __builtin_amdgcn_s_barrier()
; #define PG8_SCHED __builtin_amdgcn_sched_barrier(0)
; template <class Epi, class Sched>
; DI void gemm_phase(LAS unsigned char* lds, const Sched& S, const Epi& E) {
;     ...
;       PG8_LDB(B0, 1, 0); PG8_LDB(B1, 1, 1); PG8_SCHED; PG8_LDA(At, 1, 0); PG8_STAGE(PG8_SA(0, 1), a2 + hstep, voffA);
;       PG8_WAIT_V(8); PG8_WAIT_L(0); PG8_BAR; PG8_MMA(0, 0, At, B0); PG8_MMA(0, 1, At, B1); PG8_BAR; PG8_SCHED;
;       PG8_LDA(At, 1, 1); PG8_STAGE(PG8_SB(1, 0), b3, voffB); PG8_STAGE(PG8_SB(1, 1), b3 + hstep, voffB); PG8_STAGE(PG8_SA(1, 0), a3, voffA);
;       PG8_WAIT_V(8); PG8_WAIT_L(0); PG8_BAR; PG8_MMA(1, 0, At, B0); PG8_MMA(1, 1, At, B1); PG8_BAR; PG8_SCHED;
;     }
;     if (wr == 0) PG8_BAR;
;     if constexpr (Epi::CARRY) E.carry(acc, cur, wr, wc, fr, fq);
;     else if constexpr (!Epi::AFTER_DRAIN) E(acc, cur, wr, wc, fr, fq);
;     if (!has_next) break;
	s_setprio 0
	s_add_i32 s44, s78, s11
	v_lshl_add_u64 v[202:203], v[202:203], 0, s[6:7]
	s_mov_b32 m0, s44
	ds_read_b128 v[170:173], v137 offset:49152
	ds_read_b128 v[174:177], v137 offset:50176
	ds_read_b128 v[178:181], v137 offset:51200
	ds_read_b128 v[182:185], v137 offset:52224
	ds_read_b128 v[186:189], v137 offset:53248
	ds_read_b128 v[190:193], v137 offset:54272
	ds_read_b128 v[194:197], v137 offset:55296
	ds_read_b128 v[198:201], v137 offset:56320
	global_load_lds_dwordx4 v[202:203], off
	s_add_i32 m0, s44, 0x2000
	s_add_u32 s26, s26, 0x80080
	v_lshl_add_u64 v[202:203], v[204:205], 0, s[6:7]
	s_addc_u32 s27, s27, 0
	s_add_i32 s44, s79, s11
	global_load_lds_dwordx4 v[202:203], off
	v_lshl_add_u64 v[202:203], s[26:27], 0, v[208:209]
	s_mov_b32 m0, s44
	s_nop 0
	global_load_lds_dwordx4 v[202:203], off
	v_lshl_add_u64 v[202:203], s[26:27], 0, v[218:219]
	s_add_i32 m0, s44, 0x2000
	s_nop 0
	global_load_lds_dwordx4 v[202:203], off
	v_lshl_add_u64 v[202:203], v[206:207], 0, s[6:7]
	s_mov_b32 m0, s65
	s_nop 0
	global_load_lds_dwordx4 v[202:203], off
	v_lshl_add_u64 v[202:203], v[210:211], 0, s[6:7]
	s_mov_b32 m0, s66
	s_nop 0
	global_load_lds_dwordx4 v[202:203], off
	s_waitcnt vmcnt(8) lgkmcnt(0)
	s_setprio 1
	s_barrier
	v_mfma_f32_16x16x32_bf16 v[60:63], v[138:141], v[170:173], v[60:63]
	v_mfma_f32_16x16x32_bf16 v[56:59], v[146:149], v[170:173], v[56:59]
	v_mfma_f32_16x16x32_bf16 v[44:47], v[138:141], v[178:181], v[44:47]
	v_mfma_f32_16x16x32_bf16 v[40:43], v[146:149], v[178:181], v[40:43]
	v_mfma_f32_16x16x32_bf16 v[28:31], v[138:141], v[186:189], v[28:31]
	v_mfma_f32_16x16x32_bf16 v[24:27], v[146:149], v[186:189], v[24:27]
	v_mfma_f32_16x16x32_bf16 v[12:15], v[138:141], v[194:197], v[12:15]
	v_mfma_f32_16x16x32_bf16 v[8:11], v[146:149], v[194:197], v[8:11]
	v_mfma_f32_16x16x32_bf16 v[60:63], v[142:145], v[174:177], v[60:63]
	v_mfma_f32_16x16x32_bf16 v[56:59], v[150:153], v[174:177], v[56:59]
	v_mfma_f32_16x16x32_bf16 v[44:47], v[142:145], v[182:185], v[44:47]
	v_mfma_f32_16x16x32_bf16 v[40:43], v[150:153], v[182:185], v[40:43]
	v_mfma_f32_16x16x32_bf16 v[28:31], v[142:145], v[190:193], v[28:31]
	v_mfma_f32_16x16x32_bf16 v[24:27], v[150:153], v[190:193], v[24:27]
	v_mfma_f32_16x16x32_bf16 v[12:15], v[142:145], v[198:201], v[12:15]
	v_mfma_f32_16x16x32_bf16 v[8:11], v[150:153], v[198:201], v[8:11]
	v_mfma_f32_16x16x32_bf16 v[52:55], v[154:157], v[170:173], v[52:55]
	v_mfma_f32_16x16x32_bf16 v[48:51], v[162:165], v[170:173], v[48:51]
	v_mfma_f32_16x16x32_bf16 v[36:39], v[154:157], v[178:181], v[36:39]
	v_mfma_f32_16x16x32_bf16 v[32:35], v[162:165], v[178:181], v[32:35]
	v_mfma_f32_16x16x32_bf16 v[20:23], v[154:157], v[186:189], v[20:23]
	v_mfma_f32_16x16x32_bf16 v[16:19], v[162:165], v[186:189], v[16:19]
	v_mfma_f32_16x16x32_bf16 v[4:7], v[154:157], v[194:197], v[4:7]
	v_mfma_f32_16x16x32_bf16 v[0:3], v[162:165], v[194:197], v[0:3]
	v_mfma_f32_16x16x32_bf16 v[52:55], v[158:161], v[174:177], v[52:55]
	v_mfma_f32_16x16x32_bf16 v[48:51], v[166:169], v[174:177], v[48:51]
	v_mfma_f32_16x16x32_bf16 v[36:39], v[158:161], v[182:185], v[36:39]
	v_mfma_f32_16x16x32_bf16 v[32:35], v[166:169], v[182:185], v[32:35]
	v_mfma_f32_16x16x32_bf16 v[20:23], v[158:161], v[190:193], v[20:23]
	v_mfma_f32_16x16x32_bf16 v[16:19], v[166:169], v[190:193], v[16:19]
	v_mfma_f32_16x16x32_bf16 v[4:7], v[158:161], v[198:201], v[4:7]
	v_mfma_f32_16x16x32_bf16 v[0:3], v[166:169], v[198:201], v[0:3]
	s_barrier
	s_setprio 0
	s_add_i32 s77, s77, 2
	s_add_u32 s22, s22, 0x100
	s_addc_u32 s23, s23, 0
	s_cmp_gt_u32 s77, 29
	s_cbranch_scc0 .LBB0_538
	s_and_b64 vcc, exec, s[40:41]
	s_cbranch_vccz .LBB0_541
	s_barrier

; #define PG8_STAGE(bufoff, gbase, voff) do { _Pragma("unroll") for (int _i = 0; _i < 2; ++_i) \
;         __builtin_amdgcn_global_load_lds((const unsigned*)((const char*)(gbase) + (voff)[_i]), (LAS unsigned*)(lds + (bufoff) + ldsw + _i * 8192), 16, 0, 0); } while (0)
; #define PG8_LDA(dst, b, h) do { _Pragma("unroll") for (int m = 0; m < 4; ++m) _Pragma("unroll") for (int k = 0; k < 2; ++k) dst[m][k] = *(const LAS bf16x8*)(lds + PG8_SA(b, h) + aoff + m * 2048 + k * 1024); } while (0)
; #define PG8_LDB(dst, b, h) do { _Pragma("unroll") for (int n = 0; n < 2; ++n) _Pragma("unroll") for (int k = 0; k < 2; ++k) dst[n][k] = *(const LAS bf16x8*)(lds + PG8_SB(b, h) + boff + n * 2048 + k * 1024); } while (0)
; #define PG8_WAIT_V(n) asm volatile("s_waitcnt vmcnt(" #n ")" ::: "memory")
; #define PG8_WAIT_L(n) asm volatile("s_waitcnt lgkmcnt(" #n ")" ::: "memory")
; #define PG8_BAR __builtin_amdgcn_s_barrier()
; #define PG8_SCHED __builtin_amdgcn_sched_barrier(0)
; template <class Epi, class Sched>
; DI void gemm_phase(LAS unsigned char* lds, const Sched& S, const Epi& E) {
;     ...
;     for (int t = 0; t < nt; t += 2) {
;       const bool last = (t == nt - 2);
;       const char* a1 = cA + (size_t)(t + 1) * kstep;
;       const char* a2 = last ? nA : cA + (size_t)(t + 2) * kstep; const char* b2 = last ? nB : cB + (size_t)(t + 2) * kstep;
;       const char* a3 = a2 + kstep; const char* b3 = b2 + kstep;
;       PG8_LDB(B0, 0, 0); PG8_LDB(B1, 0, 1); PG8_SCHED; PG8_LDA(At, 0, 0); PG8_STAGE(PG8_SA(1, 1), a1 + hstep, voffA);
;       PG8_WAIT_V(8); PG8_WAIT_L(0); PG8_BAR; PG8_MMA(0, 0, At, B0); PG8_MMA(0, 1, At, B1); PG8_BAR; PG8_SCHED;
;       PG8_LDA(At, 0, 1); PG8_STAGE(PG8_SB(0, 0), b2, voffB); PG8_STAGE(PG8_SB(0, 1), b2 + hstep, voffB); PG8_STAGE(PG8_SA(0, 0), a2, voffA);
;       PG8_WAIT_V(8); PG8_WAIT_L(0); PG8_BAR; PG8_MMA(1, 0, At, B0); PG8_MMA(1, 1, At, B1); PG8_BAR; PG8_SCHED;
;       PG8_LDB(B0, 1, 0); PG8_LDB(B1, 1, 1); PG8_SCHED; PG8_LDA(At, 1, 0); PG8_STAGE(PG8_SA(0, 1), a2 + hstep, voffA);
;       PG8_WAIT_V(8); PG8_WAIT_L(0); PG8_BAR; PG8_MMA(0, 0, At, B0); PG8_MMA(0, 1, At, B1); PG8_BAR; PG8_SCHED;
;       PG8_LDA(At, 1, 1); PG8_STAGE(PG8_SB(1, 0), b3, voffB); PG8_STAGE(PG8_SB(1, 1), b3 + hstep, voffB); PG8_STAGE(PG8_SA(1, 0), a3, voffA);
;       PG8_WAIT_V(8); PG8_WAIT_L(0); PG8_BAR; PG8_MMA(1, 0, At, B0); PG8_MMA(1, 1, At, B1); PG8_BAR; PG8_SCHED;
;     }
.LBB0_639:
	s_add_u32 s26, s60, s22
	s_addc_u32 s27, s61, s23
	s_add_u32 s26, s26, 0x100
	s_addc_u32 s27, s27, 0
	s_add_u32 s76, s67, s22
	s_addc_u32 s77, s72, s23
	s_add_i32 s78, 0, 0x10000
	s_cmpk_eq_i32 s22, 0xf00
	s_cselect_b32 s45, s53, s27
	s_cselect_b32 s44, s73, s26
	v_add_u32_e32 v86, s78, v80
	s_cselect_b32 s27, s43, s77
	s_cselect_b32 s26, s74, s76
	s_add_i32 s79, 0, 0x14000
	ds_read_b128 v[82:85], v86
	ds_read_b128 v[144:147], v86 offset:1024
	ds_read_b128 v[148:151], v86 offset:2048
	ds_read_b128 v[152:155], v86 offset:3072
	v_add_u32_e32 v86, s79, v80
	ds_read_b128 v[156:159], v86
	ds_read_b128 v[160:163], v86 offset:1024
	ds_read_b128 v[164:167], v86 offset:2048
	ds_read_b128 v[168:171], v86 offset:3072
	v_lshl_add_u64 v[86:87], v[68:69], 0, s[22:23]
	s_add_i32 m0, s41, 0xc000
	ds_read_b128 v[172:175], v81
	ds_read_b128 v[176:179], v81 offset:1024
	ds_read_b128 v[180:183], v81 offset:2048
	ds_read_b128 v[184:187], v81 offset:3072
	ds_read_b128 v[188:191], v81 offset:4096
	ds_read_b128 v[192:195], v81 offset:5120
	ds_read_b128 v[196:199], v81 offset:6144
	ds_read_b128 v[200:203], v81 offset:7168
	global_load_lds_dwordx4 v[86:87], off
	v_lshl_add_u64 v[86:87], v[70:71], 0, s[22:23]
	s_add_i32 m0, s41, 0xe000
	s_nop 0
	global_load_lds_dwordx4 v[86:87], off
	s_waitcnt vmcnt(8) lgkmcnt(0)
	s_setprio 1
	s_barrier
	v_mfma_f32_16x16x32_bf16 v[140:143], v[82:85], v[172:175], v[140:143]
	v_mfma_f32_16x16x32_bf16 v[136:139], v[148:151], v[172:175], v[136:139]
	v_mfma_f32_16x16x32_bf16 v[124:127], v[82:85], v[180:183], v[124:127]
	v_mfma_f32_16x16x32_bf16 v[120:123], v[148:151], v[180:183], v[120:123]
	v_mfma_f32_16x16x32_bf16 v[108:111], v[82:85], v[188:191], v[108:111]
	v_mfma_f32_16x16x32_bf16 v[104:107], v[148:151], v[188:191], v[104:107]
	v_mfma_f32_16x16x32_bf16 v[92:95], v[82:85], v[196:199], v[92:95]
	v_mfma_f32_16x16x32_bf16 v[86:89], v[148:151], v[196:199], v[88:91]
	v_mfma_f32_16x16x32_bf16 v[140:143], v[144:147], v[176:179], v[140:143]
	v_mfma_f32_16x16x32_bf16 v[136:139], v[152:155], v[176:179], v[136:139]
	v_mfma_f32_16x16x32_bf16 v[124:127], v[144:147], v[184:187], v[124:127]
	v_mfma_f32_16x16x32_bf16 v[120:123], v[152:155], v[184:187], v[120:123]
	v_mfma_f32_16x16x32_bf16 v[108:111], v[144:147], v[192:195], v[108:111]
	v_mfma_f32_16x16x32_bf16 v[104:107], v[152:155], v[192:195], v[104:107]
	v_mfma_f32_16x16x32_bf16 v[92:95], v[144:147], v[200:203], v[92:95]
	v_mfma_f32_16x16x32_bf16 v[86:89], v[152:155], v[200:203], v[86:89]
	v_mfma_f32_16x16x32_bf16 v[132:135], v[156:159], v[172:175], v[132:135]
	v_mfma_f32_16x16x32_bf16 v[128:131], v[164:167], v[172:175], v[128:131]
	v_mfma_f32_16x16x32_bf16 v[116:119], v[156:159], v[180:183], v[116:119]
	v_mfma_f32_16x16x32_bf16 v[112:115], v[164:167], v[180:183], v[112:115]
	v_mfma_f32_16x16x32_bf16 v[100:103], v[156:159], v[188:191], v[100:103]
	v_mfma_f32_16x16x32_bf16 v[96:99], v[164:167], v[188:191], v[96:99]
	v_mfma_f32_16x16x32_bf16 v[76:79], v[156:159], v[196:199], v[76:79]
	v_mfma_f32_16x16x32_bf16 v[72:75], v[164:167], v[196:199], v[72:75]
	v_mfma_f32_16x16x32_bf16 v[132:135], v[160:163], v[176:179], v[132:135]
	v_mfma_f32_16x16x32_bf16 v[128:131], v[168:171], v[176:179], v[128:131]
	v_mfma_f32_16x16x32_bf16 v[116:119], v[160:163], v[184:187], v[116:119]
	v_mfma_f32_16x16x32_bf16 v[112:115], v[168:171], v[184:187], v[112:115]
	v_mfma_f32_16x16x32_bf16 v[100:103], v[160:163], v[192:195], v[100:103]
	v_mfma_f32_16x16x32_bf16 v[96:99], v[168:171], v[192:195], v[96:99]
	v_mfma_f32_16x16x32_bf16 v[76:79], v[160:163], v[200:203], v[76:79]
	v_mfma_f32_16x16x32_bf16 v[72:75], v[168:171], v[200:203], v[72:75]
	s_barrier
	s_setprio 0
	s_add_i32 s76, s78, s11
	v_lshl_add_u64 v[204:205], s[26:27], 0, v[208:209]
	s_mov_b32 m0, s76
	ds_read_b128 v[172:175], v81 offset:16384
	ds_read_b128 v[176:179], v81 offset:17408
	ds_read_b128 v[180:183], v81 offset:18432
	ds_read_b128 v[184:187], v81 offset:19456
	ds_read_b128 v[188:191], v81 offset:20480
	ds_read_b128 v[192:195], v81 offset:21504
	ds_read_b128 v[196:199], v81 offset:22528
	ds_read_b128 v[200:203], v81 offset:23552
	global_load_lds_dwordx4 v[204:205], off
	s_add_i32 m0, s76, 0x2000
	s_add_u32 s76, s26, 0x80000
	v_lshl_add_u64 v[206:207], s[26:27], 0, v[218:219]
	s_addc_u32 s77, s27, 0
	s_add_i32 s78, s79, s11
	global_load_lds_dwordx4 v[206:207], off
	v_lshl_add_u64 v[90:91], s[76:77], 0, v[208:209]
	s_mov_b32 m0, s78
	v_lshl_add_u64 v[210:211], s[44:45], 0, v[214:215]
	global_load_lds_dwordx4 v[90:91], off
	v_lshl_add_u64 v[90:91], s[76:77], 0, v[218:219]
	s_add_i32 m0, s78, 0x2000
	v_lshl_add_u64 v[212:213], s[44:45], 0, v[216:217]
	global_load_lds_dwordx4 v[90:91], off
	s_mov_b32 m0, s41
	s_nop 0
	global_load_lds_dwordx4 v[210:211], off
	s_mov_b32 m0, s51
	s_nop 0
	global_load_lds_dwordx4 v[212:213], off
	s_waitcnt vmcnt(8) lgkmcnt(0)
	s_setprio 1
	s_barrier
; #define PG8_STAGE(bufoff, gbase, voff) do { _Pragma("unroll") for (int _i = 0; _i < 2; ++_i) \
;         __builtin_amdgcn_global_load_lds((const unsigned*)((const char*)(gbase) + (voff)[_i]), (LAS unsigned*)(lds + (bufoff) + ldsw + _i * 8192), 16, 0, 0); } while (0)
; #define PG8_LDA(dst, b, h) do { _Pragma("unroll") for (int m = 0; m < 4; ++m) _Pragma("unroll") for (int k = 0; k < 2; ++k) dst[m][k] = *(const LAS bf16x8*)(lds + PG8_SA(b, h) + aoff + m * 2048 + k * 1024); } while (0)
; #define PG8_LDB(dst, b, h) do { _Pragma("unroll") for (int n = 0; n < 2; ++n) _Pragma("unroll") for (int k = 0; k < 2; ++k) dst[n][k] = *(const LAS bf16x8*)(lds + PG8_SB(b, h) + boff + n * 2048 + k * 1024); } while (0)
; #define PG8_WAIT_V(n) asm volatile("s_waitcnt vmcnt(" #n ")" ::: "memory")
; #define PG8_WAIT_L(n) asm volatile("s_waitcnt lgkmcnt(" #n ")" ::: "memory")
; #define PG8_BAR __builtin_amdgcn_s_barrier()
; #define PG8_SCHED __builtin_amdgcn_sched_barrier(0)
; template <class Epi, class Sched>
; DI void gemm_phase(LAS unsigned char* lds, const Sched& S, const Epi& E) {
;     ...
;     for (int t = 0; t < nt; t += 2) {
;       const bool last = (t == nt - 2);
;       const char* a1 = cA + (size_t)(t + 1) * kstep;
;       const char* a2 = last ? nA : cA + (size_t)(t + 2) * kstep; const char* b2 = last ? nB : cB + (size_t)(t + 2) * kstep;
;       const char* a3 = a2 + kstep; const char* b3 = b2 + kstep;
;       PG8_LDB(B0, 0, 0); PG8_LDB(B1, 0, 1); PG8_SCHED; PG8_LDA(At, 0, 0); PG8_STAGE(PG8_SA(1, 1), a1 + hstep, voffA);
;       PG8_WAIT_V(8); PG8_WAIT_L(0); PG8_BAR; PG8_MMA(0, 0, At, B0); PG8_MMA(0, 1, At, B1); PG8_BAR; PG8_SCHED;
;       PG8_LDA(At, 0, 1); PG8_STAGE(PG8_SB(0, 0), b2, voffB); PG8_STAGE(PG8_SB(0, 1), b2 + hstep, voffB); PG8_STAGE(PG8_SA(0, 0), a2, voffA);
;       PG8_WAIT_V(8); PG8_WAIT_L(0); PG8_BAR; PG8_MMA(1, 0, At, B0); PG8_MMA(1, 1, At, B1); PG8_BAR; PG8_SCHED;
;       PG8_LDB(B0, 1, 0); PG8_LDB(B1, 1, 1); PG8_SCHED; PG8_LDA(At, 1, 0); PG8_STAGE(PG8_SA(0, 1), a2 + hstep, voffA);
;       PG8_WAIT_V(8); PG8_WAIT_L(0); PG8_BAR; PG8_MMA(0, 0, At, B0); PG8_MMA(0, 1, At, B1); PG8_BAR; PG8_SCHED;
;       PG8_LDA(At, 1, 1); PG8_STAGE(PG8_SB(1, 0), b3, voffB); PG8_STAGE(PG8_SB(1, 1), b3 + hstep, voffB); PG8_STAGE(PG8_SA(1, 0), a3, voffA);
;       PG8_WAIT_V(8); PG8_WAIT_L(0); PG8_BAR; PG8_MMA(1, 0, At, B0); PG8_MMA(1, 1, At, B1); PG8_BAR; PG8_SCHED;
;     }
	v_mfma_f32_16x16x32_bf16 v[60:63], v[82:85], v[172:175], v[60:63]
	v_mfma_f32_16x16x32_bf16 v[56:59], v[148:151], v[172:175], v[56:59]
	v_mfma_f32_16x16x32_bf16 v[44:47], v[82:85], v[180:183], v[44:47]
	v_mfma_f32_16x16x32_bf16 v[40:43], v[148:151], v[180:183], v[40:43]
	v_mfma_f32_16x16x32_bf16 v[28:31], v[82:85], v[188:191], v[28:31]
	v_mfma_f32_16x16x32_bf16 v[24:27], v[148:151], v[188:191], v[24:27]
	v_mfma_f32_16x16x32_bf16 v[12:15], v[82:85], v[196:199], v[12:15]
	v_mfma_f32_16x16x32_bf16 v[8:11], v[148:151], v[196:199], v[8:11]
	v_mfma_f32_16x16x32_bf16 v[60:63], v[144:147], v[176:179], v[60:63]
	v_mfma_f32_16x16x32_bf16 v[56:59], v[152:155], v[176:179], v[56:59]
	v_mfma_f32_16x16x32_bf16 v[44:47], v[144:147], v[184:187], v[44:47]
	v_mfma_f32_16x16x32_bf16 v[40:43], v[152:155], v[184:187], v[40:43]
	v_mfma_f32_16x16x32_bf16 v[28:31], v[144:147], v[192:195], v[28:31]
	v_mfma_f32_16x16x32_bf16 v[24:27], v[152:155], v[192:195], v[24:27]
	v_mfma_f32_16x16x32_bf16 v[12:15], v[144:147], v[200:203], v[12:15]
	v_mfma_f32_16x16x32_bf16 v[8:11], v[152:155], v[200:203], v[8:11]
	v_mfma_f32_16x16x32_bf16 v[52:55], v[156:159], v[172:175], v[52:55]
	v_mfma_f32_16x16x32_bf16 v[48:51], v[164:167], v[172:175], v[48:51]
	v_mfma_f32_16x16x32_bf16 v[36:39], v[156:159], v[180:183], v[36:39]
	v_mfma_f32_16x16x32_bf16 v[32:35], v[164:167], v[180:183], v[32:35]
	v_mfma_f32_16x16x32_bf16 v[20:23], v[156:159], v[188:191], v[20:23]
	v_mfma_f32_16x16x32_bf16 v[16:19], v[164:167], v[188:191], v[16:19]
	v_mfma_f32_16x16x32_bf16 v[4:7], v[156:159], v[196:199], v[4:7]
	v_mfma_f32_16x16x32_bf16 v[0:3], v[164:167], v[196:199], v[0:3]
	v_mfma_f32_16x16x32_bf16 v[52:55], v[160:163], v[176:179], v[52:55]
	v_mfma_f32_16x16x32_bf16 v[48:51], v[168:171], v[176:179], v[48:51]
	v_mfma_f32_16x16x32_bf16 v[36:39], v[160:163], v[184:187], v[36:39]
	v_mfma_f32_16x16x32_bf16 v[32:35], v[168:171], v[184:187], v[32:35]
	v_mfma_f32_16x16x32_bf16 v[20:23], v[160:163], v[192:195], v[20:23]
	v_mfma_f32_16x16x32_bf16 v[16:19], v[168:171], v[192:195], v[16:19]
	v_mfma_f32_16x16x32_bf16 v[4:7], v[160:163], v[200:203], v[4:7]
	v_mfma_f32_16x16x32_bf16 v[0:3], v[168:171], v[200:203], v[0:3]
	s_barrier
	s_setprio 0
	s_add_i32 s76, 0, 0x18000
	v_add_u32_e32 v90, s76, v80
	s_add_i32 s77, 0, 0x1c000
	ds_read_b128 v[82:85], v90
	ds_read_b128 v[144:147], v90 offset:1024
	ds_read_b128 v[148:151], v90 offset:2048
	ds_read_b128 v[152:155], v90 offset:3072
	v_add_u32_e32 v90, s77, v80
	ds_read_b128 v[156:159], v90
	ds_read_b128 v[160:163], v90 offset:1024
	ds_read_b128 v[164:167], v90 offset:2048
	ds_read_b128 v[168:171], v90 offset:3072
	s_add_u32 s44, s44, 0x80000
	s_addc_u32 s45, s45, 0
	s_mov_b32 m0, s54
	v_lshl_add_u64 v[90:91], s[44:45], 0, v[214:215]
	ds_read_b128 v[172:175], v81 offset:32768
	ds_read_b128 v[176:179], v81 offset:33792
	ds_read_b128 v[180:183], v81 offset:34816
	ds_read_b128 v[184:187], v81 offset:35840
	ds_read_b128 v[188:191], v81 offset:36864
	ds_read_b128 v[192:195], v81 offset:37888
	ds_read_b128 v[196:199], v81 offset:38912
	ds_read_b128 v[200:203], v81 offset:39936
	global_load_lds_dwordx4 v[90:91], off
	v_lshl_add_u64 v[90:91], s[44:45], 0, v[216:217]
	s_mov_b32 m0, s55
	s_nop 0
	global_load_lds_dwordx4 v[90:91], off
	s_waitcnt vmcnt(8) lgkmcnt(0)
	s_setprio 1
	s_barrier
	v_mfma_f32_16x16x32_bf16 v[140:143], v[82:85], v[172:175], v[140:143]
	v_mfma_f32_16x16x32_bf16 v[136:139], v[148:151], v[172:175], v[136:139]
	v_mfma_f32_16x16x32_bf16 v[124:127], v[82:85], v[180:183], v[124:127]
	v_mfma_f32_16x16x32_bf16 v[120:123], v[148:151], v[180:183], v[120:123]
	v_mfma_f32_16x16x32_bf16 v[108:111], v[82:85], v[188:191], v[108:111]
	v_mfma_f32_16x16x32_bf16 v[104:107], v[148:151], v[188:191], v[104:107]
	v_mfma_f32_16x16x32_bf16 v[90:93], v[82:85], v[196:199], v[92:95]
	v_mfma_f32_16x16x32_bf16 v[86:89], v[148:151], v[196:199], v[86:89]
	v_mfma_f32_16x16x32_bf16 v[140:143], v[144:147], v[176:179], v[140:143]
	v_mfma_f32_16x16x32_bf16 v[136:139], v[152:155], v[176:179], v[136:139]
	v_mfma_f32_16x16x32_bf16 v[124:127], v[144:147], v[184:187], v[124:127]
	v_mfma_f32_16x16x32_bf16 v[120:123], v[152:155], v[184:187], v[120:123]
	v_mfma_f32_16x16x32_bf16 v[108:111], v[144:147], v[192:195], v[108:111]
	v_mfma_f32_16x16x32_bf16 v[104:107], v[152:155], v[192:195], v[104:107]
	v_mfma_f32_16x16x32_bf16 v[92:95], v[144:147], v[200:203], v[90:93]
	v_mfma_f32_16x16x32_bf16 v[88:91], v[152:155], v[200:203], v[86:89]
	v_mfma_f32_16x16x32_bf16 v[132:135], v[156:159], v[172:175], v[132:135]
	v_mfma_f32_16x16x32_bf16 v[128:131], v[164:167], v[172:175], v[128:131]
	v_mfma_f32_16x16x32_bf16 v[116:119], v[156:159], v[180:183], v[116:119]
	v_mfma_f32_16x16x32_bf16 v[112:115], v[164:167], v[180:183], v[112:115]
	v_mfma_f32_16x16x32_bf16 v[100:103], v[156:159], v[188:191], v[100:103]
	v_mfma_f32_16x16x32_bf16 v[96:99], v[164:167], v[188:191], v[96:99]
	v_mfma_f32_16x16x32_bf16 v[76:79], v[156:159], v[196:199], v[76:79]
	v_mfma_f32_16x16x32_bf16 v[72:75], v[164:167], v[196:199], v[72:75]
	v_mfma_f32_16x16x32_bf16 v[132:135], v[160:163], v[176:179], v[132:135]
	v_mfma_f32_16x16x32_bf16 v[128:131], v[168:171], v[176:179], v[128:131]
	v_mfma_f32_16x16x32_bf16 v[116:119], v[160:163], v[184:187], v[116:119]
	v_mfma_f32_16x16x32_bf16 v[112:115], v[168:171], v[184:187], v[112:115]
	v_mfma_f32_16x16x32_bf16 v[100:103], v[160:163], v[192:195], v[100:103]
	v_mfma_f32_16x16x32_bf16 v[96:99], v[168:171], v[192:195], v[96:99]
	v_mfma_f32_16x16x32_bf16 v[76:79], v[160:163], v[200:203], v[76:79]
	v_mfma_f32_16x16x32_bf16 v[72:75], v[168:171], v[200:203], v[72:75]
	s_barrier
; #define PG8_STAGE(bufoff, gbase, voff) do { _Pragma("unroll") for (int _i = 0; _i < 2; ++_i) \
;         __builtin_amdgcn_global_load_lds((const unsigned*)((const char*)(gbase) + (voff)[_i]), (LAS unsigned*)(lds + (bufoff) + ldsw + _i * 8192), 16, 0, 0); } while (0)
; #define PG8_LDA(dst, b, h) do { _Pragma("unroll") for (int m = 0; m < 4; ++m) _Pragma("unroll") for (int k = 0; k < 2; ++k) dst[m][k] = *(const LAS bf16x8*)(lds + PG8_SA(b, h) + aoff + m * 2048 + k * 1024); } while (0)
; #define PG8_LDB(dst, b, h) do { _Pragma("unroll") for (int n = 0; n < 2; ++n) _Pragma("unroll") for (int k = 0; k < 2; ++k) dst[n][k] = *(const LAS bf16x8*)(lds + PG8_SB(b, h) + boff + n * 2048 + k * 1024); } while (0)
; #define PG8_WAIT_V(n) asm volatile("s_waitcnt vmcnt(" #n ")" ::: "memory")
; #define PG8_WAIT_L(n) asm volatile("s_waitcnt lgkmcnt(" #n ")" ::: "memory")
; #define PG8_BAR __builtin_amdgcn_s_barrier()
; template <class Epi, class Sched>
; DI void gemm_phase(LAS unsigned char* lds, const Sched& S, const Epi& E) {
;     ...
;     for (int t = 0; t < nt; t += 2) {
;       const bool last = (t == nt - 2);
;       const char* a1 = cA + (size_t)(t + 1) * kstep;
;       const char* a2 = last ? nA : cA + (size_t)(t + 2) * kstep; const char* b2 = last ? nB : cB + (size_t)(t + 2) * kstep;
;       const char* a3 = a2 + kstep; const char* b3 = b2 + kstep;
;       PG8_LDB(B0, 0, 0); PG8_LDB(B1, 0, 1); PG8_SCHED; PG8_LDA(At, 0, 0); PG8_STAGE(PG8_SA(1, 1), a1 + hstep, voffA);
;       PG8_WAIT_V(8); PG8_WAIT_L(0); PG8_BAR; PG8_MMA(0, 0, At, B0); PG8_MMA(0, 1, At, B1); PG8_BAR; PG8_SCHED;
;       PG8_LDA(At, 0, 1); PG8_STAGE(PG8_SB(0, 0), b2, voffB); PG8_STAGE(PG8_SB(0, 1), b2 + hstep, voffB); PG8_STAGE(PG8_SA(0, 0), a2, voffA);
;       PG8_WAIT_V(8); PG8_WAIT_L(0); PG8_BAR; PG8_MMA(1, 0, At, B0); PG8_MMA(1, 1, At, B1); PG8_BAR; PG8_SCHED;
;       PG8_LDB(B0, 1, 0); PG8_LDB(B1, 1, 1); PG8_SCHED; PG8_LDA(At, 1, 0); PG8_STAGE(PG8_SA(0, 1), a2 + hstep, voffA);
;       PG8_WAIT_V(8); PG8_WAIT_L(0); PG8_BAR; PG8_MMA(0, 0, At, B0); PG8_MMA(0, 1, At, B1); PG8_BAR; PG8_SCHED;
;       PG8_LDA(At, 1, 1); PG8_STAGE(PG8_SB(1, 0), b3, voffB); PG8_STAGE(PG8_SB(1, 1), b3 + hstep, voffB); PG8_STAGE(PG8_SA(1, 0), a3, voffA);
;       PG8_WAIT_V(8); PG8_WAIT_L(0); PG8_BAR; PG8_MMA(1, 0, At, B0); PG8_MMA(1, 1, At, B1); PG8_BAR; PG8_SCHED;
;     }
;     if (wr == 0) PG8_BAR;
	s_setprio 0
	s_add_i32 s44, s76, s11
	v_lshl_add_u64 v[86:87], v[204:205], 0, s[6:7]
	s_mov_b32 m0, s44
	ds_read_b128 v[172:175], v81 offset:49152
	ds_read_b128 v[176:179], v81 offset:50176
	ds_read_b128 v[180:183], v81 offset:51200
	ds_read_b128 v[184:187], v81 offset:52224
	ds_read_b128 v[188:191], v81 offset:53248
	ds_read_b128 v[192:195], v81 offset:54272
	ds_read_b128 v[196:199], v81 offset:55296
	ds_read_b128 v[200:203], v81 offset:56320
	global_load_lds_dwordx4 v[86:87], off
	s_add_i32 m0, s44, 0x2000
	s_add_u32 s26, s26, 0x80080
	v_lshl_add_u64 v[86:87], v[206:207], 0, s[6:7]
	s_addc_u32 s27, s27, 0
	s_add_i32 s44, s77, s11
	global_load_lds_dwordx4 v[86:87], off
	v_lshl_add_u64 v[86:87], s[26:27], 0, v[208:209]
	s_mov_b32 m0, s44
	s_nop 0
	global_load_lds_dwordx4 v[86:87], off
	v_lshl_add_u64 v[86:87], s[26:27], 0, v[218:219]
	s_add_i32 m0, s44, 0x2000
	s_nop 0
	global_load_lds_dwordx4 v[86:87], off
	v_lshl_add_u64 v[86:87], v[210:211], 0, s[6:7]
	s_mov_b32 m0, s63
	s_nop 0
	global_load_lds_dwordx4 v[86:87], off
	v_lshl_add_u64 v[86:87], v[212:213], 0, s[6:7]
	s_mov_b32 m0, s64
	s_nop 0
	global_load_lds_dwordx4 v[86:87], off
	s_waitcnt vmcnt(8) lgkmcnt(0)
	s_setprio 1
	s_barrier
	v_mfma_f32_16x16x32_bf16 v[60:63], v[82:85], v[172:175], v[60:63]
	v_mfma_f32_16x16x32_bf16 v[56:59], v[148:151], v[172:175], v[56:59]
	v_mfma_f32_16x16x32_bf16 v[44:47], v[82:85], v[180:183], v[44:47]
	v_mfma_f32_16x16x32_bf16 v[40:43], v[148:151], v[180:183], v[40:43]
	v_mfma_f32_16x16x32_bf16 v[28:31], v[82:85], v[188:191], v[28:31]
	v_mfma_f32_16x16x32_bf16 v[24:27], v[148:151], v[188:191], v[24:27]
	v_mfma_f32_16x16x32_bf16 v[12:15], v[82:85], v[196:199], v[12:15]
	v_mfma_f32_16x16x32_bf16 v[8:11], v[148:151], v[196:199], v[8:11]
	v_mfma_f32_16x16x32_bf16 v[60:63], v[144:147], v[176:179], v[60:63]
	v_mfma_f32_16x16x32_bf16 v[56:59], v[152:155], v[176:179], v[56:59]
	v_mfma_f32_16x16x32_bf16 v[44:47], v[144:147], v[184:187], v[44:47]
	v_mfma_f32_16x16x32_bf16 v[40:43], v[152:155], v[184:187], v[40:43]
	v_mfma_f32_16x16x32_bf16 v[28:31], v[144:147], v[192:195], v[28:31]
	v_mfma_f32_16x16x32_bf16 v[24:27], v[152:155], v[192:195], v[24:27]
	v_mfma_f32_16x16x32_bf16 v[12:15], v[144:147], v[200:203], v[12:15]
	v_mfma_f32_16x16x32_bf16 v[8:11], v[152:155], v[200:203], v[8:11]
	v_mfma_f32_16x16x32_bf16 v[52:55], v[156:159], v[172:175], v[52:55]
	v_mfma_f32_16x16x32_bf16 v[48:51], v[164:167], v[172:175], v[48:51]
	v_mfma_f32_16x16x32_bf16 v[36:39], v[156:159], v[180:183], v[36:39]
	v_mfma_f32_16x16x32_bf16 v[32:35], v[164:167], v[180:183], v[32:35]
	v_mfma_f32_16x16x32_bf16 v[20:23], v[156:159], v[188:191], v[20:23]
	v_mfma_f32_16x16x32_bf16 v[16:19], v[164:167], v[188:191], v[16:19]
	v_mfma_f32_16x16x32_bf16 v[4:7], v[156:159], v[196:199], v[4:7]
	v_mfma_f32_16x16x32_bf16 v[0:3], v[164:167], v[196:199], v[0:3]
	v_mfma_f32_16x16x32_bf16 v[52:55], v[160:163], v[176:179], v[52:55]
	v_mfma_f32_16x16x32_bf16 v[48:51], v[168:171], v[176:179], v[48:51]
	v_mfma_f32_16x16x32_bf16 v[36:39], v[160:163], v[184:187], v[36:39]
	v_mfma_f32_16x16x32_bf16 v[32:35], v[168:171], v[184:187], v[32:35]
	v_mfma_f32_16x16x32_bf16 v[20:23], v[160:163], v[192:195], v[20:23]
	v_mfma_f32_16x16x32_bf16 v[16:19], v[168:171], v[192:195], v[16:19]
	v_mfma_f32_16x16x32_bf16 v[4:7], v[160:163], v[200:203], v[4:7]
	v_mfma_f32_16x16x32_bf16 v[0:3], v[168:171], v[200:203], v[0:3]
	s_barrier
	s_setprio 0
	s_add_i32 s75, s75, 2
	s_add_u32 s22, s22, 0x100
	s_addc_u32 s23, s23, 0
	s_cmp_gt_u32 s75, 29
	s_cbranch_scc0 .LBB0_639
	s_and_b64 vcc, exec, s[38:39]
	s_cbranch_vccz .LBB0_642
	s_barrier

; #define PG8_STAGE(bufoff, gbase, voff) do { _Pragma("unroll") for (int _i = 0; _i < 2; ++_i) \
;         __builtin_amdgcn_global_load_lds((const unsigned*)((const char*)(gbase) + (voff)[_i]), (LAS unsigned*)(lds + (bufoff) + ldsw + _i * 8192), 16, 0, 0); } while (0)
; #define PG8_LDA(dst, b, h) do { _Pragma("unroll") for (int m = 0; m < 4; ++m) _Pragma("unroll") for (int k = 0; k < 2; ++k) dst[m][k] = *(const LAS bf16x8*)(lds + PG8_SA(b, h) + aoff + m * 2048 + k * 1024); } while (0)
; #define PG8_LDB(dst, b, h) do { _Pragma("unroll") for (int n = 0; n < 2; ++n) _Pragma("unroll") for (int k = 0; k < 2; ++k) dst[n][k] = *(const LAS bf16x8*)(lds + PG8_SB(b, h) + boff + n * 2048 + k * 1024); } while (0)
; #define PG8_WAIT_V(n) asm volatile("s_waitcnt vmcnt(" #n ")" ::: "memory")
; #define PG8_WAIT_L(n) asm volatile("s_waitcnt lgkmcnt(" #n ")" ::: "memory")
; #define PG8_BAR __builtin_amdgcn_s_barrier()
; #define PG8_SCHED __builtin_amdgcn_sched_barrier(0)
; template <class Epi, class Sched>
; DI void gemm_phase(LAS unsigned char* lds, const Sched& S, const Epi& E) {
;     ...
;     for (int t = 0; t < nt; t += 2) {
;       const bool last = (t == nt - 2);
;       const char* a1 = cA + (size_t)(t + 1) * kstep;
;       const char* a2 = last ? nA : cA + (size_t)(t + 2) * kstep; const char* b2 = last ? nB : cB + (size_t)(t + 2) * kstep;
;       const char* a3 = a2 + kstep; const char* b3 = b2 + kstep;
;       PG8_LDB(B0, 0, 0); PG8_LDB(B1, 0, 1); PG8_SCHED; PG8_LDA(At, 0, 0); PG8_STAGE(PG8_SA(1, 1), a1 + hstep, voffA);
;       PG8_WAIT_V(8); PG8_WAIT_L(0); PG8_BAR; PG8_MMA(0, 0, At, B0); PG8_MMA(0, 1, At, B1); PG8_BAR; PG8_SCHED;
;       PG8_LDA(At, 0, 1); PG8_STAGE(PG8_SB(0, 0), b2, voffB); PG8_STAGE(PG8_SB(0, 1), b2 + hstep, voffB); PG8_STAGE(PG8_SA(0, 0), a2, voffA);
;       PG8_WAIT_V(8); PG8_WAIT_L(0); PG8_BAR; PG8_MMA(1, 0, At, B0); PG8_MMA(1, 1, At, B1); PG8_BAR; PG8_SCHED;
;       PG8_LDB(B0, 1, 0); PG8_LDB(B1, 1, 1); PG8_SCHED; PG8_LDA(At, 1, 0); PG8_STAGE(PG8_SA(0, 1), a2 + hstep, voffA);
;       PG8_WAIT_V(8); PG8_WAIT_L(0); PG8_BAR; PG8_MMA(0, 0, At, B0); PG8_MMA(0, 1, At, B1); PG8_BAR; PG8_SCHED;
;       PG8_LDA(At, 1, 1); PG8_STAGE(PG8_SB(1, 0), b3, voffB); PG8_STAGE(PG8_SB(1, 1), b3 + hstep, voffB); PG8_STAGE(PG8_SA(1, 0), a3, voffA);
;       PG8_WAIT_V(8); PG8_WAIT_L(0); PG8_BAR; PG8_MMA(1, 0, At, B0); PG8_MMA(1, 1, At, B1); PG8_BAR; PG8_SCHED;
;     }
.LBB0_744:
	s_add_u32 s22, s58, 0xfff80080
	s_addc_u32 s23, s59, -1
	s_add_i32 s67, 0, 0x10000
	s_cmp_eq_u32 s66, 28
	s_cselect_b32 s27, s12, s23
	s_cselect_b32 s26, s25, s22
	s_cselect_b32 s23, s41, s45
	s_cselect_b32 s22, s43, s44
	s_add_i32 s74, 0, 0x14000
	v_add_u32_e32 v154, s67, v143
	v_add_u32_e32 v170, s74, v143
	ds_read_b128 v[138:141], v154
	ds_read_b128 v[146:149], v154 offset:1024
	ds_read_b128 v[150:153], v154 offset:2048
	ds_read_b128 v[154:157], v154 offset:3072
	ds_read_b128 v[158:161], v170
	ds_read_b128 v[162:165], v170 offset:1024
	ds_read_b128 v[166:169], v170 offset:2048
	ds_read_b128 v[170:173], v170 offset:3072
	v_lshl_add_u64 v[206:207], s[58:59], 0, v[134:135]
	s_add_i32 m0, s11, 0xc000
	ds_read_b128 v[174:177], v145
	ds_read_b128 v[178:181], v145 offset:1024
	ds_read_b128 v[182:185], v145 offset:2048
	ds_read_b128 v[186:189], v145 offset:3072
	ds_read_b128 v[190:193], v145 offset:4096
	ds_read_b128 v[194:197], v145 offset:5120
	ds_read_b128 v[198:201], v145 offset:6144
	ds_read_b128 v[202:205], v145 offset:7168
	global_load_lds_dwordx4 v[206:207], off
	v_lshl_add_u64 v[206:207], s[58:59], 0, v[136:137]
	s_add_i32 m0, s11, 0xe000
	s_nop 0
	global_load_lds_dwordx4 v[206:207], off
	s_waitcnt vmcnt(8) lgkmcnt(0)
	s_setprio 1
	s_barrier
	v_mfma_f32_16x16x32_bf16 v[124:127], v[138:141], v[174:177], v[124:127]
	v_mfma_f32_16x16x32_bf16 v[120:123], v[150:153], v[174:177], v[120:123]
	v_mfma_f32_16x16x32_bf16 v[108:111], v[138:141], v[182:185], v[108:111]
	v_mfma_f32_16x16x32_bf16 v[104:107], v[150:153], v[182:185], v[104:107]
	v_mfma_f32_16x16x32_bf16 v[92:95], v[138:141], v[190:193], v[92:95]
	v_mfma_f32_16x16x32_bf16 v[88:91], v[150:153], v[190:193], v[88:91]
	v_mfma_f32_16x16x32_bf16 v[76:79], v[138:141], v[198:201], v[76:79]
	v_mfma_f32_16x16x32_bf16 v[72:75], v[150:153], v[198:201], v[72:75]
	v_mfma_f32_16x16x32_bf16 v[124:127], v[146:149], v[178:181], v[124:127]
	v_mfma_f32_16x16x32_bf16 v[120:123], v[154:157], v[178:181], v[120:123]
	v_mfma_f32_16x16x32_bf16 v[108:111], v[146:149], v[186:189], v[108:111]
	v_mfma_f32_16x16x32_bf16 v[104:107], v[154:157], v[186:189], v[104:107]
	v_mfma_f32_16x16x32_bf16 v[92:95], v[146:149], v[194:197], v[92:95]
	v_mfma_f32_16x16x32_bf16 v[88:91], v[154:157], v[194:197], v[88:91]
	v_mfma_f32_16x16x32_bf16 v[76:79], v[146:149], v[202:205], v[76:79]
	v_mfma_f32_16x16x32_bf16 v[72:75], v[154:157], v[202:205], v[72:75]
	v_mfma_f32_16x16x32_bf16 v[116:119], v[158:161], v[174:177], v[116:119]
	v_mfma_f32_16x16x32_bf16 v[112:115], v[166:169], v[174:177], v[112:115]
	v_mfma_f32_16x16x32_bf16 v[100:103], v[158:161], v[182:185], v[100:103]
	v_mfma_f32_16x16x32_bf16 v[96:99], v[166:169], v[182:185], v[96:99]
	v_mfma_f32_16x16x32_bf16 v[84:87], v[158:161], v[190:193], v[84:87]
	v_mfma_f32_16x16x32_bf16 v[80:83], v[166:169], v[190:193], v[80:83]
	v_mfma_f32_16x16x32_bf16 v[68:71], v[158:161], v[198:201], v[68:71]
	v_mfma_f32_16x16x32_bf16 v[64:67], v[166:169], v[198:201], v[64:67]
	v_mfma_f32_16x16x32_bf16 v[116:119], v[162:165], v[178:181], v[116:119]
	v_mfma_f32_16x16x32_bf16 v[112:115], v[170:173], v[178:181], v[112:115]
	v_mfma_f32_16x16x32_bf16 v[100:103], v[162:165], v[186:189], v[100:103]
	v_mfma_f32_16x16x32_bf16 v[96:99], v[170:173], v[186:189], v[96:99]
	v_mfma_f32_16x16x32_bf16 v[84:87], v[162:165], v[194:197], v[84:87]
	v_mfma_f32_16x16x32_bf16 v[80:83], v[170:173], v[194:197], v[80:83]
	v_mfma_f32_16x16x32_bf16 v[68:71], v[162:165], v[202:205], v[68:71]
	v_mfma_f32_16x16x32_bf16 v[64:67], v[170:173], v[202:205], v[64:67]
	s_barrier
	s_setprio 0
	s_add_i32 s67, s67, s10
	v_lshl_add_u64 v[206:207], s[22:23], 0, v[208:209]
	s_mov_b32 m0, s67
	ds_read_b128 v[174:177], v145 offset:16384
	ds_read_b128 v[178:181], v145 offset:17408
	ds_read_b128 v[182:185], v145 offset:18432
	ds_read_b128 v[186:189], v145 offset:19456
	ds_read_b128 v[190:193], v145 offset:20480
	ds_read_b128 v[194:197], v145 offset:21504
	ds_read_b128 v[198:201], v145 offset:22528
	ds_read_b128 v[202:205], v145 offset:23552
	global_load_lds_dwordx4 v[206:207], off
	s_add_i32 m0, s67, 0x2000
	s_add_u32 s72, s22, 0x80000
	v_lshl_add_u64 v[210:211], s[22:23], 0, v[132:133]
	s_addc_u32 s73, s23, 0
	s_add_i32 s67, s74, s10
	global_load_lds_dwordx4 v[210:211], off
	v_lshl_add_u64 v[212:213], s[72:73], 0, v[208:209]
	s_mov_b32 m0, s67
	v_lshl_add_u64 v[214:215], s[26:27], 0, v[130:131]
	global_load_lds_dwordx4 v[212:213], off
	v_lshl_add_u64 v[212:213], s[72:73], 0, v[132:133]
	s_add_i32 m0, s67, 0x2000
	s_nop 0
	global_load_lds_dwordx4 v[212:213], off
	v_lshl_add_u64 v[212:213], s[26:27], 0, v[128:129]
	s_mov_b32 m0, s11
	s_nop 0
	global_load_lds_dwordx4 v[212:213], off
	s_mov_b32 m0, s50
	s_nop 0
	global_load_lds_dwordx4 v[214:215], off
	s_waitcnt vmcnt(8) lgkmcnt(0)
	s_setprio 1
	s_barrier
; #define PG8_STAGE(bufoff, gbase, voff) do { _Pragma("unroll") for (int _i = 0; _i < 2; ++_i) \
;         __builtin_amdgcn_global_load_lds((const unsigned*)((const char*)(gbase) + (voff)[_i]), (LAS unsigned*)(lds + (bufoff) + ldsw + _i * 8192), 16, 0, 0); } while (0)
; #define PG8_LDA(dst, b, h) do { _Pragma("unroll") for (int m = 0; m < 4; ++m) _Pragma("unroll") for (int k = 0; k < 2; ++k) dst[m][k] = *(const LAS bf16x8*)(lds + PG8_SA(b, h) + aoff + m * 2048 + k * 1024); } while (0)
; #define PG8_LDB(dst, b, h) do { _Pragma("unroll") for (int n = 0; n < 2; ++n) _Pragma("unroll") for (int k = 0; k < 2; ++k) dst[n][k] = *(const LAS bf16x8*)(lds + PG8_SB(b, h) + boff + n * 2048 + k * 1024); } while (0)
; #define PG8_WAIT_V(n) asm volatile("s_waitcnt vmcnt(" #n ")" ::: "memory")
; #define PG8_WAIT_L(n) asm volatile("s_waitcnt lgkmcnt(" #n ")" ::: "memory")
; #define PG8_BAR __builtin_amdgcn_s_barrier()
; #define PG8_SCHED __builtin_amdgcn_sched_barrier(0)
; template <class Epi, class Sched>
; DI void gemm_phase(LAS unsigned char* lds, const Sched& S, const Epi& E) {
;     ...
;     for (int t = 0; t < nt; t += 2) {
;       const bool last = (t == nt - 2);
;       const char* a1 = cA + (size_t)(t + 1) * kstep;
;       const char* a2 = last ? nA : cA + (size_t)(t + 2) * kstep; const char* b2 = last ? nB : cB + (size_t)(t + 2) * kstep;
;       const char* a3 = a2 + kstep; const char* b3 = b2 + kstep;
;       PG8_LDB(B0, 0, 0); PG8_LDB(B1, 0, 1); PG8_SCHED; PG8_LDA(At, 0, 0); PG8_STAGE(PG8_SA(1, 1), a1 + hstep, voffA);
;       PG8_WAIT_V(8); PG8_WAIT_L(0); PG8_BAR; PG8_MMA(0, 0, At, B0); PG8_MMA(0, 1, At, B1); PG8_BAR; PG8_SCHED;
;       PG8_LDA(At, 0, 1); PG8_STAGE(PG8_SB(0, 0), b2, voffB); PG8_STAGE(PG8_SB(0, 1), b2 + hstep, voffB); PG8_STAGE(PG8_SA(0, 0), a2, voffA);
;       PG8_WAIT_V(8); PG8_WAIT_L(0); PG8_BAR; PG8_MMA(1, 0, At, B0); PG8_MMA(1, 1, At, B1); PG8_BAR; PG8_SCHED;
;       PG8_LDB(B0, 1, 0); PG8_LDB(B1, 1, 1); PG8_SCHED; PG8_LDA(At, 1, 0); PG8_STAGE(PG8_SA(0, 1), a2 + hstep, voffA);
;       PG8_WAIT_V(8); PG8_WAIT_L(0); PG8_BAR; PG8_MMA(0, 0, At, B0); PG8_MMA(0, 1, At, B1); PG8_BAR; PG8_SCHED;
;       PG8_LDA(At, 1, 1); PG8_STAGE(PG8_SB(1, 0), b3, voffB); PG8_STAGE(PG8_SB(1, 1), b3 + hstep, voffB); PG8_STAGE(PG8_SA(1, 0), a3, voffA);
;       PG8_WAIT_V(8); PG8_WAIT_L(0); PG8_BAR; PG8_MMA(1, 0, At, B0); PG8_MMA(1, 1, At, B1); PG8_BAR; PG8_SCHED;
;     }
	v_mfma_f32_16x16x32_bf16 v[60:63], v[138:141], v[174:177], v[60:63]
	v_mfma_f32_16x16x32_bf16 v[56:59], v[150:153], v[174:177], v[56:59]
	v_mfma_f32_16x16x32_bf16 v[44:47], v[138:141], v[182:185], v[44:47]
	v_mfma_f32_16x16x32_bf16 v[40:43], v[150:153], v[182:185], v[40:43]
	v_mfma_f32_16x16x32_bf16 v[28:31], v[138:141], v[190:193], v[28:31]
	v_mfma_f32_16x16x32_bf16 v[24:27], v[150:153], v[190:193], v[24:27]
	v_mfma_f32_16x16x32_bf16 v[12:15], v[138:141], v[198:201], v[12:15]
	v_mfma_f32_16x16x32_bf16 v[8:11], v[150:153], v[198:201], v[8:11]
	v_mfma_f32_16x16x32_bf16 v[60:63], v[146:149], v[178:181], v[60:63]
	v_mfma_f32_16x16x32_bf16 v[56:59], v[154:157], v[178:181], v[56:59]
	v_mfma_f32_16x16x32_bf16 v[44:47], v[146:149], v[186:189], v[44:47]
	v_mfma_f32_16x16x32_bf16 v[40:43], v[154:157], v[186:189], v[40:43]
	v_mfma_f32_16x16x32_bf16 v[28:31], v[146:149], v[194:197], v[28:31]
	v_mfma_f32_16x16x32_bf16 v[24:27], v[154:157], v[194:197], v[24:27]
	v_mfma_f32_16x16x32_bf16 v[12:15], v[146:149], v[202:205], v[12:15]
	v_mfma_f32_16x16x32_bf16 v[8:11], v[154:157], v[202:205], v[8:11]
	v_mfma_f32_16x16x32_bf16 v[52:55], v[158:161], v[174:177], v[52:55]
	v_mfma_f32_16x16x32_bf16 v[48:51], v[166:169], v[174:177], v[48:51]
	v_mfma_f32_16x16x32_bf16 v[36:39], v[158:161], v[182:185], v[36:39]
	v_mfma_f32_16x16x32_bf16 v[32:35], v[166:169], v[182:185], v[32:35]
	v_mfma_f32_16x16x32_bf16 v[20:23], v[158:161], v[190:193], v[20:23]
	v_mfma_f32_16x16x32_bf16 v[16:19], v[166:169], v[190:193], v[16:19]
	v_mfma_f32_16x16x32_bf16 v[4:7], v[158:161], v[198:201], v[4:7]
	v_mfma_f32_16x16x32_bf16 v[0:3], v[166:169], v[198:201], v[0:3]
	v_mfma_f32_16x16x32_bf16 v[52:55], v[162:165], v[178:181], v[52:55]
	v_mfma_f32_16x16x32_bf16 v[48:51], v[170:173], v[178:181], v[48:51]
	v_mfma_f32_16x16x32_bf16 v[36:39], v[162:165], v[186:189], v[36:39]
	v_mfma_f32_16x16x32_bf16 v[32:35], v[170:173], v[186:189], v[32:35]
	v_mfma_f32_16x16x32_bf16 v[20:23], v[162:165], v[194:197], v[20:23]
	v_mfma_f32_16x16x32_bf16 v[16:19], v[170:173], v[194:197], v[16:19]
	v_mfma_f32_16x16x32_bf16 v[4:7], v[162:165], v[202:205], v[4:7]
	v_mfma_f32_16x16x32_bf16 v[0:3], v[170:173], v[202:205], v[0:3]
	s_barrier
	s_setprio 0
	s_add_i32 s67, 0, 0x18000
	s_add_i32 s72, 0, 0x1c000
	v_add_u32_e32 v154, s67, v143
	v_add_u32_e32 v170, s72, v143
	ds_read_b128 v[138:141], v154
	ds_read_b128 v[146:149], v154 offset:1024
	ds_read_b128 v[150:153], v154 offset:2048
	ds_read_b128 v[154:157], v154 offset:3072
	ds_read_b128 v[158:161], v170
	ds_read_b128 v[162:165], v170 offset:1024
	ds_read_b128 v[166:169], v170 offset:2048
	ds_read_b128 v[170:173], v170 offset:3072
	s_add_u32 s26, s26, 0x80000
	s_addc_u32 s27, s27, 0
	s_mov_b32 m0, s51
	v_lshl_add_u64 v[216:217], s[26:27], 0, v[128:129]
	ds_read_b128 v[174:177], v145 offset:32768
	ds_read_b128 v[178:181], v145 offset:33792
	ds_read_b128 v[182:185], v145 offset:34816
	ds_read_b128 v[186:189], v145 offset:35840
	ds_read_b128 v[190:193], v145 offset:36864
	ds_read_b128 v[194:197], v145 offset:37888
	ds_read_b128 v[198:201], v145 offset:38912
	ds_read_b128 v[202:205], v145 offset:39936
	global_load_lds_dwordx4 v[216:217], off
	v_lshl_add_u64 v[216:217], s[26:27], 0, v[130:131]
	s_mov_b32 m0, s57
	s_nop 0
	global_load_lds_dwordx4 v[216:217], off
	s_waitcnt vmcnt(8) lgkmcnt(0)
	s_setprio 1
	s_barrier
	v_mfma_f32_16x16x32_bf16 v[124:127], v[138:141], v[174:177], v[124:127]
	v_mfma_f32_16x16x32_bf16 v[120:123], v[150:153], v[174:177], v[120:123]
	v_mfma_f32_16x16x32_bf16 v[108:111], v[138:141], v[182:185], v[108:111]
	v_mfma_f32_16x16x32_bf16 v[104:107], v[150:153], v[182:185], v[104:107]
	v_mfma_f32_16x16x32_bf16 v[92:95], v[138:141], v[190:193], v[92:95]
	v_mfma_f32_16x16x32_bf16 v[88:91], v[150:153], v[190:193], v[88:91]
	v_mfma_f32_16x16x32_bf16 v[76:79], v[138:141], v[198:201], v[76:79]
	v_mfma_f32_16x16x32_bf16 v[72:75], v[150:153], v[198:201], v[72:75]
	v_mfma_f32_16x16x32_bf16 v[124:127], v[146:149], v[178:181], v[124:127]
	v_mfma_f32_16x16x32_bf16 v[120:123], v[154:157], v[178:181], v[120:123]
	v_mfma_f32_16x16x32_bf16 v[108:111], v[146:149], v[186:189], v[108:111]
	v_mfma_f32_16x16x32_bf16 v[104:107], v[154:157], v[186:189], v[104:107]
	v_mfma_f32_16x16x32_bf16 v[92:95], v[146:149], v[194:197], v[92:95]
	v_mfma_f32_16x16x32_bf16 v[88:91], v[154:157], v[194:197], v[88:91]
	v_mfma_f32_16x16x32_bf16 v[76:79], v[146:149], v[202:205], v[76:79]
	v_mfma_f32_16x16x32_bf16 v[72:75], v[154:157], v[202:205], v[72:75]
	v_mfma_f32_16x16x32_bf16 v[116:119], v[158:161], v[174:177], v[116:119]
	v_mfma_f32_16x16x32_bf16 v[112:115], v[166:169], v[174:177], v[112:115]
	v_mfma_f32_16x16x32_bf16 v[100:103], v[158:161], v[182:185], v[100:103]
	v_mfma_f32_16x16x32_bf16 v[96:99], v[166:169], v[182:185], v[96:99]
	v_mfma_f32_16x16x32_bf16 v[84:87], v[158:161], v[190:193], v[84:87]
	v_mfma_f32_16x16x32_bf16 v[80:83], v[166:169], v[190:193], v[80:83]
	v_mfma_f32_16x16x32_bf16 v[68:71], v[158:161], v[198:201], v[68:71]
	v_mfma_f32_16x16x32_bf16 v[64:67], v[166:169], v[198:201], v[64:67]
	v_mfma_f32_16x16x32_bf16 v[116:119], v[162:165], v[178:181], v[116:119]
	v_mfma_f32_16x16x32_bf16 v[112:115], v[170:173], v[178:181], v[112:115]
	v_mfma_f32_16x16x32_bf16 v[100:103], v[162:165], v[186:189], v[100:103]
	v_mfma_f32_16x16x32_bf16 v[96:99], v[170:173], v[186:189], v[96:99]
	v_mfma_f32_16x16x32_bf16 v[84:87], v[162:165], v[194:197], v[84:87]
	v_mfma_f32_16x16x32_bf16 v[80:83], v[170:173], v[194:197], v[80:83]
	v_mfma_f32_16x16x32_bf16 v[68:71], v[162:165], v[202:205], v[68:71]
	v_mfma_f32_16x16x32_bf16 v[64:67], v[170:173], v[202:205], v[64:67]
	s_barrier
; #define PG8_STAGE(bufoff, gbase, voff) do { _Pragma("unroll") for (int _i = 0; _i < 2; ++_i) \
;         __builtin_amdgcn_global_load_lds((const unsigned*)((const char*)(gbase) + (voff)[_i]), (LAS unsigned*)(lds + (bufoff) + ldsw + _i * 8192), 16, 0, 0); } while (0)
; #define PG8_LDA(dst, b, h) do { _Pragma("unroll") for (int m = 0; m < 4; ++m) _Pragma("unroll") for (int k = 0; k < 2; ++k) dst[m][k] = *(const LAS bf16x8*)(lds + PG8_SA(b, h) + aoff + m * 2048 + k * 1024); } while (0)
; #define PG8_LDB(dst, b, h) do { _Pragma("unroll") for (int n = 0; n < 2; ++n) _Pragma("unroll") for (int k = 0; k < 2; ++k) dst[n][k] = *(const LAS bf16x8*)(lds + PG8_SB(b, h) + boff + n * 2048 + k * 1024); } while (0)
; #define PG8_WAIT_V(n) asm volatile("s_waitcnt vmcnt(" #n ")" ::: "memory")
; #define PG8_WAIT_L(n) asm volatile("s_waitcnt lgkmcnt(" #n ")" ::: "memory")
; #define PG8_BAR __builtin_amdgcn_s_barrier()
; template <class Epi, class Sched>
; DI void gemm_phase(LAS unsigned char* lds, const Sched& S, const Epi& E) {
;     ...
;     for (int t = 0; t < nt; t += 2) {
;       const bool last = (t == nt - 2);
;       const char* a1 = cA + (size_t)(t + 1) * kstep;
;       const char* a2 = last ? nA : cA + (size_t)(t + 2) * kstep; const char* b2 = last ? nB : cB + (size_t)(t + 2) * kstep;
;       const char* a3 = a2 + kstep; const char* b3 = b2 + kstep;
;       PG8_LDB(B0, 0, 0); PG8_LDB(B1, 0, 1); PG8_SCHED; PG8_LDA(At, 0, 0); PG8_STAGE(PG8_SA(1, 1), a1 + hstep, voffA);
;       PG8_WAIT_V(8); PG8_WAIT_L(0); PG8_BAR; PG8_MMA(0, 0, At, B0); PG8_MMA(0, 1, At, B1); PG8_BAR; PG8_SCHED;
;       PG8_LDA(At, 0, 1); PG8_STAGE(PG8_SB(0, 0), b2, voffB); PG8_STAGE(PG8_SB(0, 1), b2 + hstep, voffB); PG8_STAGE(PG8_SA(0, 0), a2, voffA);
;       PG8_WAIT_V(8); PG8_WAIT_L(0); PG8_BAR; PG8_MMA(1, 0, At, B0); PG8_MMA(1, 1, At, B1); PG8_BAR; PG8_SCHED;
;       PG8_LDB(B0, 1, 0); PG8_LDB(B1, 1, 1); PG8_SCHED; PG8_LDA(At, 1, 0); PG8_STAGE(PG8_SA(0, 1), a2 + hstep, voffA);
;       PG8_WAIT_V(8); PG8_WAIT_L(0); PG8_BAR; PG8_MMA(0, 0, At, B0); PG8_MMA(0, 1, At, B1); PG8_BAR; PG8_SCHED;
;       PG8_LDA(At, 1, 1); PG8_STAGE(PG8_SB(1, 0), b3, voffB); PG8_STAGE(PG8_SB(1, 1), b3 + hstep, voffB); PG8_STAGE(PG8_SA(1, 0), a3, voffA);
;       PG8_WAIT_V(8); PG8_WAIT_L(0); PG8_BAR; PG8_MMA(1, 0, At, B0); PG8_MMA(1, 1, At, B1); PG8_BAR; PG8_SCHED;
;     }
;     if (wr == 0) PG8_BAR;
	s_setprio 0
	s_add_i32 s26, s67, s10
	v_lshl_add_u64 v[206:207], v[206:207], 0, s[6:7]
	s_mov_b32 m0, s26
	ds_read_b128 v[174:177], v145 offset:49152
	ds_read_b128 v[178:181], v145 offset:50176
	ds_read_b128 v[182:185], v145 offset:51200
	ds_read_b128 v[186:189], v145 offset:52224
	ds_read_b128 v[190:193], v145 offset:53248
	ds_read_b128 v[194:197], v145 offset:54272
	ds_read_b128 v[198:201], v145 offset:55296
	ds_read_b128 v[202:205], v145 offset:56320
	global_load_lds_dwordx4 v[206:207], off
	s_add_i32 m0, s26, 0x2000
	s_add_u32 s22, s22, 0x80080
	v_lshl_add_u64 v[206:207], v[210:211], 0, s[6:7]
	s_addc_u32 s23, s23, 0
	s_add_i32 s26, s72, s10
	global_load_lds_dwordx4 v[206:207], off
	v_lshl_add_u64 v[206:207], s[22:23], 0, v[208:209]
	s_mov_b32 m0, s26
	s_nop 0
	global_load_lds_dwordx4 v[206:207], off
	v_lshl_add_u64 v[206:207], s[22:23], 0, v[132:133]
	s_add_i32 m0, s26, 0x2000
	s_nop 0
	global_load_lds_dwordx4 v[206:207], off
	v_lshl_add_u64 v[206:207], v[212:213], 0, s[6:7]
	s_mov_b32 m0, s62
	s_nop 0
	global_load_lds_dwordx4 v[206:207], off
	v_lshl_add_u64 v[206:207], v[214:215], 0, s[6:7]
	s_mov_b32 m0, s63
	s_nop 0
	global_load_lds_dwordx4 v[206:207], off
	s_waitcnt vmcnt(8) lgkmcnt(0)
	s_setprio 1
	s_barrier
	v_mfma_f32_16x16x32_bf16 v[60:63], v[138:141], v[174:177], v[60:63]
	v_mfma_f32_16x16x32_bf16 v[56:59], v[150:153], v[174:177], v[56:59]
	v_mfma_f32_16x16x32_bf16 v[44:47], v[138:141], v[182:185], v[44:47]
	v_mfma_f32_16x16x32_bf16 v[40:43], v[150:153], v[182:185], v[40:43]
	v_mfma_f32_16x16x32_bf16 v[28:31], v[138:141], v[190:193], v[28:31]
	v_mfma_f32_16x16x32_bf16 v[24:27], v[150:153], v[190:193], v[24:27]
	v_mfma_f32_16x16x32_bf16 v[12:15], v[138:141], v[198:201], v[12:15]
	v_mfma_f32_16x16x32_bf16 v[8:11], v[150:153], v[198:201], v[8:11]
	v_mfma_f32_16x16x32_bf16 v[60:63], v[146:149], v[178:181], v[60:63]
	v_mfma_f32_16x16x32_bf16 v[56:59], v[154:157], v[178:181], v[56:59]
	v_mfma_f32_16x16x32_bf16 v[44:47], v[146:149], v[186:189], v[44:47]
	v_mfma_f32_16x16x32_bf16 v[40:43], v[154:157], v[186:189], v[40:43]
	v_mfma_f32_16x16x32_bf16 v[28:31], v[146:149], v[194:197], v[28:31]
	v_mfma_f32_16x16x32_bf16 v[24:27], v[154:157], v[194:197], v[24:27]
	v_mfma_f32_16x16x32_bf16 v[12:15], v[146:149], v[202:205], v[12:15]
	v_mfma_f32_16x16x32_bf16 v[8:11], v[154:157], v[202:205], v[8:11]
	v_mfma_f32_16x16x32_bf16 v[52:55], v[158:161], v[174:177], v[52:55]
	v_mfma_f32_16x16x32_bf16 v[48:51], v[166:169], v[174:177], v[48:51]
	v_mfma_f32_16x16x32_bf16 v[36:39], v[158:161], v[182:185], v[36:39]
	v_mfma_f32_16x16x32_bf16 v[32:35], v[166:169], v[182:185], v[32:35]
	v_mfma_f32_16x16x32_bf16 v[20:23], v[158:161], v[190:193], v[20:23]
	v_mfma_f32_16x16x32_bf16 v[16:19], v[166:169], v[190:193], v[16:19]
	v_mfma_f32_16x16x32_bf16 v[4:7], v[158:161], v[198:201], v[4:7]
	v_mfma_f32_16x16x32_bf16 v[0:3], v[166:169], v[198:201], v[0:3]
	v_mfma_f32_16x16x32_bf16 v[52:55], v[162:165], v[178:181], v[52:55]
	v_mfma_f32_16x16x32_bf16 v[48:51], v[170:173], v[178:181], v[48:51]
	v_mfma_f32_16x16x32_bf16 v[36:39], v[162:165], v[186:189], v[36:39]
	v_mfma_f32_16x16x32_bf16 v[32:35], v[170:173], v[186:189], v[32:35]
	v_mfma_f32_16x16x32_bf16 v[20:23], v[162:165], v[194:197], v[20:23]
	v_mfma_f32_16x16x32_bf16 v[16:19], v[170:173], v[194:197], v[16:19]
	v_mfma_f32_16x16x32_bf16 v[4:7], v[162:165], v[202:205], v[4:7]
	v_mfma_f32_16x16x32_bf16 v[0:3], v[170:173], v[202:205], v[0:3]
	s_barrier
	s_setprio 0
	s_add_i32 s66, s66, 2
	s_add_u32 s58, s58, 0x100
	s_addc_u32 s59, s59, 0
	s_add_u32 s44, s44, 0x100
	s_addc_u32 s45, s45, 0
	s_cmp_gt_u32 s66, 29
	s_cbranch_scc0 .LBB0_744
	s_and_b64 vcc, exec, s[38:39]
	s_cbranch_vccz .LBB0_747
	s_barrier

; #define PG8_STAGE(bufoff, gbase, voff) do { _Pragma("unroll") for (int _i = 0; _i < 2; ++_i) \
;         __builtin_amdgcn_global_load_lds((const unsigned*)((const char*)(gbase) + (voff)[_i]), (LAS unsigned*)(lds + (bufoff) + ldsw + _i * 8192), 16, 0, 0); } while (0)
; #define PG8_LDA(dst, b, h) do { _Pragma("unroll") for (int m = 0; m < 4; ++m) _Pragma("unroll") for (int k = 0; k < 2; ++k) dst[m][k] = *(const LAS bf16x8*)(lds + PG8_SA(b, h) + aoff + m * 2048 + k * 1024); } while (0)
; #define PG8_LDB(dst, b, h) do { _Pragma("unroll") for (int n = 0; n < 2; ++n) _Pragma("unroll") for (int k = 0; k < 2; ++k) dst[n][k] = *(const LAS bf16x8*)(lds + PG8_SB(b, h) + boff + n * 2048 + k * 1024); } while (0)
; #define PG8_WAIT_V(n) asm volatile("s_waitcnt vmcnt(" #n ")" ::: "memory")
; #define PG8_WAIT_L(n) asm volatile("s_waitcnt lgkmcnt(" #n ")" ::: "memory")
; #define PG8_BAR __builtin_amdgcn_s_barrier()
; #define PG8_SCHED __builtin_amdgcn_sched_barrier(0)
; template <class Epi, class Sched>
; DI void gemm_phase(LAS unsigned char* lds, const Sched& S, const Epi& E) {
;     ...
;     for (int t = 0; t < nt; t += 2) {
;       const bool last = (t == nt - 2);
;       const char* a1 = cA + (size_t)(t + 1) * kstep;
;       const char* a2 = last ? nA : cA + (size_t)(t + 2) * kstep; const char* b2 = last ? nB : cB + (size_t)(t + 2) * kstep;
;       const char* a3 = a2 + kstep; const char* b3 = b2 + kstep;
;       PG8_LDB(B0, 0, 0); PG8_LDB(B1, 0, 1); PG8_SCHED; PG8_LDA(At, 0, 0); PG8_STAGE(PG8_SA(1, 1), a1 + hstep, voffA);
;       PG8_WAIT_V(8); PG8_WAIT_L(0); PG8_BAR; PG8_MMA(0, 0, At, B0); PG8_MMA(0, 1, At, B1); PG8_BAR; PG8_SCHED;
;       PG8_LDA(At, 0, 1); PG8_STAGE(PG8_SB(0, 0), b2, voffB); PG8_STAGE(PG8_SB(0, 1), b2 + hstep, voffB); PG8_STAGE(PG8_SA(0, 0), a2, voffA);
;       PG8_WAIT_V(8); PG8_WAIT_L(0); PG8_BAR; PG8_MMA(1, 0, At, B0); PG8_MMA(1, 1, At, B1); PG8_BAR; PG8_SCHED;
;       PG8_LDB(B0, 1, 0); PG8_LDB(B1, 1, 1); PG8_SCHED; PG8_LDA(At, 1, 0); PG8_STAGE(PG8_SA(0, 1), a2 + hstep, voffA);
;       PG8_WAIT_V(8); PG8_WAIT_L(0); PG8_BAR; PG8_MMA(0, 0, At, B0); PG8_MMA(0, 1, At, B1); PG8_BAR; PG8_SCHED;
;       PG8_LDA(At, 1, 1); PG8_STAGE(PG8_SB(1, 0), b3, voffB); PG8_STAGE(PG8_SB(1, 1), b3 + hstep, voffB); PG8_STAGE(PG8_SA(1, 0), a3, voffA);
;       PG8_WAIT_V(8); PG8_WAIT_L(0); PG8_BAR; PG8_MMA(1, 0, At, B0); PG8_MMA(1, 1, At, B1); PG8_BAR; PG8_SCHED;
;     }
.LBB0_790:
	s_add_u32 s22, s24, 0xfffc0080
	s_addc_u32 s23, s25, -1
	s_add_i32 s63, 0, 0x10000
	s_cmp_eq_u32 s62, 12
	s_cselect_b32 s27, s39, s23
	s_cselect_b32 s26, s49, s22
	s_cselect_b32 s23, s43, s61
	s_cselect_b32 s22, s47, s60
	s_add_i32 s66, 0, 0x14000
	v_add_u32_e32 v140, s63, v219
	v_add_u32_e32 v156, s66, v219
	ds_read_b128 v[128:131], v140
	ds_read_b128 v[132:135], v140 offset:1024
	ds_read_b128 v[136:139], v140 offset:2048
	ds_read_b128 v[140:143], v140 offset:3072
	ds_read_b128 v[144:147], v156
	ds_read_b128 v[148:151], v156 offset:1024
	ds_read_b128 v[152:155], v156 offset:2048
	ds_read_b128 v[156:159], v156 offset:3072
	v_lshl_add_u64 v[202:203], s[24:25], 0, v[198:199]
	s_add_i32 m0, s44, 0xc000
	ds_read_b128 v[160:163], v221
	ds_read_b128 v[164:167], v221 offset:1024
	ds_read_b128 v[168:171], v221 offset:2048
	ds_read_b128 v[172:175], v221 offset:3072
	ds_read_b128 v[176:179], v221 offset:4096
	ds_read_b128 v[180:183], v221 offset:5120
	ds_read_b128 v[184:187], v221 offset:6144
	ds_read_b128 v[188:191], v221 offset:7168
	global_load_lds_dwordx4 v[202:203], off
	v_lshl_add_u64 v[202:203], s[24:25], 0, v[200:201]
	s_add_i32 m0, s44, 0xe000
	s_nop 0
	global_load_lds_dwordx4 v[202:203], off
	s_waitcnt vmcnt(8) lgkmcnt(0)
	s_setprio 1
	s_barrier
	v_mfma_f32_16x16x32_bf16 v[124:127], v[128:131], v[160:163], v[124:127]
	v_mfma_f32_16x16x32_bf16 v[120:123], v[136:139], v[160:163], v[120:123]
	v_mfma_f32_16x16x32_bf16 v[116:119], v[128:131], v[168:171], v[116:119]
	v_mfma_f32_16x16x32_bf16 v[112:115], v[136:139], v[168:171], v[112:115]
	v_mfma_f32_16x16x32_bf16 v[108:111], v[128:131], v[176:179], v[108:111]
	v_mfma_f32_16x16x32_bf16 v[104:107], v[136:139], v[176:179], v[104:107]
	v_mfma_f32_16x16x32_bf16 v[100:103], v[128:131], v[184:187], v[100:103]
	v_mfma_f32_16x16x32_bf16 v[96:99], v[136:139], v[184:187], v[96:99]
	v_mfma_f32_16x16x32_bf16 v[124:127], v[132:135], v[164:167], v[124:127]
	v_mfma_f32_16x16x32_bf16 v[120:123], v[140:143], v[164:167], v[120:123]
	v_mfma_f32_16x16x32_bf16 v[116:119], v[132:135], v[172:175], v[116:119]
	v_mfma_f32_16x16x32_bf16 v[112:115], v[140:143], v[172:175], v[112:115]
	v_mfma_f32_16x16x32_bf16 v[108:111], v[132:135], v[180:183], v[108:111]
	v_mfma_f32_16x16x32_bf16 v[104:107], v[140:143], v[180:183], v[104:107]
	v_mfma_f32_16x16x32_bf16 v[100:103], v[132:135], v[188:191], v[100:103]
	v_mfma_f32_16x16x32_bf16 v[96:99], v[140:143], v[188:191], v[96:99]
	v_mfma_f32_16x16x32_bf16 v[92:95], v[144:147], v[160:163], v[92:95]
	v_mfma_f32_16x16x32_bf16 v[88:91], v[152:155], v[160:163], v[88:91]
	v_mfma_f32_16x16x32_bf16 v[84:87], v[144:147], v[168:171], v[84:87]
	v_mfma_f32_16x16x32_bf16 v[80:83], v[152:155], v[168:171], v[80:83]
	v_mfma_f32_16x16x32_bf16 v[76:79], v[144:147], v[176:179], v[76:79]
	v_mfma_f32_16x16x32_bf16 v[72:75], v[152:155], v[176:179], v[72:75]
	v_mfma_f32_16x16x32_bf16 v[68:71], v[144:147], v[184:187], v[68:71]
	v_mfma_f32_16x16x32_bf16 v[64:67], v[152:155], v[184:187], v[64:67]
	v_mfma_f32_16x16x32_bf16 v[92:95], v[148:151], v[164:167], v[92:95]
	v_mfma_f32_16x16x32_bf16 v[88:91], v[156:159], v[164:167], v[88:91]
	v_mfma_f32_16x16x32_bf16 v[84:87], v[148:151], v[172:175], v[84:87]
	v_mfma_f32_16x16x32_bf16 v[80:83], v[156:159], v[172:175], v[80:83]
	v_mfma_f32_16x16x32_bf16 v[76:79], v[148:151], v[180:183], v[76:79]
	v_mfma_f32_16x16x32_bf16 v[72:75], v[156:159], v[180:183], v[72:75]
	v_mfma_f32_16x16x32_bf16 v[68:71], v[148:151], v[188:191], v[68:71]
	v_mfma_f32_16x16x32_bf16 v[64:67], v[156:159], v[188:191], v[64:67]
	s_barrier
	s_setprio 0
	s_add_i32 s63, s63, s12
	v_lshl_add_u64 v[202:203], s[22:23], 0, v[208:209]
	s_mov_b32 m0, s63
	ds_read_b128 v[160:163], v221 offset:16384
	ds_read_b128 v[164:167], v221 offset:17408
	ds_read_b128 v[168:171], v221 offset:18432
	ds_read_b128 v[172:175], v221 offset:19456
	ds_read_b128 v[176:179], v221 offset:20480
	ds_read_b128 v[180:183], v221 offset:21504
	ds_read_b128 v[184:187], v221 offset:22528
	ds_read_b128 v[188:191], v221 offset:23552
	global_load_lds_dwordx4 v[202:203], off
	s_add_i32 m0, s63, 0x2000
	s_add_u32 s64, s22, 0x40000
	v_lshl_add_u64 v[204:205], s[22:23], 0, v[196:197]
	s_addc_u32 s65, s23, 0
	s_add_i32 s63, s66, s12
	global_load_lds_dwordx4 v[204:205], off
	v_lshl_add_u64 v[206:207], s[64:65], 0, v[208:209]
	s_mov_b32 m0, s63
	v_lshl_add_u64 v[210:211], s[26:27], 0, v[194:195]
	global_load_lds_dwordx4 v[206:207], off
	v_lshl_add_u64 v[206:207], s[64:65], 0, v[196:197]
	s_add_i32 m0, s63, 0x2000
	s_nop 0
	global_load_lds_dwordx4 v[206:207], off
	v_lshl_add_u64 v[206:207], s[26:27], 0, v[192:193]
	s_mov_b32 m0, s44
	s_nop 0
	global_load_lds_dwordx4 v[206:207], off
	s_mov_b32 m0, s45
	s_nop 0
	global_load_lds_dwordx4 v[210:211], off
	s_waitcnt vmcnt(8) lgkmcnt(0)
	s_setprio 1
	s_barrier
; #define PG8_STAGE(bufoff, gbase, voff) do { _Pragma("unroll") for (int _i = 0; _i < 2; ++_i) \
;         __builtin_amdgcn_global_load_lds((const unsigned*)((const char*)(gbase) + (voff)[_i]), (LAS unsigned*)(lds + (bufoff) + ldsw + _i * 8192), 16, 0, 0); } while (0)
; #define PG8_LDA(dst, b, h) do { _Pragma("unroll") for (int m = 0; m < 4; ++m) _Pragma("unroll") for (int k = 0; k < 2; ++k) dst[m][k] = *(const LAS bf16x8*)(lds + PG8_SA(b, h) + aoff + m * 2048 + k * 1024); } while (0)
; #define PG8_LDB(dst, b, h) do { _Pragma("unroll") for (int n = 0; n < 2; ++n) _Pragma("unroll") for (int k = 0; k < 2; ++k) dst[n][k] = *(const LAS bf16x8*)(lds + PG8_SB(b, h) + boff + n * 2048 + k * 1024); } while (0)
; #define PG8_WAIT_V(n) asm volatile("s_waitcnt vmcnt(" #n ")" ::: "memory")
; #define PG8_WAIT_L(n) asm volatile("s_waitcnt lgkmcnt(" #n ")" ::: "memory")
; #define PG8_BAR __builtin_amdgcn_s_barrier()
; #define PG8_SCHED __builtin_amdgcn_sched_barrier(0)
; template <class Epi, class Sched>
; DI void gemm_phase(LAS unsigned char* lds, const Sched& S, const Epi& E) {
;     ...
;     for (int t = 0; t < nt; t += 2) {
;       const bool last = (t == nt - 2);
;       const char* a1 = cA + (size_t)(t + 1) * kstep;
;       const char* a2 = last ? nA : cA + (size_t)(t + 2) * kstep; const char* b2 = last ? nB : cB + (size_t)(t + 2) * kstep;
;       const char* a3 = a2 + kstep; const char* b3 = b2 + kstep;
;       PG8_LDB(B0, 0, 0); PG8_LDB(B1, 0, 1); PG8_SCHED; PG8_LDA(At, 0, 0); PG8_STAGE(PG8_SA(1, 1), a1 + hstep, voffA);
;       PG8_WAIT_V(8); PG8_WAIT_L(0); PG8_BAR; PG8_MMA(0, 0, At, B0); PG8_MMA(0, 1, At, B1); PG8_BAR; PG8_SCHED;
;       PG8_LDA(At, 0, 1); PG8_STAGE(PG8_SB(0, 0), b2, voffB); PG8_STAGE(PG8_SB(0, 1), b2 + hstep, voffB); PG8_STAGE(PG8_SA(0, 0), a2, voffA);
;       PG8_WAIT_V(8); PG8_WAIT_L(0); PG8_BAR; PG8_MMA(1, 0, At, B0); PG8_MMA(1, 1, At, B1); PG8_BAR; PG8_SCHED;
;       PG8_LDB(B0, 1, 0); PG8_LDB(B1, 1, 1); PG8_SCHED; PG8_LDA(At, 1, 0); PG8_STAGE(PG8_SA(0, 1), a2 + hstep, voffA);
;       PG8_WAIT_V(8); PG8_WAIT_L(0); PG8_BAR; PG8_MMA(0, 0, At, B0); PG8_MMA(0, 1, At, B1); PG8_BAR; PG8_SCHED;
;       PG8_LDA(At, 1, 1); PG8_STAGE(PG8_SB(1, 0), b3, voffB); PG8_STAGE(PG8_SB(1, 1), b3 + hstep, voffB); PG8_STAGE(PG8_SA(1, 0), a3, voffA);
;       PG8_WAIT_V(8); PG8_WAIT_L(0); PG8_BAR; PG8_MMA(1, 0, At, B0); PG8_MMA(1, 1, At, B1); PG8_BAR; PG8_SCHED;
;     }
	v_mfma_f32_16x16x32_bf16 v[60:63], v[128:131], v[160:163], v[60:63]
	v_mfma_f32_16x16x32_bf16 v[56:59], v[136:139], v[160:163], v[56:59]
	v_mfma_f32_16x16x32_bf16 v[52:55], v[128:131], v[168:171], v[52:55]
	v_mfma_f32_16x16x32_bf16 v[48:51], v[136:139], v[168:171], v[48:51]
	v_mfma_f32_16x16x32_bf16 v[44:47], v[128:131], v[176:179], v[44:47]
	v_mfma_f32_16x16x32_bf16 v[40:43], v[136:139], v[176:179], v[40:43]
	v_mfma_f32_16x16x32_bf16 v[36:39], v[128:131], v[184:187], v[36:39]
	v_mfma_f32_16x16x32_bf16 v[32:35], v[136:139], v[184:187], v[32:35]
	v_mfma_f32_16x16x32_bf16 v[60:63], v[132:135], v[164:167], v[60:63]
	v_mfma_f32_16x16x32_bf16 v[56:59], v[140:143], v[164:167], v[56:59]
	v_mfma_f32_16x16x32_bf16 v[52:55], v[132:135], v[172:175], v[52:55]
	v_mfma_f32_16x16x32_bf16 v[48:51], v[140:143], v[172:175], v[48:51]
	v_mfma_f32_16x16x32_bf16 v[44:47], v[132:135], v[180:183], v[44:47]
	v_mfma_f32_16x16x32_bf16 v[40:43], v[140:143], v[180:183], v[40:43]
	v_mfma_f32_16x16x32_bf16 v[36:39], v[132:135], v[188:191], v[36:39]
	v_mfma_f32_16x16x32_bf16 v[32:35], v[140:143], v[188:191], v[32:35]
	v_mfma_f32_16x16x32_bf16 v[28:31], v[144:147], v[160:163], v[28:31]
	v_mfma_f32_16x16x32_bf16 v[24:27], v[152:155], v[160:163], v[24:27]
	v_mfma_f32_16x16x32_bf16 v[20:23], v[144:147], v[168:171], v[20:23]
	v_mfma_f32_16x16x32_bf16 v[16:19], v[152:155], v[168:171], v[16:19]
	v_mfma_f32_16x16x32_bf16 v[12:15], v[144:147], v[176:179], v[12:15]
	v_mfma_f32_16x16x32_bf16 v[8:11], v[152:155], v[176:179], v[8:11]
	v_mfma_f32_16x16x32_bf16 v[4:7], v[144:147], v[184:187], v[4:7]
	v_mfma_f32_16x16x32_bf16 v[0:3], v[152:155], v[184:187], v[0:3]
	v_mfma_f32_16x16x32_bf16 v[28:31], v[148:151], v[164:167], v[28:31]
	v_mfma_f32_16x16x32_bf16 v[24:27], v[156:159], v[164:167], v[24:27]
	v_mfma_f32_16x16x32_bf16 v[20:23], v[148:151], v[172:175], v[20:23]
	v_mfma_f32_16x16x32_bf16 v[16:19], v[156:159], v[172:175], v[16:19]
	v_mfma_f32_16x16x32_bf16 v[12:15], v[148:151], v[180:183], v[12:15]
	v_mfma_f32_16x16x32_bf16 v[8:11], v[156:159], v[180:183], v[8:11]
	v_mfma_f32_16x16x32_bf16 v[4:7], v[148:151], v[188:191], v[4:7]
	v_mfma_f32_16x16x32_bf16 v[0:3], v[156:159], v[188:191], v[0:3]
	s_barrier
	s_setprio 0
	s_add_i32 s63, 0, 0x18000
	s_add_i32 s64, 0, 0x1c000
	v_add_u32_e32 v140, s63, v219
	v_add_u32_e32 v156, s64, v219
	ds_read_b128 v[128:131], v140
	ds_read_b128 v[132:135], v140 offset:1024
	ds_read_b128 v[136:139], v140 offset:2048
	ds_read_b128 v[140:143], v140 offset:3072
	ds_read_b128 v[144:147], v156
	ds_read_b128 v[148:151], v156 offset:1024
	ds_read_b128 v[152:155], v156 offset:2048
	ds_read_b128 v[156:159], v156 offset:3072
	s_add_u32 s26, s26, 0x40000
	s_addc_u32 s27, s27, 0
	s_mov_b32 m0, s54
	v_lshl_add_u64 v[212:213], s[26:27], 0, v[192:193]
	ds_read_b128 v[160:163], v221 offset:32768
	ds_read_b128 v[164:167], v221 offset:33792
	ds_read_b128 v[168:171], v221 offset:34816
	ds_read_b128 v[172:175], v221 offset:35840
	ds_read_b128 v[176:179], v221 offset:36864
	ds_read_b128 v[180:183], v221 offset:37888
	ds_read_b128 v[184:187], v221 offset:38912
	ds_read_b128 v[188:191], v221 offset:39936
	global_load_lds_dwordx4 v[212:213], off
	v_lshl_add_u64 v[212:213], s[26:27], 0, v[194:195]
	s_mov_b32 m0, s55
	s_nop 0
	global_load_lds_dwordx4 v[212:213], off
	s_waitcnt vmcnt(8) lgkmcnt(0)
	s_setprio 1
	s_barrier
	v_mfma_f32_16x16x32_bf16 v[124:127], v[128:131], v[160:163], v[124:127]
	v_mfma_f32_16x16x32_bf16 v[120:123], v[136:139], v[160:163], v[120:123]
	v_mfma_f32_16x16x32_bf16 v[116:119], v[128:131], v[168:171], v[116:119]
	v_mfma_f32_16x16x32_bf16 v[112:115], v[136:139], v[168:171], v[112:115]
	v_mfma_f32_16x16x32_bf16 v[108:111], v[128:131], v[176:179], v[108:111]
	v_mfma_f32_16x16x32_bf16 v[104:107], v[136:139], v[176:179], v[104:107]
	v_mfma_f32_16x16x32_bf16 v[100:103], v[128:131], v[184:187], v[100:103]
	v_mfma_f32_16x16x32_bf16 v[96:99], v[136:139], v[184:187], v[96:99]
	v_mfma_f32_16x16x32_bf16 v[124:127], v[132:135], v[164:167], v[124:127]
	v_mfma_f32_16x16x32_bf16 v[120:123], v[140:143], v[164:167], v[120:123]
	v_mfma_f32_16x16x32_bf16 v[116:119], v[132:135], v[172:175], v[116:119]
	v_mfma_f32_16x16x32_bf16 v[112:115], v[140:143], v[172:175], v[112:115]
	v_mfma_f32_16x16x32_bf16 v[108:111], v[132:135], v[180:183], v[108:111]
	v_mfma_f32_16x16x32_bf16 v[104:107], v[140:143], v[180:183], v[104:107]
	v_mfma_f32_16x16x32_bf16 v[100:103], v[132:135], v[188:191], v[100:103]
	v_mfma_f32_16x16x32_bf16 v[96:99], v[140:143], v[188:191], v[96:99]
	v_mfma_f32_16x16x32_bf16 v[92:95], v[144:147], v[160:163], v[92:95]
	v_mfma_f32_16x16x32_bf16 v[88:91], v[152:155], v[160:163], v[88:91]
	v_mfma_f32_16x16x32_bf16 v[84:87], v[144:147], v[168:171], v[84:87]
	v_mfma_f32_16x16x32_bf16 v[80:83], v[152:155], v[168:171], v[80:83]
	v_mfma_f32_16x16x32_bf16 v[76:79], v[144:147], v[176:179], v[76:79]
	v_mfma_f32_16x16x32_bf16 v[72:75], v[152:155], v[176:179], v[72:75]
	v_mfma_f32_16x16x32_bf16 v[68:71], v[144:147], v[184:187], v[68:71]
	v_mfma_f32_16x16x32_bf16 v[64:67], v[152:155], v[184:187], v[64:67]
	v_mfma_f32_16x16x32_bf16 v[92:95], v[148:151], v[164:167], v[92:95]
	v_mfma_f32_16x16x32_bf16 v[88:91], v[156:159], v[164:167], v[88:91]
	v_mfma_f32_16x16x32_bf16 v[84:87], v[148:151], v[172:175], v[84:87]
	v_mfma_f32_16x16x32_bf16 v[80:83], v[156:159], v[172:175], v[80:83]
	v_mfma_f32_16x16x32_bf16 v[76:79], v[148:151], v[180:183], v[76:79]
	v_mfma_f32_16x16x32_bf16 v[72:75], v[156:159], v[180:183], v[72:75]
	v_mfma_f32_16x16x32_bf16 v[68:71], v[148:151], v[188:191], v[68:71]
	v_mfma_f32_16x16x32_bf16 v[64:67], v[156:159], v[188:191], v[64:67]
	s_barrier
; #define PG8_STAGE(bufoff, gbase, voff) do { _Pragma("unroll") for (int _i = 0; _i < 2; ++_i) \
;         __builtin_amdgcn_global_load_lds((const unsigned*)((const char*)(gbase) + (voff)[_i]), (LAS unsigned*)(lds + (bufoff) + ldsw + _i * 8192), 16, 0, 0); } while (0)
; #define PG8_LDA(dst, b, h) do { _Pragma("unroll") for (int m = 0; m < 4; ++m) _Pragma("unroll") for (int k = 0; k < 2; ++k) dst[m][k] = *(const LAS bf16x8*)(lds + PG8_SA(b, h) + aoff + m * 2048 + k * 1024); } while (0)
; #define PG8_LDB(dst, b, h) do { _Pragma("unroll") for (int n = 0; n < 2; ++n) _Pragma("unroll") for (int k = 0; k < 2; ++k) dst[n][k] = *(const LAS bf16x8*)(lds + PG8_SB(b, h) + boff + n * 2048 + k * 1024); } while (0)
; #define PG8_WAIT_V(n) asm volatile("s_waitcnt vmcnt(" #n ")" ::: "memory")
; #define PG8_WAIT_L(n) asm volatile("s_waitcnt lgkmcnt(" #n ")" ::: "memory")
; #define PG8_BAR __builtin_amdgcn_s_barrier()
; template <class Epi, class Sched>
; DI void gemm_phase(LAS unsigned char* lds, const Sched& S, const Epi& E) {
;     ...
;     for (int t = 0; t < nt; t += 2) {
;       const bool last = (t == nt - 2);
;       const char* a1 = cA + (size_t)(t + 1) * kstep;
;       const char* a2 = last ? nA : cA + (size_t)(t + 2) * kstep; const char* b2 = last ? nB : cB + (size_t)(t + 2) * kstep;
;       const char* a3 = a2 + kstep; const char* b3 = b2 + kstep;
;       PG8_LDB(B0, 0, 0); PG8_LDB(B1, 0, 1); PG8_SCHED; PG8_LDA(At, 0, 0); PG8_STAGE(PG8_SA(1, 1), a1 + hstep, voffA);
;       PG8_WAIT_V(8); PG8_WAIT_L(0); PG8_BAR; PG8_MMA(0, 0, At, B0); PG8_MMA(0, 1, At, B1); PG8_BAR; PG8_SCHED;
;       PG8_LDA(At, 0, 1); PG8_STAGE(PG8_SB(0, 0), b2, voffB); PG8_STAGE(PG8_SB(0, 1), b2 + hstep, voffB); PG8_STAGE(PG8_SA(0, 0), a2, voffA);
;       PG8_WAIT_V(8); PG8_WAIT_L(0); PG8_BAR; PG8_MMA(1, 0, At, B0); PG8_MMA(1, 1, At, B1); PG8_BAR; PG8_SCHED;
;       PG8_LDB(B0, 1, 0); PG8_LDB(B1, 1, 1); PG8_SCHED; PG8_LDA(At, 1, 0); PG8_STAGE(PG8_SA(0, 1), a2 + hstep, voffA);
;       PG8_WAIT_V(8); PG8_WAIT_L(0); PG8_BAR; PG8_MMA(0, 0, At, B0); PG8_MMA(0, 1, At, B1); PG8_BAR; PG8_SCHED;
;       PG8_LDA(At, 1, 1); PG8_STAGE(PG8_SB(1, 0), b3, voffB); PG8_STAGE(PG8_SB(1, 1), b3 + hstep, voffB); PG8_STAGE(PG8_SA(1, 0), a3, voffA);
;       PG8_WAIT_V(8); PG8_WAIT_L(0); PG8_BAR; PG8_MMA(1, 0, At, B0); PG8_MMA(1, 1, At, B1); PG8_BAR; PG8_SCHED;
;     }
;     if (wr == 0) PG8_BAR;
	s_setprio 0
	s_add_i32 s26, s63, s12
	v_lshl_add_u64 v[202:203], v[202:203], 0, s[6:7]
	s_mov_b32 m0, s26
	ds_read_b128 v[160:163], v221 offset:49152
	ds_read_b128 v[164:167], v221 offset:50176
	ds_read_b128 v[168:171], v221 offset:51200
	ds_read_b128 v[172:175], v221 offset:52224
	ds_read_b128 v[176:179], v221 offset:53248
	ds_read_b128 v[180:183], v221 offset:54272
	ds_read_b128 v[184:187], v221 offset:55296
	ds_read_b128 v[188:191], v221 offset:56320
	global_load_lds_dwordx4 v[202:203], off
	s_add_i32 m0, s26, 0x2000
	s_add_u32 s22, s22, 0x40080
	v_lshl_add_u64 v[202:203], v[204:205], 0, s[6:7]
	s_addc_u32 s23, s23, 0
	s_add_i32 s26, s64, s12
	global_load_lds_dwordx4 v[202:203], off
	v_lshl_add_u64 v[202:203], s[22:23], 0, v[208:209]
	s_mov_b32 m0, s26
	s_nop 0
	global_load_lds_dwordx4 v[202:203], off
	v_lshl_add_u64 v[202:203], s[22:23], 0, v[196:197]
	s_add_i32 m0, s26, 0x2000
	s_nop 0
	global_load_lds_dwordx4 v[202:203], off
	v_lshl_add_u64 v[202:203], v[206:207], 0, s[6:7]
	s_mov_b32 m0, s57
	s_nop 0
	global_load_lds_dwordx4 v[202:203], off
	v_lshl_add_u64 v[202:203], v[210:211], 0, s[6:7]
	s_mov_b32 m0, s58
	s_nop 0
	global_load_lds_dwordx4 v[202:203], off
	s_waitcnt vmcnt(8) lgkmcnt(0)
	s_setprio 1
	s_barrier
	v_mfma_f32_16x16x32_bf16 v[60:63], v[128:131], v[160:163], v[60:63]
	v_mfma_f32_16x16x32_bf16 v[56:59], v[136:139], v[160:163], v[56:59]
	v_mfma_f32_16x16x32_bf16 v[52:55], v[128:131], v[168:171], v[52:55]
	v_mfma_f32_16x16x32_bf16 v[48:51], v[136:139], v[168:171], v[48:51]
	v_mfma_f32_16x16x32_bf16 v[44:47], v[128:131], v[176:179], v[44:47]
	v_mfma_f32_16x16x32_bf16 v[40:43], v[136:139], v[176:179], v[40:43]
	v_mfma_f32_16x16x32_bf16 v[36:39], v[128:131], v[184:187], v[36:39]
	v_mfma_f32_16x16x32_bf16 v[32:35], v[136:139], v[184:187], v[32:35]
	v_mfma_f32_16x16x32_bf16 v[60:63], v[132:135], v[164:167], v[60:63]
	v_mfma_f32_16x16x32_bf16 v[56:59], v[140:143], v[164:167], v[56:59]
	v_mfma_f32_16x16x32_bf16 v[52:55], v[132:135], v[172:175], v[52:55]
	v_mfma_f32_16x16x32_bf16 v[48:51], v[140:143], v[172:175], v[48:51]
	v_mfma_f32_16x16x32_bf16 v[44:47], v[132:135], v[180:183], v[44:47]
	v_mfma_f32_16x16x32_bf16 v[40:43], v[140:143], v[180:183], v[40:43]
	v_mfma_f32_16x16x32_bf16 v[36:39], v[132:135], v[188:191], v[36:39]
	v_mfma_f32_16x16x32_bf16 v[32:35], v[140:143], v[188:191], v[32:35]
	v_mfma_f32_16x16x32_bf16 v[28:31], v[144:147], v[160:163], v[28:31]
	v_mfma_f32_16x16x32_bf16 v[24:27], v[152:155], v[160:163], v[24:27]
	v_mfma_f32_16x16x32_bf16 v[20:23], v[144:147], v[168:171], v[20:23]
	v_mfma_f32_16x16x32_bf16 v[16:19], v[152:155], v[168:171], v[16:19]
	v_mfma_f32_16x16x32_bf16 v[12:15], v[144:147], v[176:179], v[12:15]
	v_mfma_f32_16x16x32_bf16 v[8:11], v[152:155], v[176:179], v[8:11]
	v_mfma_f32_16x16x32_bf16 v[4:7], v[144:147], v[184:187], v[4:7]
	v_mfma_f32_16x16x32_bf16 v[0:3], v[152:155], v[184:187], v[0:3]
	v_mfma_f32_16x16x32_bf16 v[28:31], v[148:151], v[164:167], v[28:31]
	v_mfma_f32_16x16x32_bf16 v[24:27], v[156:159], v[164:167], v[24:27]
	v_mfma_f32_16x16x32_bf16 v[20:23], v[148:151], v[172:175], v[20:23]
	v_mfma_f32_16x16x32_bf16 v[16:19], v[156:159], v[172:175], v[16:19]
	v_mfma_f32_16x16x32_bf16 v[12:15], v[148:151], v[180:183], v[12:15]
	v_mfma_f32_16x16x32_bf16 v[8:11], v[156:159], v[180:183], v[8:11]
	v_mfma_f32_16x16x32_bf16 v[4:7], v[148:151], v[188:191], v[4:7]
	v_mfma_f32_16x16x32_bf16 v[0:3], v[156:159], v[188:191], v[0:3]
	s_barrier
	s_setprio 0
	s_add_i32 s62, s62, 2
	s_add_u32 s24, s24, 0x100
	s_addc_u32 s25, s25, 0
	s_add_u32 s60, s60, 0x100
	s_addc_u32 s61, s61, 0
	s_cmp_gt_u32 s62, 13
	s_cbranch_scc0 .LBB0_790
	s_and_b64 vcc, exec, s[40:41]
	s_cbranch_vccz .LBB0_793
	s_barrier

; #define PG8_STAGE(bufoff, gbase, voff) do { _Pragma("unroll") for (int _i = 0; _i < 2; ++_i) \
;         __builtin_amdgcn_global_load_lds((const unsigned*)((const char*)(gbase) + (voff)[_i]), (LAS unsigned*)(lds + (bufoff) + ldsw + _i * 8192), 16, 0, 0); } while (0)
; #define PG8_LDA(dst, b, h) do { _Pragma("unroll") for (int m = 0; m < 4; ++m) _Pragma("unroll") for (int k = 0; k < 2; ++k) dst[m][k] = *(const LAS bf16x8*)(lds + PG8_SA(b, h) + aoff + m * 2048 + k * 1024); } while (0)
; #define PG8_LDB(dst, b, h) do { _Pragma("unroll") for (int n = 0; n < 2; ++n) _Pragma("unroll") for (int k = 0; k < 2; ++k) dst[n][k] = *(const LAS bf16x8*)(lds + PG8_SB(b, h) + boff + n * 2048 + k * 1024); } while (0)
; #define PG8_WAIT_V(n) asm volatile("s_waitcnt vmcnt(" #n ")" ::: "memory")
; #define PG8_WAIT_L(n) asm volatile("s_waitcnt lgkmcnt(" #n ")" ::: "memory")
; #define PG8_BAR __builtin_amdgcn_s_barrier()
; #define PG8_SCHED __builtin_amdgcn_sched_barrier(0)
; template <class Epi, class Sched>
; DI void gemm_phase(LAS unsigned char* lds, const Sched& S, const Epi& E) {
;     ...
;     for (int t = 0; t < nt; t += 2) {
;       const bool last = (t == nt - 2);
;       const char* a1 = cA + (size_t)(t + 1) * kstep;
;       const char* a2 = last ? nA : cA + (size_t)(t + 2) * kstep; const char* b2 = last ? nB : cB + (size_t)(t + 2) * kstep;
;       const char* a3 = a2 + kstep; const char* b3 = b2 + kstep;
;       PG8_LDB(B0, 0, 0); PG8_LDB(B1, 0, 1); PG8_SCHED; PG8_LDA(At, 0, 0); PG8_STAGE(PG8_SA(1, 1), a1 + hstep, voffA);
;       PG8_WAIT_V(8); PG8_WAIT_L(0); PG8_BAR; PG8_MMA(0, 0, At, B0); PG8_MMA(0, 1, At, B1); PG8_BAR; PG8_SCHED;
;       PG8_LDA(At, 0, 1); PG8_STAGE(PG8_SB(0, 0), b2, voffB); PG8_STAGE(PG8_SB(0, 1), b2 + hstep, voffB); PG8_STAGE(PG8_SA(0, 0), a2, voffA);
;       PG8_WAIT_V(8); PG8_WAIT_L(0); PG8_BAR; PG8_MMA(1, 0, At, B0); PG8_MMA(1, 1, At, B1); PG8_BAR; PG8_SCHED;
;       PG8_LDB(B0, 1, 0); PG8_LDB(B1, 1, 1); PG8_SCHED; PG8_LDA(At, 1, 0); PG8_STAGE(PG8_SA(0, 1), a2 + hstep, voffA);
;       PG8_WAIT_V(8); PG8_WAIT_L(0); PG8_BAR; PG8_MMA(0, 0, At, B0); PG8_MMA(0, 1, At, B1); PG8_BAR; PG8_SCHED;
;       PG8_LDA(At, 1, 1); PG8_STAGE(PG8_SB(1, 0), b3, voffB); PG8_STAGE(PG8_SB(1, 1), b3 + hstep, voffB); PG8_STAGE(PG8_SA(1, 0), a3, voffA);
;       PG8_WAIT_V(8); PG8_WAIT_L(0); PG8_BAR; PG8_MMA(1, 0, At, B0); PG8_MMA(1, 1, At, B1); PG8_BAR; PG8_SCHED;
;     }
.LBB0_969:
	s_add_u32 s26, s36, 0xfff80080
	s_addc_u32 s27, s37, -1
	s_add_i32 s58, 0, 0x10000
	s_cmp_eq_u32 s57, 28
	s_cselect_b32 s49, s25, s27
	s_cselect_b32 s48, s39, s26
	s_cselect_b32 s27, s41, s56
	s_cselect_b32 s26, s43, s55
	s_add_i32 s60, 0, 0x14000
	v_add_u32_e32 v44, s58, v183
	v_add_u32_e32 v166, s60, v183
	ds_read_b128 v[28:31], v44
	ds_read_b128 v[36:39], v44 offset:1024
	ds_read_b128 v[40:43], v44 offset:2048
	ds_read_b128 v[44:47], v44 offset:3072
	ds_read_b128 v[154:157], v166
	ds_read_b128 v[158:161], v166 offset:1024
	ds_read_b128 v[162:165], v166 offset:2048
	ds_read_b128 v[166:169], v166 offset:3072
	v_lshl_add_u64 v[206:207], s[36:37], 0, v[150:151]
	s_add_i32 m0, s10, 0xc000
	ds_read_b128 v[170:173], v185
	ds_read_b128 v[174:177], v185 offset:1024
	ds_read_b128 v[178:181], v185 offset:2048
	ds_read_b128 v[186:189], v185 offset:3072
	ds_read_b128 v[190:193], v185 offset:4096
	ds_read_b128 v[194:197], v185 offset:5120
	ds_read_b128 v[198:201], v185 offset:6144
	ds_read_b128 v[202:205], v185 offset:7168
	global_load_lds_dwordx4 v[206:207], off
	v_lshl_add_u64 v[206:207], s[36:37], 0, v[152:153]
	s_add_i32 m0, s10, 0xe000
	s_nop 0
	global_load_lds_dwordx4 v[206:207], off
	s_waitcnt vmcnt(8) lgkmcnt(0)
	s_setprio 1
	s_barrier
	v_mfma_f32_16x16x32_bf16 v[140:143], v[28:31], v[170:173], v[140:143]
	v_mfma_f32_16x16x32_bf16 v[136:139], v[40:43], v[170:173], v[136:139]
	v_mfma_f32_16x16x32_bf16 v[124:127], v[28:31], v[178:181], v[124:127]
	v_mfma_f32_16x16x32_bf16 v[120:123], v[40:43], v[178:181], v[120:123]
	v_mfma_f32_16x16x32_bf16 v[108:111], v[28:31], v[190:193], v[108:111]
	v_mfma_f32_16x16x32_bf16 v[104:107], v[40:43], v[190:193], v[104:107]
	v_mfma_f32_16x16x32_bf16 v[92:95], v[28:31], v[198:201], v[92:95]
	v_mfma_f32_16x16x32_bf16 v[88:91], v[40:43], v[198:201], v[88:91]
	v_mfma_f32_16x16x32_bf16 v[140:143], v[36:39], v[174:177], v[140:143]
	v_mfma_f32_16x16x32_bf16 v[136:139], v[44:47], v[174:177], v[136:139]
	v_mfma_f32_16x16x32_bf16 v[124:127], v[36:39], v[186:189], v[124:127]
	v_mfma_f32_16x16x32_bf16 v[120:123], v[44:47], v[186:189], v[120:123]
	v_mfma_f32_16x16x32_bf16 v[108:111], v[36:39], v[194:197], v[108:111]
	v_mfma_f32_16x16x32_bf16 v[104:107], v[44:47], v[194:197], v[104:107]
	v_mfma_f32_16x16x32_bf16 v[92:95], v[36:39], v[202:205], v[92:95]
	v_mfma_f32_16x16x32_bf16 v[88:91], v[44:47], v[202:205], v[88:91]
	v_mfma_f32_16x16x32_bf16 v[132:135], v[154:157], v[170:173], v[132:135]
	v_mfma_f32_16x16x32_bf16 v[128:131], v[162:165], v[170:173], v[128:131]
	v_mfma_f32_16x16x32_bf16 v[116:119], v[154:157], v[178:181], v[116:119]
	v_mfma_f32_16x16x32_bf16 v[112:115], v[162:165], v[178:181], v[112:115]
	v_mfma_f32_16x16x32_bf16 v[100:103], v[154:157], v[190:193], v[100:103]
	v_mfma_f32_16x16x32_bf16 v[96:99], v[162:165], v[190:193], v[96:99]
	v_mfma_f32_16x16x32_bf16 v[84:87], v[154:157], v[198:201], v[84:87]
	v_mfma_f32_16x16x32_bf16 v[80:83], v[162:165], v[198:201], v[80:83]
	v_mfma_f32_16x16x32_bf16 v[132:135], v[158:161], v[174:177], v[132:135]
	v_mfma_f32_16x16x32_bf16 v[128:131], v[166:169], v[174:177], v[128:131]
	v_mfma_f32_16x16x32_bf16 v[116:119], v[158:161], v[186:189], v[116:119]
	v_mfma_f32_16x16x32_bf16 v[112:115], v[166:169], v[186:189], v[112:115]
	v_mfma_f32_16x16x32_bf16 v[100:103], v[158:161], v[194:197], v[100:103]
	v_mfma_f32_16x16x32_bf16 v[96:99], v[166:169], v[194:197], v[96:99]
	v_mfma_f32_16x16x32_bf16 v[84:87], v[158:161], v[202:205], v[84:87]
	v_mfma_f32_16x16x32_bf16 v[80:83], v[166:169], v[202:205], v[80:83]
	s_barrier
	s_setprio 0
	s_add_i32 s58, s58, s9
	v_lshl_add_u64 v[206:207], s[26:27], 0, v[208:209]
	s_mov_b32 m0, s58
	ds_read_b128 v[170:173], v185 offset:16384
	ds_read_b128 v[174:177], v185 offset:17408
	ds_read_b128 v[178:181], v185 offset:18432
	ds_read_b128 v[186:189], v185 offset:19456
	ds_read_b128 v[190:193], v185 offset:20480
	ds_read_b128 v[194:197], v185 offset:21504
	ds_read_b128 v[198:201], v185 offset:22528
	ds_read_b128 v[202:205], v185 offset:23552
	global_load_lds_dwordx4 v[206:207], off
	s_add_i32 m0, s58, 0x2000
	s_add_u32 s58, s26, 0x80000
	v_lshl_add_u64 v[210:211], s[26:27], 0, v[148:149]
	s_addc_u32 s59, s27, 0
	s_add_i32 s60, s60, s9
	global_load_lds_dwordx4 v[210:211], off
	v_lshl_add_u64 v[212:213], s[58:59], 0, v[208:209]
	s_mov_b32 m0, s60
	v_lshl_add_u64 v[214:215], s[48:49], 0, v[146:147]
	global_load_lds_dwordx4 v[212:213], off
	v_lshl_add_u64 v[212:213], s[58:59], 0, v[148:149]
	s_add_i32 m0, s60, 0x2000
	s_nop 0
	global_load_lds_dwordx4 v[212:213], off
	v_lshl_add_u64 v[212:213], s[48:49], 0, v[144:145]
	s_mov_b32 m0, s10
	s_nop 0
	global_load_lds_dwordx4 v[212:213], off
	s_mov_b32 m0, s11
	s_nop 0
	global_load_lds_dwordx4 v[214:215], off
	s_waitcnt vmcnt(8) lgkmcnt(0)
	s_setprio 1
	s_barrier
; #define PG8_STAGE(bufoff, gbase, voff) do { _Pragma("unroll") for (int _i = 0; _i < 2; ++_i) \
;         __builtin_amdgcn_global_load_lds((const unsigned*)((const char*)(gbase) + (voff)[_i]), (LAS unsigned*)(lds + (bufoff) + ldsw + _i * 8192), 16, 0, 0); } while (0)
; #define PG8_LDA(dst, b, h) do { _Pragma("unroll") for (int m = 0; m < 4; ++m) _Pragma("unroll") for (int k = 0; k < 2; ++k) dst[m][k] = *(const LAS bf16x8*)(lds + PG8_SA(b, h) + aoff + m * 2048 + k * 1024); } while (0)
; #define PG8_LDB(dst, b, h) do { _Pragma("unroll") for (int n = 0; n < 2; ++n) _Pragma("unroll") for (int k = 0; k < 2; ++k) dst[n][k] = *(const LAS bf16x8*)(lds + PG8_SB(b, h) + boff + n * 2048 + k * 1024); } while (0)
; #define PG8_WAIT_V(n) asm volatile("s_waitcnt vmcnt(" #n ")" ::: "memory")
; #define PG8_WAIT_L(n) asm volatile("s_waitcnt lgkmcnt(" #n ")" ::: "memory")
; #define PG8_BAR __builtin_amdgcn_s_barrier()
; #define PG8_SCHED __builtin_amdgcn_sched_barrier(0)
; template <class Epi, class Sched>
; DI void gemm_phase(LAS unsigned char* lds, const Sched& S, const Epi& E) {
;     ...
;     for (int t = 0; t < nt; t += 2) {
;       const bool last = (t == nt - 2);
;       const char* a1 = cA + (size_t)(t + 1) * kstep;
;       const char* a2 = last ? nA : cA + (size_t)(t + 2) * kstep; const char* b2 = last ? nB : cB + (size_t)(t + 2) * kstep;
;       const char* a3 = a2 + kstep; const char* b3 = b2 + kstep;
;       PG8_LDB(B0, 0, 0); PG8_LDB(B1, 0, 1); PG8_SCHED; PG8_LDA(At, 0, 0); PG8_STAGE(PG8_SA(1, 1), a1 + hstep, voffA);
;       PG8_WAIT_V(8); PG8_WAIT_L(0); PG8_BAR; PG8_MMA(0, 0, At, B0); PG8_MMA(0, 1, At, B1); PG8_BAR; PG8_SCHED;
;       PG8_LDA(At, 0, 1); PG8_STAGE(PG8_SB(0, 0), b2, voffB); PG8_STAGE(PG8_SB(0, 1), b2 + hstep, voffB); PG8_STAGE(PG8_SA(0, 0), a2, voffA);
;       PG8_WAIT_V(8); PG8_WAIT_L(0); PG8_BAR; PG8_MMA(1, 0, At, B0); PG8_MMA(1, 1, At, B1); PG8_BAR; PG8_SCHED;
;       PG8_LDB(B0, 1, 0); PG8_LDB(B1, 1, 1); PG8_SCHED; PG8_LDA(At, 1, 0); PG8_STAGE(PG8_SA(0, 1), a2 + hstep, voffA);
;       PG8_WAIT_V(8); PG8_WAIT_L(0); PG8_BAR; PG8_MMA(0, 0, At, B0); PG8_MMA(0, 1, At, B1); PG8_BAR; PG8_SCHED;
;       PG8_LDA(At, 1, 1); PG8_STAGE(PG8_SB(1, 0), b3, voffB); PG8_STAGE(PG8_SB(1, 1), b3 + hstep, voffB); PG8_STAGE(PG8_SA(1, 0), a3, voffA);
;       PG8_WAIT_V(8); PG8_WAIT_L(0); PG8_BAR; PG8_MMA(1, 0, At, B0); PG8_MMA(1, 1, At, B1); PG8_BAR; PG8_SCHED;
;     }
	v_mfma_f32_16x16x32_bf16 v[76:79], v[28:31], v[170:173], v[76:79]
	v_mfma_f32_16x16x32_bf16 v[72:75], v[40:43], v[170:173], v[72:75]
	v_mfma_f32_16x16x32_bf16 v[60:63], v[28:31], v[178:181], v[60:63]
	v_mfma_f32_16x16x32_bf16 v[56:59], v[40:43], v[178:181], v[56:59]
	v_mfma_f32_16x16x32_bf16 v[32:35], v[28:31], v[190:193], v[32:35]
	v_mfma_f32_16x16x32_bf16 v[24:27], v[40:43], v[190:193], v[24:27]
	v_mfma_f32_16x16x32_bf16 v[12:15], v[28:31], v[198:201], v[12:15]
	v_mfma_f32_16x16x32_bf16 v[8:11], v[40:43], v[198:201], v[8:11]
	v_mfma_f32_16x16x32_bf16 v[76:79], v[36:39], v[174:177], v[76:79]
	v_mfma_f32_16x16x32_bf16 v[72:75], v[44:47], v[174:177], v[72:75]
	v_mfma_f32_16x16x32_bf16 v[60:63], v[36:39], v[186:189], v[60:63]
	v_mfma_f32_16x16x32_bf16 v[56:59], v[44:47], v[186:189], v[56:59]
	v_mfma_f32_16x16x32_bf16 v[32:35], v[36:39], v[194:197], v[32:35]
	v_mfma_f32_16x16x32_bf16 v[24:27], v[44:47], v[194:197], v[24:27]
	v_mfma_f32_16x16x32_bf16 v[12:15], v[36:39], v[202:205], v[12:15]
	v_mfma_f32_16x16x32_bf16 v[8:11], v[44:47], v[202:205], v[8:11]
	v_mfma_f32_16x16x32_bf16 v[20:23], v[154:157], v[190:193], v[20:23]
	v_mfma_f32_16x16x32_bf16 v[16:19], v[162:165], v[190:193], v[16:19]
	v_mfma_f32_16x16x32_bf16 v[4:7], v[154:157], v[198:201], v[4:7]
	v_mfma_f32_16x16x32_bf16 v[0:3], v[162:165], v[198:201], v[0:3]
	v_mfma_f32_16x16x32_bf16 v[28:31], v[154:157], v[170:173], v[68:71]
	v_mfma_f32_16x16x32_bf16 v[36:39], v[162:165], v[170:173], v[64:67]
	v_mfma_f32_16x16x32_bf16 v[40:43], v[154:157], v[178:181], v[52:55]
	v_mfma_f32_16x16x32_bf16 v[44:47], v[162:165], v[178:181], v[48:51]
	v_mfma_f32_16x16x32_bf16 v[20:23], v[158:161], v[194:197], v[20:23]
	v_mfma_f32_16x16x32_bf16 v[16:19], v[166:169], v[194:197], v[16:19]
	v_mfma_f32_16x16x32_bf16 v[4:7], v[158:161], v[202:205], v[4:7]
	v_mfma_f32_16x16x32_bf16 v[0:3], v[166:169], v[202:205], v[0:3]
	v_mfma_f32_16x16x32_bf16 v[28:31], v[158:161], v[174:177], v[28:31]
	v_mfma_f32_16x16x32_bf16 v[36:39], v[166:169], v[174:177], v[36:39]
	v_mfma_f32_16x16x32_bf16 v[40:43], v[158:161], v[186:189], v[40:43]
	v_mfma_f32_16x16x32_bf16 v[44:47], v[166:169], v[186:189], v[44:47]
	s_barrier
	s_setprio 0
	s_add_i32 s58, 0, 0x18000
	s_add_i32 s59, 0, 0x1c000
	v_add_u32_e32 v68, s58, v183
	v_add_u32_e32 v166, s59, v183
	ds_read_b128 v[48:51], v68
	ds_read_b128 v[52:55], v68 offset:1024
	ds_read_b128 v[64:67], v68 offset:2048
	ds_read_b128 v[68:71], v68 offset:3072
	ds_read_b128 v[154:157], v166
	ds_read_b128 v[158:161], v166 offset:1024
	ds_read_b128 v[162:165], v166 offset:2048
	ds_read_b128 v[166:169], v166 offset:3072
	s_add_u32 s48, s48, 0x80000
	s_addc_u32 s49, s49, 0
	s_mov_b32 m0, s12
	v_lshl_add_u64 v[216:217], s[48:49], 0, v[144:145]
	ds_read_b128 v[170:173], v185 offset:32768
	ds_read_b128 v[174:177], v185 offset:33792
	ds_read_b128 v[178:181], v185 offset:34816
	ds_read_b128 v[186:189], v185 offset:35840
	ds_read_b128 v[190:193], v185 offset:36864
	ds_read_b128 v[194:197], v185 offset:37888
	ds_read_b128 v[198:201], v185 offset:38912
	ds_read_b128 v[202:205], v185 offset:39936
	global_load_lds_dwordx4 v[216:217], off
	v_lshl_add_u64 v[216:217], s[48:49], 0, v[146:147]
	s_mov_b32 m0, s18
	s_nop 0
	global_load_lds_dwordx4 v[216:217], off
	s_waitcnt vmcnt(8) lgkmcnt(0)
	s_setprio 1
	s_barrier
	v_mfma_f32_16x16x32_bf16 v[140:143], v[48:51], v[170:173], v[140:143]
	v_mfma_f32_16x16x32_bf16 v[136:139], v[64:67], v[170:173], v[136:139]
	v_mfma_f32_16x16x32_bf16 v[124:127], v[48:51], v[178:181], v[124:127]
	v_mfma_f32_16x16x32_bf16 v[120:123], v[64:67], v[178:181], v[120:123]
	v_mfma_f32_16x16x32_bf16 v[108:111], v[48:51], v[190:193], v[108:111]
	v_mfma_f32_16x16x32_bf16 v[104:107], v[64:67], v[190:193], v[104:107]
	v_mfma_f32_16x16x32_bf16 v[92:95], v[48:51], v[198:201], v[92:95]
	v_mfma_f32_16x16x32_bf16 v[88:91], v[64:67], v[198:201], v[88:91]
	v_mfma_f32_16x16x32_bf16 v[140:143], v[52:55], v[174:177], v[140:143]
	v_mfma_f32_16x16x32_bf16 v[136:139], v[68:71], v[174:177], v[136:139]
	v_mfma_f32_16x16x32_bf16 v[124:127], v[52:55], v[186:189], v[124:127]
	v_mfma_f32_16x16x32_bf16 v[120:123], v[68:71], v[186:189], v[120:123]
	v_mfma_f32_16x16x32_bf16 v[108:111], v[52:55], v[194:197], v[108:111]
	v_mfma_f32_16x16x32_bf16 v[104:107], v[68:71], v[194:197], v[104:107]
	v_mfma_f32_16x16x32_bf16 v[92:95], v[52:55], v[202:205], v[92:95]
	v_mfma_f32_16x16x32_bf16 v[88:91], v[68:71], v[202:205], v[88:91]
	v_mfma_f32_16x16x32_bf16 v[132:135], v[154:157], v[170:173], v[132:135]
	v_mfma_f32_16x16x32_bf16 v[128:131], v[162:165], v[170:173], v[128:131]
	v_mfma_f32_16x16x32_bf16 v[116:119], v[154:157], v[178:181], v[116:119]
	v_mfma_f32_16x16x32_bf16 v[112:115], v[162:165], v[178:181], v[112:115]
	v_mfma_f32_16x16x32_bf16 v[100:103], v[154:157], v[190:193], v[100:103]
	v_mfma_f32_16x16x32_bf16 v[96:99], v[162:165], v[190:193], v[96:99]
	v_mfma_f32_16x16x32_bf16 v[84:87], v[154:157], v[198:201], v[84:87]
	v_mfma_f32_16x16x32_bf16 v[80:83], v[162:165], v[198:201], v[80:83]
	v_mfma_f32_16x16x32_bf16 v[132:135], v[158:161], v[174:177], v[132:135]
	v_mfma_f32_16x16x32_bf16 v[128:131], v[166:169], v[174:177], v[128:131]
	v_mfma_f32_16x16x32_bf16 v[116:119], v[158:161], v[186:189], v[116:119]
	v_mfma_f32_16x16x32_bf16 v[112:115], v[166:169], v[186:189], v[112:115]
	v_mfma_f32_16x16x32_bf16 v[100:103], v[158:161], v[194:197], v[100:103]
	v_mfma_f32_16x16x32_bf16 v[96:99], v[166:169], v[194:197], v[96:99]
	v_mfma_f32_16x16x32_bf16 v[84:87], v[158:161], v[202:205], v[84:87]
	v_mfma_f32_16x16x32_bf16 v[80:83], v[166:169], v[202:205], v[80:83]
	s_barrier
; #define PG8_STAGE(bufoff, gbase, voff) do { _Pragma("unroll") for (int _i = 0; _i < 2; ++_i) \
;         __builtin_amdgcn_global_load_lds((const unsigned*)((const char*)(gbase) + (voff)[_i]), (LAS unsigned*)(lds + (bufoff) + ldsw + _i * 8192), 16, 0, 0); } while (0)
; #define PG8_LDA(dst, b, h) do { _Pragma("unroll") for (int m = 0; m < 4; ++m) _Pragma("unroll") for (int k = 0; k < 2; ++k) dst[m][k] = *(const LAS bf16x8*)(lds + PG8_SA(b, h) + aoff + m * 2048 + k * 1024); } while (0)
; #define PG8_LDB(dst, b, h) do { _Pragma("unroll") for (int n = 0; n < 2; ++n) _Pragma("unroll") for (int k = 0; k < 2; ++k) dst[n][k] = *(const LAS bf16x8*)(lds + PG8_SB(b, h) + boff + n * 2048 + k * 1024); } while (0)
; #define PG8_WAIT_V(n) asm volatile("s_waitcnt vmcnt(" #n ")" ::: "memory")
; #define PG8_WAIT_L(n) asm volatile("s_waitcnt lgkmcnt(" #n ")" ::: "memory")
; #define PG8_BAR __builtin_amdgcn_s_barrier()
; template <class Epi, class Sched>
; DI void gemm_phase(LAS unsigned char* lds, const Sched& S, const Epi& E) {
;     ...
;     for (int t = 0; t < nt; t += 2) {
;       const bool last = (t == nt - 2);
;       const char* a1 = cA + (size_t)(t + 1) * kstep;
;       const char* a2 = last ? nA : cA + (size_t)(t + 2) * kstep; const char* b2 = last ? nB : cB + (size_t)(t + 2) * kstep;
;       const char* a3 = a2 + kstep; const char* b3 = b2 + kstep;
;       PG8_LDB(B0, 0, 0); PG8_LDB(B1, 0, 1); PG8_SCHED; PG8_LDA(At, 0, 0); PG8_STAGE(PG8_SA(1, 1), a1 + hstep, voffA);
;       PG8_WAIT_V(8); PG8_WAIT_L(0); PG8_BAR; PG8_MMA(0, 0, At, B0); PG8_MMA(0, 1, At, B1); PG8_BAR; PG8_SCHED;
;       PG8_LDA(At, 0, 1); PG8_STAGE(PG8_SB(0, 0), b2, voffB); PG8_STAGE(PG8_SB(0, 1), b2 + hstep, voffB); PG8_STAGE(PG8_SA(0, 0), a2, voffA);
;       PG8_WAIT_V(8); PG8_WAIT_L(0); PG8_BAR; PG8_MMA(1, 0, At, B0); PG8_MMA(1, 1, At, B1); PG8_BAR; PG8_SCHED;
;       PG8_LDB(B0, 1, 0); PG8_LDB(B1, 1, 1); PG8_SCHED; PG8_LDA(At, 1, 0); PG8_STAGE(PG8_SA(0, 1), a2 + hstep, voffA);
;       PG8_WAIT_V(8); PG8_WAIT_L(0); PG8_BAR; PG8_MMA(0, 0, At, B0); PG8_MMA(0, 1, At, B1); PG8_BAR; PG8_SCHED;
;       PG8_LDA(At, 1, 1); PG8_STAGE(PG8_SB(1, 0), b3, voffB); PG8_STAGE(PG8_SB(1, 1), b3 + hstep, voffB); PG8_STAGE(PG8_SA(1, 0), a3, voffA);
;       PG8_WAIT_V(8); PG8_WAIT_L(0); PG8_BAR; PG8_MMA(1, 0, At, B0); PG8_MMA(1, 1, At, B1); PG8_BAR; PG8_SCHED;
;     }
;     if (wr == 0) PG8_BAR;
	s_setprio 0
	s_add_i32 s48, s58, s9
	v_lshl_add_u64 v[206:207], v[206:207], 0, s[6:7]
	s_mov_b32 m0, s48
	ds_read_b128 v[170:173], v185 offset:49152
	ds_read_b128 v[174:177], v185 offset:50176
	ds_read_b128 v[178:181], v185 offset:51200
	ds_read_b128 v[186:189], v185 offset:52224
	ds_read_b128 v[190:193], v185 offset:53248
	ds_read_b128 v[194:197], v185 offset:54272
	ds_read_b128 v[198:201], v185 offset:55296
	ds_read_b128 v[202:205], v185 offset:56320
	global_load_lds_dwordx4 v[206:207], off
	s_add_i32 m0, s48, 0x2000
	s_add_u32 s26, s26, 0x80080
	v_lshl_add_u64 v[206:207], v[210:211], 0, s[6:7]
	s_addc_u32 s27, s27, 0
	s_add_i32 s48, s59, s9
	global_load_lds_dwordx4 v[206:207], off
	v_lshl_add_u64 v[206:207], s[26:27], 0, v[208:209]
	s_mov_b32 m0, s48
	s_nop 0
	global_load_lds_dwordx4 v[206:207], off
	v_lshl_add_u64 v[206:207], s[26:27], 0, v[148:149]
	s_add_i32 m0, s48, 0x2000
	s_nop 0
	global_load_lds_dwordx4 v[206:207], off
	v_lshl_add_u64 v[206:207], v[212:213], 0, s[6:7]
	s_mov_b32 m0, s51
	s_nop 0
	global_load_lds_dwordx4 v[206:207], off
	v_lshl_add_u64 v[206:207], v[214:215], 0, s[6:7]
	s_mov_b32 m0, s52
	s_nop 0
	global_load_lds_dwordx4 v[206:207], off
	s_waitcnt vmcnt(8) lgkmcnt(0)
	s_setprio 1
	s_barrier
	v_mfma_f32_16x16x32_bf16 v[76:79], v[48:51], v[170:173], v[76:79]
	v_mfma_f32_16x16x32_bf16 v[72:75], v[64:67], v[170:173], v[72:75]
	v_mfma_f32_16x16x32_bf16 v[60:63], v[48:51], v[178:181], v[60:63]
	v_mfma_f32_16x16x32_bf16 v[56:59], v[64:67], v[178:181], v[56:59]
	v_mfma_f32_16x16x32_bf16 v[32:35], v[48:51], v[190:193], v[32:35]
	v_mfma_f32_16x16x32_bf16 v[24:27], v[64:67], v[190:193], v[24:27]
	v_mfma_f32_16x16x32_bf16 v[12:15], v[48:51], v[198:201], v[12:15]
	v_mfma_f32_16x16x32_bf16 v[8:11], v[64:67], v[198:201], v[8:11]
	v_mfma_f32_16x16x32_bf16 v[76:79], v[52:55], v[174:177], v[76:79]
	v_mfma_f32_16x16x32_bf16 v[72:75], v[68:71], v[174:177], v[72:75]
	v_mfma_f32_16x16x32_bf16 v[60:63], v[52:55], v[186:189], v[60:63]
	v_mfma_f32_16x16x32_bf16 v[56:59], v[68:71], v[186:189], v[56:59]
	v_mfma_f32_16x16x32_bf16 v[32:35], v[52:55], v[194:197], v[32:35]
	v_mfma_f32_16x16x32_bf16 v[24:27], v[68:71], v[194:197], v[24:27]
	v_mfma_f32_16x16x32_bf16 v[12:15], v[52:55], v[202:205], v[12:15]
	v_mfma_f32_16x16x32_bf16 v[8:11], v[68:71], v[202:205], v[8:11]
	v_mfma_f32_16x16x32_bf16 v[28:31], v[154:157], v[170:173], v[28:31]
	v_mfma_f32_16x16x32_bf16 v[68:71], v[158:161], v[174:177], v[28:31]
	v_mfma_f32_16x16x32_bf16 v[28:31], v[162:165], v[170:173], v[36:39]
	v_mfma_f32_16x16x32_bf16 v[64:67], v[166:169], v[174:177], v[28:31]
	v_mfma_f32_16x16x32_bf16 v[28:31], v[154:157], v[178:181], v[40:43]
	v_mfma_f32_16x16x32_bf16 v[52:55], v[158:161], v[186:189], v[28:31]
	v_mfma_f32_16x16x32_bf16 v[28:31], v[162:165], v[178:181], v[44:47]
	v_mfma_f32_16x16x32_bf16 v[20:23], v[154:157], v[190:193], v[20:23]
	v_mfma_f32_16x16x32_bf16 v[16:19], v[162:165], v[190:193], v[16:19]
	v_mfma_f32_16x16x32_bf16 v[4:7], v[154:157], v[198:201], v[4:7]
	v_mfma_f32_16x16x32_bf16 v[0:3], v[162:165], v[198:201], v[0:3]
	v_mfma_f32_16x16x32_bf16 v[48:51], v[166:169], v[186:189], v[28:31]
	v_mfma_f32_16x16x32_bf16 v[20:23], v[158:161], v[194:197], v[20:23]
	v_mfma_f32_16x16x32_bf16 v[16:19], v[166:169], v[194:197], v[16:19]
	v_mfma_f32_16x16x32_bf16 v[4:7], v[158:161], v[202:205], v[4:7]
	v_mfma_f32_16x16x32_bf16 v[0:3], v[166:169], v[202:205], v[0:3]
	s_barrier
	s_setprio 0
	s_add_i32 s57, s57, 2
	s_add_u32 s36, s36, 0x100
	s_addc_u32 s37, s37, 0
	s_add_u32 s55, s55, 0x100
	s_addc_u32 s56, s56, 0
	s_cmp_gt_u32 s57, 29
	s_cbranch_scc0 .LBB0_969
	s_and_b64 vcc, exec, s[30:31]
	s_cbranch_vccz .LBB0_972
	s_barrier
